# v26 with the closing barrier taken 4 MFMAs early (was 2)
# speedup vs baseline: 1.0102x; 1.0001x over previous
.LBB0_291:
	s_ashr_i32 s5, s4, 31
	s_lshl_b64 s[28:29], s[4:5], 20
	s_add_u32 s28, s14, s28
	s_addc_u32 s29, s15, s29
	s_and_b64 s[34:35], s[22:23], exec
	s_cselect_b32 s5, s29, s37
	s_cselect_b32 s8, s28, s36
	s_ashr_i32 s19, s18, 31
	s_lshl_b64 s[34:35], s[18:19], 20
	v_readlane_b32 s19, v245, 38
	s_add_u32 s34, s19, s34
	v_readlane_b32 s19, v245, 39
	s_addc_u32 s35, s19, s35
	s_and_b64 s[44:45], s[22:23], exec
	s_cselect_b32 s19, s35, s43
	s_cselect_b32 s21, s34, s42
	s_add_u32 s36, s36, 0x80080
	s_addc_u32 s37, s37, 0
	s_add_u32 s41, s42, 0x100
	s_addc_u32 s46, s43, 0
	s_mov_b32 s47, -2
	s_waitcnt vmcnt(0) lgkmcnt(0)
	s_add_u32 s42, s36, 0xfff80080
	s_addc_u32 s43, s37, -1
	s_add_i32 s48, 0, 0x10000
	s_cmp_eq_u32 s47, 28
	s_cselect_b32 s45, s5, s43
	s_cselect_b32 s44, s8, s42
	s_cselect_b32 s43, s19, s46
	s_cselect_b32 s42, s21, s41
	s_add_i32 s50, 0, 0x14000
	v_add_u32_e32 v158, s48, v147
	v_add_u32_e32 v162, s50, v147
	ds_read_b128 v[130:133], v158
	ds_read_b128 v[134:137], v158 offset:1024
	ds_read_b128 v[152:155], v158 offset:2048
	ds_read_b128 v[158:161], v158 offset:3072
	ds_read_b128 v[164:167], v162
	ds_read_b128 v[180:183], v162 offset:1024
	ds_read_b128 v[184:187], v162 offset:2048
	ds_read_b128 v[188:191], v162 offset:3072
	v_lshl_add_u64 v[168:169], s[36:37], 0, v[148:149]
	s_add_i32 m0, s11, 0xc000
	ds_read_b128 v[192:195], v157
	ds_read_b128 v[196:199], v157 offset:1024
	ds_read_b128 v[200:203], v157 offset:2048
	ds_read_b128 v[204:207], v157 offset:3072
	ds_read_b128 v[208:211], v157 offset:4096
	ds_read_b128 v[212:215], v157 offset:5120
	ds_read_b128 v[216:219], v157 offset:6144
	ds_read_b128 v[220:223], v157 offset:7168
	global_load_lds_dwordx4 v[168:169], off
	v_lshl_add_u64 v[168:169], s[36:37], 0, v[150:151]
	s_add_i32 m0, s11, 0xe000
	s_nop 0
	global_load_lds_dwordx4 v[168:169], off
	s_waitcnt vmcnt(8)
	s_waitcnt lgkmcnt(0)
	s_barrier
	s_setprio 1
	s_waitcnt lgkmcnt(0)
	v_mfma_f32_16x16x32_bf16 v[126:129], v[130:133], v[192:195], 0
	v_mfma_f32_16x16x32_bf16 v[122:125], v[152:155], v[192:195], 0
	v_mfma_f32_16x16x32_bf16 v[110:113], v[130:133], v[200:203], 0
	v_mfma_f32_16x16x32_bf16 v[106:109], v[152:155], v[200:203], 0
	v_mfma_f32_16x16x32_bf16 v[94:97], v[130:133], v[208:211], 0
	v_mfma_f32_16x16x32_bf16 v[90:93], v[152:155], v[208:211], 0
	v_mfma_f32_16x16x32_bf16 v[78:81], v[130:133], v[216:219], 0
	v_mfma_f32_16x16x32_bf16 v[74:77], v[152:155], v[216:219], 0
	v_mfma_f32_16x16x32_bf16 v[126:129], v[134:137], v[196:199], v[126:129]
	v_mfma_f32_16x16x32_bf16 v[122:125], v[158:161], v[196:199], v[122:125]
	v_mfma_f32_16x16x32_bf16 v[110:113], v[134:137], v[204:207], v[110:113]
	v_mfma_f32_16x16x32_bf16 v[106:109], v[158:161], v[204:207], v[106:109]
	v_mfma_f32_16x16x32_bf16 v[94:97], v[134:137], v[212:215], v[94:97]
	v_mfma_f32_16x16x32_bf16 v[90:93], v[158:161], v[212:215], v[90:93]
	v_mfma_f32_16x16x32_bf16 v[78:81], v[134:137], v[220:223], v[78:81]
	v_mfma_f32_16x16x32_bf16 v[74:77], v[158:161], v[220:223], v[74:77]
	s_setprio 0
	s_setprio 1
	v_mfma_f32_16x16x32_bf16 v[118:121], v[164:167], v[192:195], 0
	v_mfma_f32_16x16x32_bf16 v[114:117], v[184:187], v[192:195], 0
	v_mfma_f32_16x16x32_bf16 v[102:105], v[164:167], v[200:203], 0
	v_mfma_f32_16x16x32_bf16 v[98:101], v[184:187], v[200:203], 0
	v_mfma_f32_16x16x32_bf16 v[86:89], v[164:167], v[208:211], 0
	v_mfma_f32_16x16x32_bf16 v[82:85], v[184:187], v[208:211], 0
	v_mfma_f32_16x16x32_bf16 v[70:73], v[164:167], v[216:219], 0
	v_mfma_f32_16x16x32_bf16 v[66:69], v[184:187], v[216:219], 0
	v_mfma_f32_16x16x32_bf16 v[118:121], v[180:183], v[196:199], v[118:121]
	v_mfma_f32_16x16x32_bf16 v[114:117], v[188:191], v[196:199], v[114:117]
	v_mfma_f32_16x16x32_bf16 v[102:105], v[180:183], v[204:207], v[102:105]
	v_mfma_f32_16x16x32_bf16 v[98:101], v[188:191], v[204:207], v[98:101]
	s_setprio 2
	s_barrier
	v_mfma_f32_16x16x32_bf16 v[86:89], v[180:183], v[212:215], v[86:89]
	v_mfma_f32_16x16x32_bf16 v[82:85], v[188:191], v[212:215], v[82:85]
	v_mfma_f32_16x16x32_bf16 v[70:73], v[180:183], v[220:223], v[70:73]
	v_mfma_f32_16x16x32_bf16 v[66:69], v[188:191], v[220:223], v[66:69]
	s_setprio 0
	s_add_i32 s48, s48, s9
	v_lshl_add_u64 v[168:169], s[42:43], 0, v[140:141]
	s_mov_b32 m0, s48
	ds_read_b128 v[192:195], v157 offset:16384
	ds_read_b128 v[196:199], v157 offset:17408
	ds_read_b128 v[200:203], v157 offset:18432
	ds_read_b128 v[204:207], v157 offset:19456
	ds_read_b128 v[208:211], v157 offset:20480
	ds_read_b128 v[212:215], v157 offset:21504
	ds_read_b128 v[216:219], v157 offset:22528
	ds_read_b128 v[220:223], v157 offset:23552
	global_load_lds_dwordx4 v[168:169], off
	s_add_i32 m0, s48, 0x2000
	s_add_u32 s48, s42, 0x80000
	v_lshl_add_u64 v[224:225], s[42:43], 0, v[144:145]
	s_addc_u32 s49, s43, 0
	s_add_i32 s50, s50, s9
	global_load_lds_dwordx4 v[224:225], off
	v_lshl_add_u64 v[226:227], s[48:49], 0, v[140:141]
	s_mov_b32 m0, s50
	v_lshl_add_u64 v[228:229], s[44:45], 0, v[142:143]
	global_load_lds_dwordx4 v[226:227], off
	v_lshl_add_u64 v[226:227], s[48:49], 0, v[144:145]
	s_add_i32 m0, s50, 0x2000
	s_nop 0
	global_load_lds_dwordx4 v[226:227], off
	v_lshl_add_u64 v[226:227], s[44:45], 0, v[138:139]
	s_mov_b32 m0, s11
	s_nop 0
	global_load_lds_dwordx4 v[226:227], off
	s_mov_b32 m0, s13
	s_nop 0
	global_load_lds_dwordx4 v[228:229], off
	s_waitcnt vmcnt(8)
	s_waitcnt lgkmcnt(0)
	s_barrier
	s_setprio 1
	s_waitcnt lgkmcnt(0)
	v_mfma_f32_16x16x32_bf16 v[62:65], v[130:133], v[192:195], 0
	v_mfma_f32_16x16x32_bf16 v[58:61], v[152:155], v[192:195], 0
	v_mfma_f32_16x16x32_bf16 v[46:49], v[130:133], v[200:203], 0
	v_mfma_f32_16x16x32_bf16 v[42:45], v[152:155], v[200:203], 0
	v_mfma_f32_16x16x32_bf16 v[30:33], v[130:133], v[208:211], 0
	v_mfma_f32_16x16x32_bf16 v[26:29], v[152:155], v[208:211], 0
	v_mfma_f32_16x16x32_bf16 v[14:17], v[130:133], v[216:219], 0
	v_mfma_f32_16x16x32_bf16 v[10:13], v[152:155], v[216:219], 0
	v_mfma_f32_16x16x32_bf16 v[62:65], v[134:137], v[196:199], v[62:65]
	v_mfma_f32_16x16x32_bf16 v[58:61], v[158:161], v[196:199], v[58:61]
	v_mfma_f32_16x16x32_bf16 v[46:49], v[134:137], v[204:207], v[46:49]
	v_mfma_f32_16x16x32_bf16 v[42:45], v[158:161], v[204:207], v[42:45]
	v_mfma_f32_16x16x32_bf16 v[30:33], v[134:137], v[212:215], v[30:33]
	v_mfma_f32_16x16x32_bf16 v[26:29], v[158:161], v[212:215], v[26:29]
	v_mfma_f32_16x16x32_bf16 v[14:17], v[134:137], v[220:223], v[14:17]
	v_mfma_f32_16x16x32_bf16 v[10:13], v[158:161], v[220:223], v[10:13]
	s_setprio 0
	s_setprio 1
	v_mfma_f32_16x16x32_bf16 v[54:57], v[164:167], v[192:195], 0
	v_mfma_f32_16x16x32_bf16 v[50:53], v[184:187], v[192:195], 0
	v_mfma_f32_16x16x32_bf16 v[38:41], v[164:167], v[200:203], 0
	v_mfma_f32_16x16x32_bf16 v[34:37], v[184:187], v[200:203], 0
	v_mfma_f32_16x16x32_bf16 v[22:25], v[164:167], v[208:211], 0
	v_mfma_f32_16x16x32_bf16 v[18:21], v[184:187], v[208:211], 0
	v_mfma_f32_16x16x32_bf16 v[6:9], v[164:167], v[216:219], 0
	v_mfma_f32_16x16x32_bf16 v[2:5], v[184:187], v[216:219], 0
	v_mfma_f32_16x16x32_bf16 v[54:57], v[180:183], v[196:199], v[54:57]
	v_mfma_f32_16x16x32_bf16 v[50:53], v[188:191], v[196:199], v[50:53]
	v_mfma_f32_16x16x32_bf16 v[38:41], v[180:183], v[204:207], v[38:41]
	v_mfma_f32_16x16x32_bf16 v[34:37], v[188:191], v[204:207], v[34:37]
	s_setprio 2
	s_barrier
	v_mfma_f32_16x16x32_bf16 v[22:25], v[180:183], v[212:215], v[22:25]
	v_mfma_f32_16x16x32_bf16 v[18:21], v[188:191], v[212:215], v[18:21]
	v_mfma_f32_16x16x32_bf16 v[6:9], v[180:183], v[220:223], v[6:9]
	v_mfma_f32_16x16x32_bf16 v[2:5], v[188:191], v[220:223], v[2:5]
	s_setprio 0
	s_add_i32 s48, 0, 0x18000
	s_add_i32 s49, 0, 0x1c000
	v_add_u32_e32 v158, s48, v147
	v_add_u32_e32 v162, s49, v147
	ds_read_b128 v[130:133], v158
	ds_read_b128 v[134:137], v158 offset:1024
	ds_read_b128 v[152:155], v158 offset:2048
	ds_read_b128 v[158:161], v158 offset:3072
	ds_read_b128 v[164:167], v162
	ds_read_b128 v[180:183], v162 offset:1024
	ds_read_b128 v[184:187], v162 offset:2048
	ds_read_b128 v[188:191], v162 offset:3072
	s_add_u32 s44, s44, 0x80000
	s_addc_u32 s45, s45, 0
	s_mov_b32 m0, s20
	v_lshl_add_u64 v[230:231], s[44:45], 0, v[138:139]
	ds_read_b128 v[192:195], v157 offset:32768
	ds_read_b128 v[196:199], v157 offset:33792
	ds_read_b128 v[200:203], v157 offset:34816
	ds_read_b128 v[204:207], v157 offset:35840
	ds_read_b128 v[208:211], v157 offset:36864
	ds_read_b128 v[212:215], v157 offset:37888
	ds_read_b128 v[216:219], v157 offset:38912
	ds_read_b128 v[220:223], v157 offset:39936
	global_load_lds_dwordx4 v[230:231], off
	v_lshl_add_u64 v[230:231], s[44:45], 0, v[142:143]
	s_mov_b32 m0, s25
	s_nop 0
	global_load_lds_dwordx4 v[230:231], off
	s_waitcnt vmcnt(8)
	s_waitcnt lgkmcnt(0)
	s_barrier
	s_setprio 1
	s_waitcnt lgkmcnt(0)
	v_mfma_f32_16x16x32_bf16 v[126:129], v[130:133], v[192:195], v[126:129]
	v_mfma_f32_16x16x32_bf16 v[122:125], v[152:155], v[192:195], v[122:125]
	v_mfma_f32_16x16x32_bf16 v[110:113], v[130:133], v[200:203], v[110:113]
	v_mfma_f32_16x16x32_bf16 v[106:109], v[152:155], v[200:203], v[106:109]
	v_mfma_f32_16x16x32_bf16 v[94:97], v[130:133], v[208:211], v[94:97]
	v_mfma_f32_16x16x32_bf16 v[90:93], v[152:155], v[208:211], v[90:93]
	v_mfma_f32_16x16x32_bf16 v[78:81], v[130:133], v[216:219], v[78:81]
	v_mfma_f32_16x16x32_bf16 v[74:77], v[152:155], v[216:219], v[74:77]
	v_mfma_f32_16x16x32_bf16 v[126:129], v[134:137], v[196:199], v[126:129]
	v_mfma_f32_16x16x32_bf16 v[122:125], v[158:161], v[196:199], v[122:125]
	v_mfma_f32_16x16x32_bf16 v[110:113], v[134:137], v[204:207], v[110:113]
	v_mfma_f32_16x16x32_bf16 v[106:109], v[158:161], v[204:207], v[106:109]
	v_mfma_f32_16x16x32_bf16 v[94:97], v[134:137], v[212:215], v[94:97]
	v_mfma_f32_16x16x32_bf16 v[90:93], v[158:161], v[212:215], v[90:93]
	v_mfma_f32_16x16x32_bf16 v[78:81], v[134:137], v[220:223], v[78:81]
	v_mfma_f32_16x16x32_bf16 v[74:77], v[158:161], v[220:223], v[74:77]
	s_setprio 0
	s_setprio 1
	v_mfma_f32_16x16x32_bf16 v[118:121], v[164:167], v[192:195], v[118:121]
	v_mfma_f32_16x16x32_bf16 v[114:117], v[184:187], v[192:195], v[114:117]
	v_mfma_f32_16x16x32_bf16 v[102:105], v[164:167], v[200:203], v[102:105]
	v_mfma_f32_16x16x32_bf16 v[98:101], v[184:187], v[200:203], v[98:101]
	v_mfma_f32_16x16x32_bf16 v[86:89], v[164:167], v[208:211], v[86:89]
	v_mfma_f32_16x16x32_bf16 v[82:85], v[184:187], v[208:211], v[82:85]
	v_mfma_f32_16x16x32_bf16 v[70:73], v[164:167], v[216:219], v[70:73]
	v_mfma_f32_16x16x32_bf16 v[66:69], v[184:187], v[216:219], v[66:69]
	v_mfma_f32_16x16x32_bf16 v[118:121], v[180:183], v[196:199], v[118:121]
	v_mfma_f32_16x16x32_bf16 v[114:117], v[188:191], v[196:199], v[114:117]
	v_mfma_f32_16x16x32_bf16 v[102:105], v[180:183], v[204:207], v[102:105]
	v_mfma_f32_16x16x32_bf16 v[98:101], v[188:191], v[204:207], v[98:101]
	s_setprio 2
	s_barrier
	v_mfma_f32_16x16x32_bf16 v[86:89], v[180:183], v[212:215], v[86:89]
	v_mfma_f32_16x16x32_bf16 v[82:85], v[188:191], v[212:215], v[82:85]
	v_mfma_f32_16x16x32_bf16 v[70:73], v[180:183], v[220:223], v[70:73]
	v_mfma_f32_16x16x32_bf16 v[66:69], v[188:191], v[220:223], v[66:69]
	s_setprio 0
	s_add_i32 s44, s48, s9
	v_lshl_add_u64 v[168:169], v[168:169], 0, s[6:7]
	s_mov_b32 m0, s44
	ds_read_b128 v[192:195], v157 offset:49152
	ds_read_b128 v[196:199], v157 offset:50176
	ds_read_b128 v[200:203], v157 offset:51200
	ds_read_b128 v[204:207], v157 offset:52224
	ds_read_b128 v[208:211], v157 offset:53248
	ds_read_b128 v[212:215], v157 offset:54272
	ds_read_b128 v[216:219], v157 offset:55296
	ds_read_b128 v[220:223], v157 offset:56320
	global_load_lds_dwordx4 v[168:169], off
	s_add_i32 m0, s44, 0x2000
	s_add_u32 s42, s42, 0x80080
	v_lshl_add_u64 v[168:169], v[224:225], 0, s[6:7]
	s_addc_u32 s43, s43, 0
	s_add_i32 s44, s49, s9
	global_load_lds_dwordx4 v[168:169], off
	v_lshl_add_u64 v[168:169], s[42:43], 0, v[140:141]
	s_mov_b32 m0, s44
	s_nop 0
	global_load_lds_dwordx4 v[168:169], off
	v_lshl_add_u64 v[168:169], s[42:43], 0, v[144:145]
	s_add_i32 m0, s44, 0x2000
	s_nop 0
	global_load_lds_dwordx4 v[168:169], off
	v_lshl_add_u64 v[168:169], v[226:227], 0, s[6:7]
	s_mov_b32 m0, s26
	s_nop 0
	global_load_lds_dwordx4 v[168:169], off
	v_lshl_add_u64 v[168:169], v[228:229], 0, s[6:7]
	s_mov_b32 m0, s27
	s_nop 0
	global_load_lds_dwordx4 v[168:169], off
	s_waitcnt vmcnt(8)
	s_waitcnt lgkmcnt(0)
	s_barrier
	s_setprio 1
	s_waitcnt lgkmcnt(0)
	v_mfma_f32_16x16x32_bf16 v[62:65], v[130:133], v[192:195], v[62:65]
	v_mfma_f32_16x16x32_bf16 v[58:61], v[152:155], v[192:195], v[58:61]
	v_mfma_f32_16x16x32_bf16 v[46:49], v[130:133], v[200:203], v[46:49]
	v_mfma_f32_16x16x32_bf16 v[42:45], v[152:155], v[200:203], v[42:45]
	v_mfma_f32_16x16x32_bf16 v[30:33], v[130:133], v[208:211], v[30:33]
	v_mfma_f32_16x16x32_bf16 v[26:29], v[152:155], v[208:211], v[26:29]
	v_mfma_f32_16x16x32_bf16 v[14:17], v[130:133], v[216:219], v[14:17]
	v_mfma_f32_16x16x32_bf16 v[10:13], v[152:155], v[216:219], v[10:13]
	v_mfma_f32_16x16x32_bf16 v[62:65], v[134:137], v[196:199], v[62:65]
	v_mfma_f32_16x16x32_bf16 v[58:61], v[158:161], v[196:199], v[58:61]
	v_mfma_f32_16x16x32_bf16 v[46:49], v[134:137], v[204:207], v[46:49]
	v_mfma_f32_16x16x32_bf16 v[42:45], v[158:161], v[204:207], v[42:45]
	v_mfma_f32_16x16x32_bf16 v[30:33], v[134:137], v[212:215], v[30:33]
	v_mfma_f32_16x16x32_bf16 v[26:29], v[158:161], v[212:215], v[26:29]
	v_mfma_f32_16x16x32_bf16 v[14:17], v[134:137], v[220:223], v[14:17]
	v_mfma_f32_16x16x32_bf16 v[10:13], v[158:161], v[220:223], v[10:13]
	s_setprio 0
	s_setprio 1
	v_mfma_f32_16x16x32_bf16 v[54:57], v[164:167], v[192:195], v[54:57]
	v_mfma_f32_16x16x32_bf16 v[50:53], v[184:187], v[192:195], v[50:53]
	v_mfma_f32_16x16x32_bf16 v[38:41], v[164:167], v[200:203], v[38:41]
	v_mfma_f32_16x16x32_bf16 v[34:37], v[184:187], v[200:203], v[34:37]
	v_mfma_f32_16x16x32_bf16 v[22:25], v[164:167], v[208:211], v[22:25]
	v_mfma_f32_16x16x32_bf16 v[18:21], v[184:187], v[208:211], v[18:21]
	v_mfma_f32_16x16x32_bf16 v[6:9], v[164:167], v[216:219], v[6:9]
	v_mfma_f32_16x16x32_bf16 v[2:5], v[184:187], v[216:219], v[2:5]
	v_mfma_f32_16x16x32_bf16 v[54:57], v[180:183], v[196:199], v[54:57]
	v_mfma_f32_16x16x32_bf16 v[50:53], v[188:191], v[196:199], v[50:53]
	v_mfma_f32_16x16x32_bf16 v[38:41], v[180:183], v[204:207], v[38:41]
	v_mfma_f32_16x16x32_bf16 v[34:37], v[188:191], v[204:207], v[34:37]
	s_setprio 2
	s_barrier
	v_mfma_f32_16x16x32_bf16 v[22:25], v[180:183], v[212:215], v[22:25]
	v_mfma_f32_16x16x32_bf16 v[18:21], v[188:191], v[212:215], v[18:21]
	v_mfma_f32_16x16x32_bf16 v[6:9], v[180:183], v[220:223], v[6:9]
	v_mfma_f32_16x16x32_bf16 v[2:5], v[188:191], v[220:223], v[2:5]
	s_setprio 0
	s_add_i32 s47, s47, 2
	s_add_u32 s36, s36, 0x100
	s_addc_u32 s37, s37, 0
	s_add_u32 s41, s41, 0x100
	s_addc_u32 s46, s46, 0
	s_cmp_gt_u32 s47, 29
.LBB0_292:
	s_add_u32 s42, s36, 0xfff80080
	s_addc_u32 s43, s37, -1
	s_add_i32 s48, 0, 0x10000
	s_cmp_eq_u32 s47, 28
	s_cselect_b32 s45, s5, s43
	s_cselect_b32 s44, s8, s42
	s_cselect_b32 s43, s19, s46
	s_cselect_b32 s42, s21, s41
	s_add_i32 s50, 0, 0x14000
	v_add_u32_e32 v158, s48, v147
	v_add_u32_e32 v162, s50, v147
	ds_read_b128 v[130:133], v158
	ds_read_b128 v[134:137], v158 offset:1024
	ds_read_b128 v[152:155], v158 offset:2048
	ds_read_b128 v[158:161], v158 offset:3072
	ds_read_b128 v[164:167], v162
	ds_read_b128 v[180:183], v162 offset:1024
	ds_read_b128 v[184:187], v162 offset:2048
	ds_read_b128 v[188:191], v162 offset:3072
	v_lshl_add_u64 v[168:169], s[36:37], 0, v[148:149]
	s_add_i32 m0, s11, 0xc000
	ds_read_b128 v[192:195], v157
	ds_read_b128 v[196:199], v157 offset:1024
	ds_read_b128 v[200:203], v157 offset:2048
	ds_read_b128 v[204:207], v157 offset:3072
	ds_read_b128 v[208:211], v157 offset:4096
	ds_read_b128 v[212:215], v157 offset:5120
	ds_read_b128 v[216:219], v157 offset:6144
	ds_read_b128 v[220:223], v157 offset:7168
	global_load_lds_dwordx4 v[168:169], off
	v_lshl_add_u64 v[168:169], s[36:37], 0, v[150:151]
	s_add_i32 m0, s11, 0xe000
	s_nop 0
	global_load_lds_dwordx4 v[168:169], off
	s_waitcnt vmcnt(8)
	s_waitcnt lgkmcnt(0)
	s_barrier
	s_setprio 1
	s_waitcnt lgkmcnt(0)
	v_mfma_f32_16x16x32_bf16 v[126:129], v[130:133], v[192:195], v[126:129]
	v_mfma_f32_16x16x32_bf16 v[122:125], v[152:155], v[192:195], v[122:125]
	v_mfma_f32_16x16x32_bf16 v[110:113], v[130:133], v[200:203], v[110:113]
	v_mfma_f32_16x16x32_bf16 v[106:109], v[152:155], v[200:203], v[106:109]
	v_mfma_f32_16x16x32_bf16 v[94:97], v[130:133], v[208:211], v[94:97]
	v_mfma_f32_16x16x32_bf16 v[90:93], v[152:155], v[208:211], v[90:93]
	v_mfma_f32_16x16x32_bf16 v[78:81], v[130:133], v[216:219], v[78:81]
	v_mfma_f32_16x16x32_bf16 v[74:77], v[152:155], v[216:219], v[74:77]
	v_mfma_f32_16x16x32_bf16 v[126:129], v[134:137], v[196:199], v[126:129]
	v_mfma_f32_16x16x32_bf16 v[122:125], v[158:161], v[196:199], v[122:125]
	v_mfma_f32_16x16x32_bf16 v[110:113], v[134:137], v[204:207], v[110:113]
	v_mfma_f32_16x16x32_bf16 v[106:109], v[158:161], v[204:207], v[106:109]
	v_mfma_f32_16x16x32_bf16 v[94:97], v[134:137], v[212:215], v[94:97]
	v_mfma_f32_16x16x32_bf16 v[90:93], v[158:161], v[212:215], v[90:93]
	v_mfma_f32_16x16x32_bf16 v[78:81], v[134:137], v[220:223], v[78:81]
	v_mfma_f32_16x16x32_bf16 v[74:77], v[158:161], v[220:223], v[74:77]
	s_setprio 0
	s_setprio 1
	v_mfma_f32_16x16x32_bf16 v[118:121], v[164:167], v[192:195], v[118:121]
	v_mfma_f32_16x16x32_bf16 v[114:117], v[184:187], v[192:195], v[114:117]
	v_mfma_f32_16x16x32_bf16 v[102:105], v[164:167], v[200:203], v[102:105]
	v_mfma_f32_16x16x32_bf16 v[98:101], v[184:187], v[200:203], v[98:101]
	v_mfma_f32_16x16x32_bf16 v[86:89], v[164:167], v[208:211], v[86:89]
	v_mfma_f32_16x16x32_bf16 v[82:85], v[184:187], v[208:211], v[82:85]
	v_mfma_f32_16x16x32_bf16 v[70:73], v[164:167], v[216:219], v[70:73]
	v_mfma_f32_16x16x32_bf16 v[66:69], v[184:187], v[216:219], v[66:69]
	v_mfma_f32_16x16x32_bf16 v[118:121], v[180:183], v[196:199], v[118:121]
	v_mfma_f32_16x16x32_bf16 v[114:117], v[188:191], v[196:199], v[114:117]
	v_mfma_f32_16x16x32_bf16 v[102:105], v[180:183], v[204:207], v[102:105]
	v_mfma_f32_16x16x32_bf16 v[98:101], v[188:191], v[204:207], v[98:101]
	s_setprio 2
	s_barrier
	v_mfma_f32_16x16x32_bf16 v[86:89], v[180:183], v[212:215], v[86:89]
	v_mfma_f32_16x16x32_bf16 v[82:85], v[188:191], v[212:215], v[82:85]
	v_mfma_f32_16x16x32_bf16 v[70:73], v[180:183], v[220:223], v[70:73]
	v_mfma_f32_16x16x32_bf16 v[66:69], v[188:191], v[220:223], v[66:69]
	s_setprio 0
	s_add_i32 s48, s48, s9
	v_lshl_add_u64 v[168:169], s[42:43], 0, v[140:141]
	s_mov_b32 m0, s48
	ds_read_b128 v[192:195], v157 offset:16384
	ds_read_b128 v[196:199], v157 offset:17408
	ds_read_b128 v[200:203], v157 offset:18432
	ds_read_b128 v[204:207], v157 offset:19456
	ds_read_b128 v[208:211], v157 offset:20480
	ds_read_b128 v[212:215], v157 offset:21504
	ds_read_b128 v[216:219], v157 offset:22528
	ds_read_b128 v[220:223], v157 offset:23552
	global_load_lds_dwordx4 v[168:169], off
	s_add_i32 m0, s48, 0x2000
	s_add_u32 s48, s42, 0x80000
	v_lshl_add_u64 v[224:225], s[42:43], 0, v[144:145]
	s_addc_u32 s49, s43, 0
	s_add_i32 s50, s50, s9
	global_load_lds_dwordx4 v[224:225], off
	v_lshl_add_u64 v[226:227], s[48:49], 0, v[140:141]
	s_mov_b32 m0, s50
	v_lshl_add_u64 v[228:229], s[44:45], 0, v[142:143]
	global_load_lds_dwordx4 v[226:227], off
	v_lshl_add_u64 v[226:227], s[48:49], 0, v[144:145]
	s_add_i32 m0, s50, 0x2000
	s_nop 0
	global_load_lds_dwordx4 v[226:227], off
	v_lshl_add_u64 v[226:227], s[44:45], 0, v[138:139]
	s_mov_b32 m0, s11
	s_nop 0
	global_load_lds_dwordx4 v[226:227], off
	s_mov_b32 m0, s13
	s_nop 0
	global_load_lds_dwordx4 v[228:229], off
	s_waitcnt vmcnt(8)
	s_waitcnt lgkmcnt(0)
	s_barrier
	s_setprio 1
	s_waitcnt lgkmcnt(0)
	v_mfma_f32_16x16x32_bf16 v[62:65], v[130:133], v[192:195], v[62:65]
	v_mfma_f32_16x16x32_bf16 v[58:61], v[152:155], v[192:195], v[58:61]
	v_mfma_f32_16x16x32_bf16 v[46:49], v[130:133], v[200:203], v[46:49]
	v_mfma_f32_16x16x32_bf16 v[42:45], v[152:155], v[200:203], v[42:45]
	v_mfma_f32_16x16x32_bf16 v[30:33], v[130:133], v[208:211], v[30:33]
	v_mfma_f32_16x16x32_bf16 v[26:29], v[152:155], v[208:211], v[26:29]
	v_mfma_f32_16x16x32_bf16 v[14:17], v[130:133], v[216:219], v[14:17]
	v_mfma_f32_16x16x32_bf16 v[10:13], v[152:155], v[216:219], v[10:13]
	v_mfma_f32_16x16x32_bf16 v[62:65], v[134:137], v[196:199], v[62:65]
	v_mfma_f32_16x16x32_bf16 v[58:61], v[158:161], v[196:199], v[58:61]
	v_mfma_f32_16x16x32_bf16 v[46:49], v[134:137], v[204:207], v[46:49]
	v_mfma_f32_16x16x32_bf16 v[42:45], v[158:161], v[204:207], v[42:45]
	v_mfma_f32_16x16x32_bf16 v[30:33], v[134:137], v[212:215], v[30:33]
	v_mfma_f32_16x16x32_bf16 v[26:29], v[158:161], v[212:215], v[26:29]
	v_mfma_f32_16x16x32_bf16 v[14:17], v[134:137], v[220:223], v[14:17]
	v_mfma_f32_16x16x32_bf16 v[10:13], v[158:161], v[220:223], v[10:13]
	s_setprio 0
	s_setprio 1
	v_mfma_f32_16x16x32_bf16 v[54:57], v[164:167], v[192:195], v[54:57]
	v_mfma_f32_16x16x32_bf16 v[50:53], v[184:187], v[192:195], v[50:53]
	v_mfma_f32_16x16x32_bf16 v[38:41], v[164:167], v[200:203], v[38:41]
	v_mfma_f32_16x16x32_bf16 v[34:37], v[184:187], v[200:203], v[34:37]
	v_mfma_f32_16x16x32_bf16 v[22:25], v[164:167], v[208:211], v[22:25]
	v_mfma_f32_16x16x32_bf16 v[18:21], v[184:187], v[208:211], v[18:21]
	v_mfma_f32_16x16x32_bf16 v[6:9], v[164:167], v[216:219], v[6:9]
	v_mfma_f32_16x16x32_bf16 v[2:5], v[184:187], v[216:219], v[2:5]
	v_mfma_f32_16x16x32_bf16 v[54:57], v[180:183], v[196:199], v[54:57]
	v_mfma_f32_16x16x32_bf16 v[50:53], v[188:191], v[196:199], v[50:53]
	v_mfma_f32_16x16x32_bf16 v[38:41], v[180:183], v[204:207], v[38:41]
	v_mfma_f32_16x16x32_bf16 v[34:37], v[188:191], v[204:207], v[34:37]
	s_setprio 2
	s_barrier
	v_mfma_f32_16x16x32_bf16 v[22:25], v[180:183], v[212:215], v[22:25]
	v_mfma_f32_16x16x32_bf16 v[18:21], v[188:191], v[212:215], v[18:21]
	v_mfma_f32_16x16x32_bf16 v[6:9], v[180:183], v[220:223], v[6:9]
	v_mfma_f32_16x16x32_bf16 v[2:5], v[188:191], v[220:223], v[2:5]
	s_setprio 0
	s_add_i32 s48, 0, 0x18000
	s_add_i32 s49, 0, 0x1c000
	v_add_u32_e32 v158, s48, v147
	v_add_u32_e32 v162, s49, v147
	ds_read_b128 v[130:133], v158
	ds_read_b128 v[134:137], v158 offset:1024
	ds_read_b128 v[152:155], v158 offset:2048
	ds_read_b128 v[158:161], v158 offset:3072
	ds_read_b128 v[164:167], v162
	ds_read_b128 v[180:183], v162 offset:1024
	ds_read_b128 v[184:187], v162 offset:2048
	ds_read_b128 v[188:191], v162 offset:3072
	s_add_u32 s44, s44, 0x80000
	s_addc_u32 s45, s45, 0
	s_mov_b32 m0, s20
	v_lshl_add_u64 v[230:231], s[44:45], 0, v[138:139]
	ds_read_b128 v[192:195], v157 offset:32768
	ds_read_b128 v[196:199], v157 offset:33792
	ds_read_b128 v[200:203], v157 offset:34816
	ds_read_b128 v[204:207], v157 offset:35840
	ds_read_b128 v[208:211], v157 offset:36864
	ds_read_b128 v[212:215], v157 offset:37888
	ds_read_b128 v[216:219], v157 offset:38912
	ds_read_b128 v[220:223], v157 offset:39936
	global_load_lds_dwordx4 v[230:231], off
	v_lshl_add_u64 v[230:231], s[44:45], 0, v[142:143]
	s_mov_b32 m0, s25
	s_nop 0
	global_load_lds_dwordx4 v[230:231], off
	s_waitcnt vmcnt(8)
	s_waitcnt lgkmcnt(0)
	s_barrier
	s_setprio 1
	s_waitcnt lgkmcnt(0)
	v_mfma_f32_16x16x32_bf16 v[126:129], v[130:133], v[192:195], v[126:129]
	v_mfma_f32_16x16x32_bf16 v[122:125], v[152:155], v[192:195], v[122:125]
	v_mfma_f32_16x16x32_bf16 v[110:113], v[130:133], v[200:203], v[110:113]
	v_mfma_f32_16x16x32_bf16 v[106:109], v[152:155], v[200:203], v[106:109]
	v_mfma_f32_16x16x32_bf16 v[94:97], v[130:133], v[208:211], v[94:97]
	v_mfma_f32_16x16x32_bf16 v[90:93], v[152:155], v[208:211], v[90:93]
	v_mfma_f32_16x16x32_bf16 v[78:81], v[130:133], v[216:219], v[78:81]
	v_mfma_f32_16x16x32_bf16 v[74:77], v[152:155], v[216:219], v[74:77]
	v_mfma_f32_16x16x32_bf16 v[126:129], v[134:137], v[196:199], v[126:129]
	v_mfma_f32_16x16x32_bf16 v[122:125], v[158:161], v[196:199], v[122:125]
	v_mfma_f32_16x16x32_bf16 v[110:113], v[134:137], v[204:207], v[110:113]
	v_mfma_f32_16x16x32_bf16 v[106:109], v[158:161], v[204:207], v[106:109]
	v_mfma_f32_16x16x32_bf16 v[94:97], v[134:137], v[212:215], v[94:97]
	v_mfma_f32_16x16x32_bf16 v[90:93], v[158:161], v[212:215], v[90:93]
	v_mfma_f32_16x16x32_bf16 v[78:81], v[134:137], v[220:223], v[78:81]
	v_mfma_f32_16x16x32_bf16 v[74:77], v[158:161], v[220:223], v[74:77]
	s_setprio 0
	s_setprio 1
	v_mfma_f32_16x16x32_bf16 v[118:121], v[164:167], v[192:195], v[118:121]
	v_mfma_f32_16x16x32_bf16 v[114:117], v[184:187], v[192:195], v[114:117]
	v_mfma_f32_16x16x32_bf16 v[102:105], v[164:167], v[200:203], v[102:105]
	v_mfma_f32_16x16x32_bf16 v[98:101], v[184:187], v[200:203], v[98:101]
	v_mfma_f32_16x16x32_bf16 v[86:89], v[164:167], v[208:211], v[86:89]
	v_mfma_f32_16x16x32_bf16 v[82:85], v[184:187], v[208:211], v[82:85]
	v_mfma_f32_16x16x32_bf16 v[70:73], v[164:167], v[216:219], v[70:73]
	v_mfma_f32_16x16x32_bf16 v[66:69], v[184:187], v[216:219], v[66:69]
	v_mfma_f32_16x16x32_bf16 v[118:121], v[180:183], v[196:199], v[118:121]
	v_mfma_f32_16x16x32_bf16 v[114:117], v[188:191], v[196:199], v[114:117]
	v_mfma_f32_16x16x32_bf16 v[102:105], v[180:183], v[204:207], v[102:105]
	v_mfma_f32_16x16x32_bf16 v[98:101], v[188:191], v[204:207], v[98:101]
	s_setprio 2
	s_barrier
	v_mfma_f32_16x16x32_bf16 v[86:89], v[180:183], v[212:215], v[86:89]
	v_mfma_f32_16x16x32_bf16 v[82:85], v[188:191], v[212:215], v[82:85]
	v_mfma_f32_16x16x32_bf16 v[70:73], v[180:183], v[220:223], v[70:73]
	v_mfma_f32_16x16x32_bf16 v[66:69], v[188:191], v[220:223], v[66:69]
	s_setprio 0
	s_add_i32 s44, s48, s9
	v_lshl_add_u64 v[168:169], v[168:169], 0, s[6:7]
	s_mov_b32 m0, s44
	ds_read_b128 v[192:195], v157 offset:49152
	ds_read_b128 v[196:199], v157 offset:50176
	ds_read_b128 v[200:203], v157 offset:51200
	ds_read_b128 v[204:207], v157 offset:52224
	ds_read_b128 v[208:211], v157 offset:53248
	ds_read_b128 v[212:215], v157 offset:54272
	ds_read_b128 v[216:219], v157 offset:55296
	ds_read_b128 v[220:223], v157 offset:56320
	global_load_lds_dwordx4 v[168:169], off
	s_add_i32 m0, s44, 0x2000
	s_add_u32 s42, s42, 0x80080
	v_lshl_add_u64 v[168:169], v[224:225], 0, s[6:7]
	s_addc_u32 s43, s43, 0
	s_add_i32 s44, s49, s9
	global_load_lds_dwordx4 v[168:169], off
	v_lshl_add_u64 v[168:169], s[42:43], 0, v[140:141]
	s_mov_b32 m0, s44
	s_nop 0
	global_load_lds_dwordx4 v[168:169], off
	v_lshl_add_u64 v[168:169], s[42:43], 0, v[144:145]
	s_add_i32 m0, s44, 0x2000
	s_nop 0
	global_load_lds_dwordx4 v[168:169], off
	v_lshl_add_u64 v[168:169], v[226:227], 0, s[6:7]
	s_mov_b32 m0, s26
	s_nop 0
	global_load_lds_dwordx4 v[168:169], off
	v_lshl_add_u64 v[168:169], v[228:229], 0, s[6:7]
	s_mov_b32 m0, s27
	s_nop 0
	global_load_lds_dwordx4 v[168:169], off
	s_waitcnt vmcnt(8)
	s_waitcnt lgkmcnt(0)
	s_barrier
	s_setprio 1
	s_waitcnt lgkmcnt(0)
	v_mfma_f32_16x16x32_bf16 v[62:65], v[130:133], v[192:195], v[62:65]
	v_mfma_f32_16x16x32_bf16 v[58:61], v[152:155], v[192:195], v[58:61]
	v_mfma_f32_16x16x32_bf16 v[46:49], v[130:133], v[200:203], v[46:49]
	v_mfma_f32_16x16x32_bf16 v[42:45], v[152:155], v[200:203], v[42:45]
	v_mfma_f32_16x16x32_bf16 v[30:33], v[130:133], v[208:211], v[30:33]
	v_mfma_f32_16x16x32_bf16 v[26:29], v[152:155], v[208:211], v[26:29]
	v_mfma_f32_16x16x32_bf16 v[14:17], v[130:133], v[216:219], v[14:17]
	v_mfma_f32_16x16x32_bf16 v[10:13], v[152:155], v[216:219], v[10:13]
	v_mfma_f32_16x16x32_bf16 v[62:65], v[134:137], v[196:199], v[62:65]
	v_mfma_f32_16x16x32_bf16 v[58:61], v[158:161], v[196:199], v[58:61]
	v_mfma_f32_16x16x32_bf16 v[46:49], v[134:137], v[204:207], v[46:49]
	v_mfma_f32_16x16x32_bf16 v[42:45], v[158:161], v[204:207], v[42:45]
	v_mfma_f32_16x16x32_bf16 v[30:33], v[134:137], v[212:215], v[30:33]
	v_mfma_f32_16x16x32_bf16 v[26:29], v[158:161], v[212:215], v[26:29]
	v_mfma_f32_16x16x32_bf16 v[14:17], v[134:137], v[220:223], v[14:17]
	v_mfma_f32_16x16x32_bf16 v[10:13], v[158:161], v[220:223], v[10:13]
	s_setprio 0
	s_setprio 1
	v_mfma_f32_16x16x32_bf16 v[54:57], v[164:167], v[192:195], v[54:57]
	v_mfma_f32_16x16x32_bf16 v[50:53], v[184:187], v[192:195], v[50:53]
	v_mfma_f32_16x16x32_bf16 v[38:41], v[164:167], v[200:203], v[38:41]
	v_mfma_f32_16x16x32_bf16 v[34:37], v[184:187], v[200:203], v[34:37]
	v_mfma_f32_16x16x32_bf16 v[22:25], v[164:167], v[208:211], v[22:25]
	v_mfma_f32_16x16x32_bf16 v[18:21], v[184:187], v[208:211], v[18:21]
	v_mfma_f32_16x16x32_bf16 v[6:9], v[164:167], v[216:219], v[6:9]
	v_mfma_f32_16x16x32_bf16 v[2:5], v[184:187], v[216:219], v[2:5]
	v_mfma_f32_16x16x32_bf16 v[54:57], v[180:183], v[196:199], v[54:57]
	v_mfma_f32_16x16x32_bf16 v[50:53], v[188:191], v[196:199], v[50:53]
	v_mfma_f32_16x16x32_bf16 v[38:41], v[180:183], v[204:207], v[38:41]
	v_mfma_f32_16x16x32_bf16 v[34:37], v[188:191], v[204:207], v[34:37]
	s_setprio 2
	s_barrier
	v_mfma_f32_16x16x32_bf16 v[22:25], v[180:183], v[212:215], v[22:25]
	v_mfma_f32_16x16x32_bf16 v[18:21], v[188:191], v[212:215], v[18:21]
	v_mfma_f32_16x16x32_bf16 v[6:9], v[180:183], v[220:223], v[6:9]
	v_mfma_f32_16x16x32_bf16 v[2:5], v[188:191], v[220:223], v[2:5]
	s_setprio 0
	s_add_i32 s47, s47, 2
	s_add_u32 s36, s36, 0x100
	s_addc_u32 s37, s37, 0
	s_add_u32 s41, s41, 0x100
	s_addc_u32 s46, s46, 0
	s_cmp_gt_u32 s47, 29
	s_cbranch_scc0 .LBB0_292
	s_and_b64 vcc, exec, s[2:3]
	s_cbranch_vccz .LBB0_295
	s_barrier

.LBB0_357:
	s_ashr_i32 s19, s18, 31
	s_lshl_b64 s[8:9], s[18:19], 20
	v_readlane_b32 s5, v243, 17
	s_add_u32 s28, s5, s8
	v_readlane_b32 s5, v243, 18
	s_addc_u32 s29, s5, s9
	s_and_b64 s[8:9], s[34:35], exec
	s_cselect_b32 s8, s29, s37
	s_cselect_b32 s9, s28, s36
	s_ashr_i32 s5, s4, 31
	s_lshl_b64 s[20:21], s[4:5], 20
	s_add_u32 s38, s30, s20
	v_readlane_b32 s5, v242, 4
	s_addc_u32 s39, s5, s21
	s_and_b64 s[20:21], s[34:35], exec
	s_cselect_b32 s5, s39, s43
	s_cselect_b32 s11, s38, s42
	s_add_u32 s36, s36, 0x80080
	s_addc_u32 s37, s37, 0
	s_add_u32 s13, s42, 0x100
	s_addc_u32 s19, s43, 0
	s_mov_b32 s20, -2
	s_waitcnt vmcnt(0)
	s_add_u32 s21, s36, 0xfff80080
	s_addc_u32 s23, s37, -1
	s_add_i32 s26, 0, 0x10000
	s_cmp_eq_u32 s20, 28
	s_cselect_b32 s45, s8, s23
	s_cselect_b32 s44, s9, s21
	v_add_u32_e32 v153, s26, v179
	s_cselect_b32 s43, s5, s19
	s_cselect_b32 s42, s11, s13
	s_add_i32 s21, 0, 0x14000
	ds_read_b128 v[130:133], v153
	ds_read_b128 v[134:137], v153 offset:1024
	ds_read_b128 v[164:167], v153 offset:2048
	ds_read_b128 v[182:185], v153 offset:3072
	v_add_u32_e32 v153, s21, v179
	ds_read_b128 v[186:189], v153
	ds_read_b128 v[190:193], v153 offset:1024
	ds_read_b128 v[194:197], v153 offset:2048
	ds_read_b128 v[198:201], v153 offset:3072
	v_lshl_add_u64 v[168:169], s[36:37], 0, v[148:149]
	s_add_i32 m0, s27, 0xc000
	ds_read_b128 v[202:205], v181
	ds_read_b128 v[206:209], v181 offset:1024
	ds_read_b128 v[210:213], v181 offset:2048
	ds_read_b128 v[214:217], v181 offset:3072
	ds_read_b128 v[218:221], v181 offset:4096
	ds_read_b128 v[222:225], v181 offset:5120
	ds_read_b128 v[226:229], v181 offset:6144
	ds_read_b128 v[230:233], v181 offset:7168
	global_load_lds_dwordx4 v[168:169], off
	v_lshl_add_u64 v[168:169], s[36:37], 0, v[150:151]
	s_add_i32 m0, s27, 0xe000
	s_nop 0
	global_load_lds_dwordx4 v[168:169], off
	s_waitcnt vmcnt(8)
	s_waitcnt lgkmcnt(0)
	s_barrier
	s_setprio 1
	s_waitcnt lgkmcnt(0)
	v_mfma_f32_16x16x32_bf16 v[126:129], v[130:133], v[202:205], 0
	v_mfma_f32_16x16x32_bf16 v[122:125], v[164:167], v[202:205], 0
	v_mfma_f32_16x16x32_bf16 v[110:113], v[130:133], v[210:213], 0
	v_mfma_f32_16x16x32_bf16 v[106:109], v[164:167], v[210:213], 0
	v_mfma_f32_16x16x32_bf16 v[94:97], v[130:133], v[218:221], 0
	v_mfma_f32_16x16x32_bf16 v[90:93], v[164:167], v[218:221], 0
	v_mfma_f32_16x16x32_bf16 v[78:81], v[130:133], v[226:229], 0
	v_mfma_f32_16x16x32_bf16 v[74:77], v[164:167], v[226:229], 0
	v_mfma_f32_16x16x32_bf16 v[126:129], v[134:137], v[206:209], v[126:129]
	v_mfma_f32_16x16x32_bf16 v[122:125], v[182:185], v[206:209], v[122:125]
	v_mfma_f32_16x16x32_bf16 v[110:113], v[134:137], v[214:217], v[110:113]
	v_mfma_f32_16x16x32_bf16 v[106:109], v[182:185], v[214:217], v[106:109]
	v_mfma_f32_16x16x32_bf16 v[94:97], v[134:137], v[222:225], v[94:97]
	v_mfma_f32_16x16x32_bf16 v[90:93], v[182:185], v[222:225], v[90:93]
	v_mfma_f32_16x16x32_bf16 v[78:81], v[134:137], v[230:233], v[78:81]
	v_mfma_f32_16x16x32_bf16 v[74:77], v[182:185], v[230:233], v[74:77]
	s_setprio 0
	s_setprio 1
	v_mfma_f32_16x16x32_bf16 v[118:121], v[186:189], v[202:205], 0
	v_mfma_f32_16x16x32_bf16 v[114:117], v[194:197], v[202:205], 0
	v_mfma_f32_16x16x32_bf16 v[102:105], v[186:189], v[210:213], 0
	v_mfma_f32_16x16x32_bf16 v[98:101], v[194:197], v[210:213], 0
	v_mfma_f32_16x16x32_bf16 v[86:89], v[186:189], v[218:221], 0
	v_mfma_f32_16x16x32_bf16 v[82:85], v[194:197], v[218:221], 0
	v_mfma_f32_16x16x32_bf16 v[70:73], v[186:189], v[226:229], 0
	v_mfma_f32_16x16x32_bf16 v[66:69], v[194:197], v[226:229], 0
	v_mfma_f32_16x16x32_bf16 v[118:121], v[190:193], v[206:209], v[118:121]
	v_mfma_f32_16x16x32_bf16 v[114:117], v[198:201], v[206:209], v[114:117]
	v_mfma_f32_16x16x32_bf16 v[102:105], v[190:193], v[214:217], v[102:105]
	v_mfma_f32_16x16x32_bf16 v[98:101], v[198:201], v[214:217], v[98:101]
	s_setprio 2
	s_barrier
	v_mfma_f32_16x16x32_bf16 v[86:89], v[190:193], v[222:225], v[86:89]
	v_mfma_f32_16x16x32_bf16 v[82:85], v[198:201], v[222:225], v[82:85]
	v_mfma_f32_16x16x32_bf16 v[70:73], v[190:193], v[230:233], v[70:73]
	v_mfma_f32_16x16x32_bf16 v[66:69], v[198:201], v[230:233], v[66:69]
	s_setprio 0
	s_add_i32 s23, s26, s25
	v_lshl_add_u64 v[168:169], s[42:43], 0, v[162:163]
	s_mov_b32 m0, s23
	ds_read_b128 v[202:205], v181 offset:16384
	ds_read_b128 v[206:209], v181 offset:17408
	ds_read_b128 v[210:213], v181 offset:18432
	ds_read_b128 v[214:217], v181 offset:19456
	ds_read_b128 v[218:221], v181 offset:20480
	ds_read_b128 v[222:225], v181 offset:21504
	ds_read_b128 v[226:229], v181 offset:22528
	ds_read_b128 v[230:233], v181 offset:23552
	global_load_lds_dwordx4 v[168:169], off
	s_add_i32 m0, s23, 0x2000
	s_add_u32 s52, s42, 0x80000
	v_lshl_add_u64 v[234:235], s[42:43], 0, v[142:143]
	s_addc_u32 s53, s43, 0
	s_add_i32 s21, s21, s25
	global_load_lds_dwordx4 v[234:235], off
	v_lshl_add_u64 v[236:237], s[52:53], 0, v[162:163]
	s_mov_b32 m0, s21
	v_lshl_add_u64 v[238:239], s[44:45], 0, v[140:141]
	global_load_lds_dwordx4 v[236:237], off
	v_lshl_add_u64 v[236:237], s[52:53], 0, v[142:143]
	s_add_i32 m0, s21, 0x2000
	s_nop 0
	global_load_lds_dwordx4 v[236:237], off
	v_lshl_add_u64 v[236:237], s[44:45], 0, v[138:139]
	s_mov_b32 m0, s27
	s_nop 0
	global_load_lds_dwordx4 v[236:237], off
	s_mov_b32 m0, s46
	s_nop 0
	global_load_lds_dwordx4 v[238:239], off
	s_waitcnt vmcnt(8)
	s_waitcnt lgkmcnt(0)
	s_barrier
	s_setprio 1
	s_waitcnt lgkmcnt(0)
	v_mfma_f32_16x16x32_bf16 v[62:65], v[130:133], v[202:205], 0
	v_mfma_f32_16x16x32_bf16 v[58:61], v[164:167], v[202:205], 0
	v_mfma_f32_16x16x32_bf16 v[46:49], v[130:133], v[210:213], 0
	v_mfma_f32_16x16x32_bf16 v[42:45], v[164:167], v[210:213], 0
	v_mfma_f32_16x16x32_bf16 v[30:33], v[130:133], v[218:221], 0
	v_mfma_f32_16x16x32_bf16 v[26:29], v[164:167], v[218:221], 0
	v_mfma_f32_16x16x32_bf16 v[14:17], v[130:133], v[226:229], 0
	v_mfma_f32_16x16x32_bf16 v[10:13], v[164:167], v[226:229], 0
	v_mfma_f32_16x16x32_bf16 v[62:65], v[134:137], v[206:209], v[62:65]
	v_mfma_f32_16x16x32_bf16 v[58:61], v[182:185], v[206:209], v[58:61]
	v_mfma_f32_16x16x32_bf16 v[46:49], v[134:137], v[214:217], v[46:49]
	v_mfma_f32_16x16x32_bf16 v[42:45], v[182:185], v[214:217], v[42:45]
	v_mfma_f32_16x16x32_bf16 v[30:33], v[134:137], v[222:225], v[30:33]
	v_mfma_f32_16x16x32_bf16 v[26:29], v[182:185], v[222:225], v[26:29]
	v_mfma_f32_16x16x32_bf16 v[14:17], v[134:137], v[230:233], v[14:17]
	v_mfma_f32_16x16x32_bf16 v[10:13], v[182:185], v[230:233], v[10:13]
	s_setprio 0
	s_setprio 1
	v_mfma_f32_16x16x32_bf16 v[54:57], v[186:189], v[202:205], 0
	v_mfma_f32_16x16x32_bf16 v[50:53], v[194:197], v[202:205], 0
	v_mfma_f32_16x16x32_bf16 v[38:41], v[186:189], v[210:213], 0
	v_mfma_f32_16x16x32_bf16 v[34:37], v[194:197], v[210:213], 0
	v_mfma_f32_16x16x32_bf16 v[22:25], v[186:189], v[218:221], 0
	v_mfma_f32_16x16x32_bf16 v[18:21], v[194:197], v[218:221], 0
	v_mfma_f32_16x16x32_bf16 v[6:9], v[186:189], v[226:229], 0
	v_mfma_f32_16x16x32_bf16 v[2:5], v[194:197], v[226:229], 0
	v_mfma_f32_16x16x32_bf16 v[54:57], v[190:193], v[206:209], v[54:57]
	v_mfma_f32_16x16x32_bf16 v[50:53], v[198:201], v[206:209], v[50:53]
	v_mfma_f32_16x16x32_bf16 v[38:41], v[190:193], v[214:217], v[38:41]
	v_mfma_f32_16x16x32_bf16 v[34:37], v[198:201], v[214:217], v[34:37]
	s_setprio 2
	s_barrier
	v_mfma_f32_16x16x32_bf16 v[22:25], v[190:193], v[222:225], v[22:25]
	v_mfma_f32_16x16x32_bf16 v[18:21], v[198:201], v[222:225], v[18:21]
	v_mfma_f32_16x16x32_bf16 v[6:9], v[190:193], v[230:233], v[6:9]
	v_mfma_f32_16x16x32_bf16 v[2:5], v[198:201], v[230:233], v[2:5]
	s_setprio 0
	s_add_i32 s21, 0, 0x18000
	v_add_u32_e32 v153, s21, v179
	s_add_i32 s23, 0, 0x1c000
	ds_read_b128 v[130:133], v153
	ds_read_b128 v[134:137], v153 offset:1024
	ds_read_b128 v[164:167], v153 offset:2048
	ds_read_b128 v[182:185], v153 offset:3072
	v_add_u32_e32 v153, s23, v179
	ds_read_b128 v[186:189], v153
	ds_read_b128 v[190:193], v153 offset:1024
	ds_read_b128 v[194:197], v153 offset:2048
	ds_read_b128 v[198:201], v153 offset:3072
	s_add_u32 s44, s44, 0x80000
	s_addc_u32 s45, s45, 0
	s_mov_b32 m0, s47
	v_lshl_add_u64 v[240:241], s[44:45], 0, v[138:139]
	ds_read_b128 v[202:205], v181 offset:32768
	ds_read_b128 v[206:209], v181 offset:33792
	ds_read_b128 v[210:213], v181 offset:34816
	ds_read_b128 v[214:217], v181 offset:35840
	ds_read_b128 v[218:221], v181 offset:36864
	ds_read_b128 v[222:225], v181 offset:37888
	ds_read_b128 v[226:229], v181 offset:38912
	ds_read_b128 v[230:233], v181 offset:39936
	global_load_lds_dwordx4 v[240:241], off
	v_lshl_add_u64 v[240:241], s[44:45], 0, v[140:141]
	s_mov_b32 m0, s48
	s_nop 0
	global_load_lds_dwordx4 v[240:241], off
	s_waitcnt vmcnt(8)
	s_waitcnt lgkmcnt(0)
	s_barrier
	s_setprio 1
	s_waitcnt lgkmcnt(0)
	v_mfma_f32_16x16x32_bf16 v[126:129], v[130:133], v[202:205], v[126:129]
	v_mfma_f32_16x16x32_bf16 v[122:125], v[164:167], v[202:205], v[122:125]
	v_mfma_f32_16x16x32_bf16 v[110:113], v[130:133], v[210:213], v[110:113]
	v_mfma_f32_16x16x32_bf16 v[106:109], v[164:167], v[210:213], v[106:109]
	v_mfma_f32_16x16x32_bf16 v[94:97], v[130:133], v[218:221], v[94:97]
	v_mfma_f32_16x16x32_bf16 v[90:93], v[164:167], v[218:221], v[90:93]
	v_mfma_f32_16x16x32_bf16 v[78:81], v[130:133], v[226:229], v[78:81]
	v_mfma_f32_16x16x32_bf16 v[74:77], v[164:167], v[226:229], v[74:77]
	v_mfma_f32_16x16x32_bf16 v[126:129], v[134:137], v[206:209], v[126:129]
	v_mfma_f32_16x16x32_bf16 v[122:125], v[182:185], v[206:209], v[122:125]
	v_mfma_f32_16x16x32_bf16 v[110:113], v[134:137], v[214:217], v[110:113]
	v_mfma_f32_16x16x32_bf16 v[106:109], v[182:185], v[214:217], v[106:109]
	v_mfma_f32_16x16x32_bf16 v[94:97], v[134:137], v[222:225], v[94:97]
	v_mfma_f32_16x16x32_bf16 v[90:93], v[182:185], v[222:225], v[90:93]
	v_mfma_f32_16x16x32_bf16 v[78:81], v[134:137], v[230:233], v[78:81]
	v_mfma_f32_16x16x32_bf16 v[74:77], v[182:185], v[230:233], v[74:77]
	s_setprio 0
	s_setprio 1
	v_mfma_f32_16x16x32_bf16 v[118:121], v[186:189], v[202:205], v[118:121]
	v_mfma_f32_16x16x32_bf16 v[114:117], v[194:197], v[202:205], v[114:117]
	v_mfma_f32_16x16x32_bf16 v[102:105], v[186:189], v[210:213], v[102:105]
	v_mfma_f32_16x16x32_bf16 v[98:101], v[194:197], v[210:213], v[98:101]
	v_mfma_f32_16x16x32_bf16 v[86:89], v[186:189], v[218:221], v[86:89]
	v_mfma_f32_16x16x32_bf16 v[82:85], v[194:197], v[218:221], v[82:85]
	v_mfma_f32_16x16x32_bf16 v[70:73], v[186:189], v[226:229], v[70:73]
	v_mfma_f32_16x16x32_bf16 v[66:69], v[194:197], v[226:229], v[66:69]
	v_mfma_f32_16x16x32_bf16 v[118:121], v[190:193], v[206:209], v[118:121]
	v_mfma_f32_16x16x32_bf16 v[114:117], v[198:201], v[206:209], v[114:117]
	v_mfma_f32_16x16x32_bf16 v[102:105], v[190:193], v[214:217], v[102:105]
	v_mfma_f32_16x16x32_bf16 v[98:101], v[198:201], v[214:217], v[98:101]
	s_setprio 2
	s_barrier
	v_mfma_f32_16x16x32_bf16 v[86:89], v[190:193], v[222:225], v[86:89]
	v_mfma_f32_16x16x32_bf16 v[82:85], v[198:201], v[222:225], v[82:85]
	v_mfma_f32_16x16x32_bf16 v[70:73], v[190:193], v[230:233], v[70:73]
	v_mfma_f32_16x16x32_bf16 v[66:69], v[198:201], v[230:233], v[66:69]
	s_setprio 0
	s_add_i32 s21, s21, s25
	v_lshl_add_u64 v[168:169], v[168:169], 0, s[6:7]
	s_mov_b32 m0, s21
	ds_read_b128 v[202:205], v181 offset:49152
	ds_read_b128 v[206:209], v181 offset:50176
	ds_read_b128 v[210:213], v181 offset:51200
	ds_read_b128 v[214:217], v181 offset:52224
	ds_read_b128 v[218:221], v181 offset:53248
	ds_read_b128 v[222:225], v181 offset:54272
	ds_read_b128 v[226:229], v181 offset:55296
	ds_read_b128 v[230:233], v181 offset:56320
	global_load_lds_dwordx4 v[168:169], off
	s_add_i32 m0, s21, 0x2000
	s_add_u32 s42, s42, 0x80080
	v_lshl_add_u64 v[168:169], v[234:235], 0, s[6:7]
	s_addc_u32 s43, s43, 0
	s_add_i32 s21, s23, s25
	global_load_lds_dwordx4 v[168:169], off
	v_lshl_add_u64 v[168:169], s[42:43], 0, v[162:163]
	s_mov_b32 m0, s21
	s_nop 0
	global_load_lds_dwordx4 v[168:169], off
	v_lshl_add_u64 v[168:169], s[42:43], 0, v[142:143]
	s_add_i32 m0, s21, 0x2000
	s_nop 0
	global_load_lds_dwordx4 v[168:169], off
	v_lshl_add_u64 v[168:169], v[236:237], 0, s[6:7]
	s_mov_b32 m0, s49
	s_nop 0
	global_load_lds_dwordx4 v[168:169], off
	v_lshl_add_u64 v[168:169], v[238:239], 0, s[6:7]
	s_mov_b32 m0, s50
	s_nop 0
	global_load_lds_dwordx4 v[168:169], off
	s_waitcnt vmcnt(8)
	s_waitcnt lgkmcnt(0)
	s_barrier
	s_setprio 1
	s_waitcnt lgkmcnt(0)
	v_mfma_f32_16x16x32_bf16 v[62:65], v[130:133], v[202:205], v[62:65]
	v_mfma_f32_16x16x32_bf16 v[58:61], v[164:167], v[202:205], v[58:61]
	v_mfma_f32_16x16x32_bf16 v[46:49], v[130:133], v[210:213], v[46:49]
	v_mfma_f32_16x16x32_bf16 v[42:45], v[164:167], v[210:213], v[42:45]
	v_mfma_f32_16x16x32_bf16 v[30:33], v[130:133], v[218:221], v[30:33]
	v_mfma_f32_16x16x32_bf16 v[26:29], v[164:167], v[218:221], v[26:29]
	v_mfma_f32_16x16x32_bf16 v[14:17], v[130:133], v[226:229], v[14:17]
	v_mfma_f32_16x16x32_bf16 v[10:13], v[164:167], v[226:229], v[10:13]
	v_mfma_f32_16x16x32_bf16 v[62:65], v[134:137], v[206:209], v[62:65]
	v_mfma_f32_16x16x32_bf16 v[58:61], v[182:185], v[206:209], v[58:61]
	v_mfma_f32_16x16x32_bf16 v[46:49], v[134:137], v[214:217], v[46:49]
	v_mfma_f32_16x16x32_bf16 v[42:45], v[182:185], v[214:217], v[42:45]
	v_mfma_f32_16x16x32_bf16 v[30:33], v[134:137], v[222:225], v[30:33]
	v_mfma_f32_16x16x32_bf16 v[26:29], v[182:185], v[222:225], v[26:29]
	v_mfma_f32_16x16x32_bf16 v[14:17], v[134:137], v[230:233], v[14:17]
	v_mfma_f32_16x16x32_bf16 v[10:13], v[182:185], v[230:233], v[10:13]
	s_setprio 0
	s_setprio 1
	v_mfma_f32_16x16x32_bf16 v[54:57], v[186:189], v[202:205], v[54:57]
	v_mfma_f32_16x16x32_bf16 v[50:53], v[194:197], v[202:205], v[50:53]
	v_mfma_f32_16x16x32_bf16 v[38:41], v[186:189], v[210:213], v[38:41]
	v_mfma_f32_16x16x32_bf16 v[34:37], v[194:197], v[210:213], v[34:37]
	v_mfma_f32_16x16x32_bf16 v[22:25], v[186:189], v[218:221], v[22:25]
	v_mfma_f32_16x16x32_bf16 v[18:21], v[194:197], v[218:221], v[18:21]
	v_mfma_f32_16x16x32_bf16 v[6:9], v[186:189], v[226:229], v[6:9]
	v_mfma_f32_16x16x32_bf16 v[2:5], v[194:197], v[226:229], v[2:5]
	v_mfma_f32_16x16x32_bf16 v[54:57], v[190:193], v[206:209], v[54:57]
	v_mfma_f32_16x16x32_bf16 v[50:53], v[198:201], v[206:209], v[50:53]
	v_mfma_f32_16x16x32_bf16 v[38:41], v[190:193], v[214:217], v[38:41]
	v_mfma_f32_16x16x32_bf16 v[34:37], v[198:201], v[214:217], v[34:37]
	s_setprio 2
	s_barrier
	v_mfma_f32_16x16x32_bf16 v[22:25], v[190:193], v[222:225], v[22:25]
	v_mfma_f32_16x16x32_bf16 v[18:21], v[198:201], v[222:225], v[18:21]
	v_mfma_f32_16x16x32_bf16 v[6:9], v[190:193], v[230:233], v[6:9]
	v_mfma_f32_16x16x32_bf16 v[2:5], v[198:201], v[230:233], v[2:5]
	s_setprio 0
	s_add_i32 s20, s20, 2
	s_add_u32 s36, s36, 0x100
	s_addc_u32 s37, s37, 0
	s_add_u32 s13, s13, 0x100
	s_addc_u32 s19, s19, 0
	s_cmp_gt_u32 s20, 29
.LBB0_358:
	s_add_u32 s21, s36, 0xfff80080
	s_addc_u32 s23, s37, -1
	s_add_i32 s26, 0, 0x10000
	s_cmp_eq_u32 s20, 28
	s_cselect_b32 s45, s8, s23
	s_cselect_b32 s44, s9, s21
	v_add_u32_e32 v153, s26, v179
	s_cselect_b32 s43, s5, s19
	s_cselect_b32 s42, s11, s13
	s_add_i32 s21, 0, 0x14000
	ds_read_b128 v[130:133], v153
	ds_read_b128 v[134:137], v153 offset:1024
	ds_read_b128 v[164:167], v153 offset:2048
	ds_read_b128 v[182:185], v153 offset:3072
	v_add_u32_e32 v153, s21, v179
	ds_read_b128 v[186:189], v153
	ds_read_b128 v[190:193], v153 offset:1024
	ds_read_b128 v[194:197], v153 offset:2048
	ds_read_b128 v[198:201], v153 offset:3072
	v_lshl_add_u64 v[168:169], s[36:37], 0, v[148:149]
	s_add_i32 m0, s27, 0xc000
	ds_read_b128 v[202:205], v181
	ds_read_b128 v[206:209], v181 offset:1024
	ds_read_b128 v[210:213], v181 offset:2048
	ds_read_b128 v[214:217], v181 offset:3072
	ds_read_b128 v[218:221], v181 offset:4096
	ds_read_b128 v[222:225], v181 offset:5120
	ds_read_b128 v[226:229], v181 offset:6144
	ds_read_b128 v[230:233], v181 offset:7168
	global_load_lds_dwordx4 v[168:169], off
	v_lshl_add_u64 v[168:169], s[36:37], 0, v[150:151]
	s_add_i32 m0, s27, 0xe000
	s_nop 0
	global_load_lds_dwordx4 v[168:169], off
	s_waitcnt vmcnt(8)
	s_waitcnt lgkmcnt(0)
	s_barrier
	s_setprio 1
	s_waitcnt lgkmcnt(0)
	v_mfma_f32_16x16x32_bf16 v[126:129], v[130:133], v[202:205], v[126:129]
	v_mfma_f32_16x16x32_bf16 v[122:125], v[164:167], v[202:205], v[122:125]
	v_mfma_f32_16x16x32_bf16 v[110:113], v[130:133], v[210:213], v[110:113]
	v_mfma_f32_16x16x32_bf16 v[106:109], v[164:167], v[210:213], v[106:109]
	v_mfma_f32_16x16x32_bf16 v[94:97], v[130:133], v[218:221], v[94:97]
	v_mfma_f32_16x16x32_bf16 v[90:93], v[164:167], v[218:221], v[90:93]
	v_mfma_f32_16x16x32_bf16 v[78:81], v[130:133], v[226:229], v[78:81]
	v_mfma_f32_16x16x32_bf16 v[74:77], v[164:167], v[226:229], v[74:77]
	v_mfma_f32_16x16x32_bf16 v[126:129], v[134:137], v[206:209], v[126:129]
	v_mfma_f32_16x16x32_bf16 v[122:125], v[182:185], v[206:209], v[122:125]
	v_mfma_f32_16x16x32_bf16 v[110:113], v[134:137], v[214:217], v[110:113]
	v_mfma_f32_16x16x32_bf16 v[106:109], v[182:185], v[214:217], v[106:109]
	v_mfma_f32_16x16x32_bf16 v[94:97], v[134:137], v[222:225], v[94:97]
	v_mfma_f32_16x16x32_bf16 v[90:93], v[182:185], v[222:225], v[90:93]
	v_mfma_f32_16x16x32_bf16 v[78:81], v[134:137], v[230:233], v[78:81]
	v_mfma_f32_16x16x32_bf16 v[74:77], v[182:185], v[230:233], v[74:77]
	s_setprio 0
	s_setprio 1
	v_mfma_f32_16x16x32_bf16 v[118:121], v[186:189], v[202:205], v[118:121]
	v_mfma_f32_16x16x32_bf16 v[114:117], v[194:197], v[202:205], v[114:117]
	v_mfma_f32_16x16x32_bf16 v[102:105], v[186:189], v[210:213], v[102:105]
	v_mfma_f32_16x16x32_bf16 v[98:101], v[194:197], v[210:213], v[98:101]
	v_mfma_f32_16x16x32_bf16 v[86:89], v[186:189], v[218:221], v[86:89]
	v_mfma_f32_16x16x32_bf16 v[82:85], v[194:197], v[218:221], v[82:85]
	v_mfma_f32_16x16x32_bf16 v[70:73], v[186:189], v[226:229], v[70:73]
	v_mfma_f32_16x16x32_bf16 v[66:69], v[194:197], v[226:229], v[66:69]
	v_mfma_f32_16x16x32_bf16 v[118:121], v[190:193], v[206:209], v[118:121]
	v_mfma_f32_16x16x32_bf16 v[114:117], v[198:201], v[206:209], v[114:117]
	v_mfma_f32_16x16x32_bf16 v[102:105], v[190:193], v[214:217], v[102:105]
	v_mfma_f32_16x16x32_bf16 v[98:101], v[198:201], v[214:217], v[98:101]
	s_setprio 2
	s_barrier
	v_mfma_f32_16x16x32_bf16 v[86:89], v[190:193], v[222:225], v[86:89]
	v_mfma_f32_16x16x32_bf16 v[82:85], v[198:201], v[222:225], v[82:85]
	v_mfma_f32_16x16x32_bf16 v[70:73], v[190:193], v[230:233], v[70:73]
	v_mfma_f32_16x16x32_bf16 v[66:69], v[198:201], v[230:233], v[66:69]
	s_setprio 0
	s_add_i32 s23, s26, s25
	v_lshl_add_u64 v[168:169], s[42:43], 0, v[162:163]
	s_mov_b32 m0, s23
	ds_read_b128 v[202:205], v181 offset:16384
	ds_read_b128 v[206:209], v181 offset:17408
	ds_read_b128 v[210:213], v181 offset:18432
	ds_read_b128 v[214:217], v181 offset:19456
	ds_read_b128 v[218:221], v181 offset:20480
	ds_read_b128 v[222:225], v181 offset:21504
	ds_read_b128 v[226:229], v181 offset:22528
	ds_read_b128 v[230:233], v181 offset:23552
	global_load_lds_dwordx4 v[168:169], off
	s_add_i32 m0, s23, 0x2000
	s_add_u32 s52, s42, 0x80000
	v_lshl_add_u64 v[234:235], s[42:43], 0, v[142:143]
	s_addc_u32 s53, s43, 0
	s_add_i32 s21, s21, s25
	global_load_lds_dwordx4 v[234:235], off
	v_lshl_add_u64 v[236:237], s[52:53], 0, v[162:163]
	s_mov_b32 m0, s21
	v_lshl_add_u64 v[238:239], s[44:45], 0, v[140:141]
	global_load_lds_dwordx4 v[236:237], off
	v_lshl_add_u64 v[236:237], s[52:53], 0, v[142:143]
	s_add_i32 m0, s21, 0x2000
	s_nop 0
	global_load_lds_dwordx4 v[236:237], off
	v_lshl_add_u64 v[236:237], s[44:45], 0, v[138:139]
	s_mov_b32 m0, s27
	s_nop 0
	global_load_lds_dwordx4 v[236:237], off
	s_mov_b32 m0, s46
	s_nop 0
	global_load_lds_dwordx4 v[238:239], off
	s_waitcnt vmcnt(8)
	s_waitcnt lgkmcnt(0)
	s_barrier
	s_setprio 1
	s_waitcnt lgkmcnt(0)
	v_mfma_f32_16x16x32_bf16 v[62:65], v[130:133], v[202:205], v[62:65]
	v_mfma_f32_16x16x32_bf16 v[58:61], v[164:167], v[202:205], v[58:61]
	v_mfma_f32_16x16x32_bf16 v[46:49], v[130:133], v[210:213], v[46:49]
	v_mfma_f32_16x16x32_bf16 v[42:45], v[164:167], v[210:213], v[42:45]
	v_mfma_f32_16x16x32_bf16 v[30:33], v[130:133], v[218:221], v[30:33]
	v_mfma_f32_16x16x32_bf16 v[26:29], v[164:167], v[218:221], v[26:29]
	v_mfma_f32_16x16x32_bf16 v[14:17], v[130:133], v[226:229], v[14:17]
	v_mfma_f32_16x16x32_bf16 v[10:13], v[164:167], v[226:229], v[10:13]
	v_mfma_f32_16x16x32_bf16 v[62:65], v[134:137], v[206:209], v[62:65]
	v_mfma_f32_16x16x32_bf16 v[58:61], v[182:185], v[206:209], v[58:61]
	v_mfma_f32_16x16x32_bf16 v[46:49], v[134:137], v[214:217], v[46:49]
	v_mfma_f32_16x16x32_bf16 v[42:45], v[182:185], v[214:217], v[42:45]
	v_mfma_f32_16x16x32_bf16 v[30:33], v[134:137], v[222:225], v[30:33]
	v_mfma_f32_16x16x32_bf16 v[26:29], v[182:185], v[222:225], v[26:29]
	v_mfma_f32_16x16x32_bf16 v[14:17], v[134:137], v[230:233], v[14:17]
	v_mfma_f32_16x16x32_bf16 v[10:13], v[182:185], v[230:233], v[10:13]
	s_setprio 0
	s_setprio 1
	v_mfma_f32_16x16x32_bf16 v[54:57], v[186:189], v[202:205], v[54:57]
	v_mfma_f32_16x16x32_bf16 v[50:53], v[194:197], v[202:205], v[50:53]
	v_mfma_f32_16x16x32_bf16 v[38:41], v[186:189], v[210:213], v[38:41]
	v_mfma_f32_16x16x32_bf16 v[34:37], v[194:197], v[210:213], v[34:37]
	v_mfma_f32_16x16x32_bf16 v[22:25], v[186:189], v[218:221], v[22:25]
	v_mfma_f32_16x16x32_bf16 v[18:21], v[194:197], v[218:221], v[18:21]
	v_mfma_f32_16x16x32_bf16 v[6:9], v[186:189], v[226:229], v[6:9]
	v_mfma_f32_16x16x32_bf16 v[2:5], v[194:197], v[226:229], v[2:5]
	v_mfma_f32_16x16x32_bf16 v[54:57], v[190:193], v[206:209], v[54:57]
	v_mfma_f32_16x16x32_bf16 v[50:53], v[198:201], v[206:209], v[50:53]
	v_mfma_f32_16x16x32_bf16 v[38:41], v[190:193], v[214:217], v[38:41]
	v_mfma_f32_16x16x32_bf16 v[34:37], v[198:201], v[214:217], v[34:37]
	s_setprio 2
	s_barrier
	v_mfma_f32_16x16x32_bf16 v[22:25], v[190:193], v[222:225], v[22:25]
	v_mfma_f32_16x16x32_bf16 v[18:21], v[198:201], v[222:225], v[18:21]
	v_mfma_f32_16x16x32_bf16 v[6:9], v[190:193], v[230:233], v[6:9]
	v_mfma_f32_16x16x32_bf16 v[2:5], v[198:201], v[230:233], v[2:5]
	s_setprio 0
	s_add_i32 s21, 0, 0x18000
	v_add_u32_e32 v153, s21, v179
	s_add_i32 s23, 0, 0x1c000
	ds_read_b128 v[130:133], v153
	ds_read_b128 v[134:137], v153 offset:1024
	ds_read_b128 v[164:167], v153 offset:2048
	ds_read_b128 v[182:185], v153 offset:3072
	v_add_u32_e32 v153, s23, v179
	ds_read_b128 v[186:189], v153
	ds_read_b128 v[190:193], v153 offset:1024
	ds_read_b128 v[194:197], v153 offset:2048
	ds_read_b128 v[198:201], v153 offset:3072
	s_add_u32 s44, s44, 0x80000
	s_addc_u32 s45, s45, 0
	s_mov_b32 m0, s47
	v_lshl_add_u64 v[240:241], s[44:45], 0, v[138:139]
	ds_read_b128 v[202:205], v181 offset:32768
	ds_read_b128 v[206:209], v181 offset:33792
	ds_read_b128 v[210:213], v181 offset:34816
	ds_read_b128 v[214:217], v181 offset:35840
	ds_read_b128 v[218:221], v181 offset:36864
	ds_read_b128 v[222:225], v181 offset:37888
	ds_read_b128 v[226:229], v181 offset:38912
	ds_read_b128 v[230:233], v181 offset:39936
	global_load_lds_dwordx4 v[240:241], off
	v_lshl_add_u64 v[240:241], s[44:45], 0, v[140:141]
	s_mov_b32 m0, s48
	s_nop 0
	global_load_lds_dwordx4 v[240:241], off
	s_waitcnt vmcnt(8)
	s_waitcnt lgkmcnt(0)
	s_barrier
	s_setprio 1
	s_waitcnt lgkmcnt(0)
	v_mfma_f32_16x16x32_bf16 v[126:129], v[130:133], v[202:205], v[126:129]
	v_mfma_f32_16x16x32_bf16 v[122:125], v[164:167], v[202:205], v[122:125]
	v_mfma_f32_16x16x32_bf16 v[110:113], v[130:133], v[210:213], v[110:113]
	v_mfma_f32_16x16x32_bf16 v[106:109], v[164:167], v[210:213], v[106:109]
	v_mfma_f32_16x16x32_bf16 v[94:97], v[130:133], v[218:221], v[94:97]
	v_mfma_f32_16x16x32_bf16 v[90:93], v[164:167], v[218:221], v[90:93]
	v_mfma_f32_16x16x32_bf16 v[78:81], v[130:133], v[226:229], v[78:81]
	v_mfma_f32_16x16x32_bf16 v[74:77], v[164:167], v[226:229], v[74:77]
	v_mfma_f32_16x16x32_bf16 v[126:129], v[134:137], v[206:209], v[126:129]
	v_mfma_f32_16x16x32_bf16 v[122:125], v[182:185], v[206:209], v[122:125]
	v_mfma_f32_16x16x32_bf16 v[110:113], v[134:137], v[214:217], v[110:113]
	v_mfma_f32_16x16x32_bf16 v[106:109], v[182:185], v[214:217], v[106:109]
	v_mfma_f32_16x16x32_bf16 v[94:97], v[134:137], v[222:225], v[94:97]
	v_mfma_f32_16x16x32_bf16 v[90:93], v[182:185], v[222:225], v[90:93]
	v_mfma_f32_16x16x32_bf16 v[78:81], v[134:137], v[230:233], v[78:81]
	v_mfma_f32_16x16x32_bf16 v[74:77], v[182:185], v[230:233], v[74:77]
	s_setprio 0
	s_setprio 1
	v_mfma_f32_16x16x32_bf16 v[118:121], v[186:189], v[202:205], v[118:121]
	v_mfma_f32_16x16x32_bf16 v[114:117], v[194:197], v[202:205], v[114:117]
	v_mfma_f32_16x16x32_bf16 v[102:105], v[186:189], v[210:213], v[102:105]
	v_mfma_f32_16x16x32_bf16 v[98:101], v[194:197], v[210:213], v[98:101]
	v_mfma_f32_16x16x32_bf16 v[86:89], v[186:189], v[218:221], v[86:89]
	v_mfma_f32_16x16x32_bf16 v[82:85], v[194:197], v[218:221], v[82:85]
	v_mfma_f32_16x16x32_bf16 v[70:73], v[186:189], v[226:229], v[70:73]
	v_mfma_f32_16x16x32_bf16 v[66:69], v[194:197], v[226:229], v[66:69]
	v_mfma_f32_16x16x32_bf16 v[118:121], v[190:193], v[206:209], v[118:121]
	v_mfma_f32_16x16x32_bf16 v[114:117], v[198:201], v[206:209], v[114:117]
	v_mfma_f32_16x16x32_bf16 v[102:105], v[190:193], v[214:217], v[102:105]
	v_mfma_f32_16x16x32_bf16 v[98:101], v[198:201], v[214:217], v[98:101]
	s_setprio 2
	s_barrier
	v_mfma_f32_16x16x32_bf16 v[86:89], v[190:193], v[222:225], v[86:89]
	v_mfma_f32_16x16x32_bf16 v[82:85], v[198:201], v[222:225], v[82:85]
	v_mfma_f32_16x16x32_bf16 v[70:73], v[190:193], v[230:233], v[70:73]
	v_mfma_f32_16x16x32_bf16 v[66:69], v[198:201], v[230:233], v[66:69]
	s_setprio 0
	s_add_i32 s21, s21, s25
	v_lshl_add_u64 v[168:169], v[168:169], 0, s[6:7]
	s_mov_b32 m0, s21
	ds_read_b128 v[202:205], v181 offset:49152
	ds_read_b128 v[206:209], v181 offset:50176
	ds_read_b128 v[210:213], v181 offset:51200
	ds_read_b128 v[214:217], v181 offset:52224
	ds_read_b128 v[218:221], v181 offset:53248
	ds_read_b128 v[222:225], v181 offset:54272
	ds_read_b128 v[226:229], v181 offset:55296
	ds_read_b128 v[230:233], v181 offset:56320
	global_load_lds_dwordx4 v[168:169], off
	s_add_i32 m0, s21, 0x2000
	s_add_u32 s42, s42, 0x80080
	v_lshl_add_u64 v[168:169], v[234:235], 0, s[6:7]
	s_addc_u32 s43, s43, 0
	s_add_i32 s21, s23, s25
	global_load_lds_dwordx4 v[168:169], off
	v_lshl_add_u64 v[168:169], s[42:43], 0, v[162:163]
	s_mov_b32 m0, s21
	s_nop 0
	global_load_lds_dwordx4 v[168:169], off
	v_lshl_add_u64 v[168:169], s[42:43], 0, v[142:143]
	s_add_i32 m0, s21, 0x2000
	s_nop 0
	global_load_lds_dwordx4 v[168:169], off
	v_lshl_add_u64 v[168:169], v[236:237], 0, s[6:7]
	s_mov_b32 m0, s49
	s_nop 0
	global_load_lds_dwordx4 v[168:169], off
	v_lshl_add_u64 v[168:169], v[238:239], 0, s[6:7]
	s_mov_b32 m0, s50
	s_nop 0
	global_load_lds_dwordx4 v[168:169], off
	s_waitcnt vmcnt(8)
	s_waitcnt lgkmcnt(0)
	s_barrier
	s_setprio 1
	s_waitcnt lgkmcnt(0)
	v_mfma_f32_16x16x32_bf16 v[62:65], v[130:133], v[202:205], v[62:65]
	v_mfma_f32_16x16x32_bf16 v[58:61], v[164:167], v[202:205], v[58:61]
	v_mfma_f32_16x16x32_bf16 v[46:49], v[130:133], v[210:213], v[46:49]
	v_mfma_f32_16x16x32_bf16 v[42:45], v[164:167], v[210:213], v[42:45]
	v_mfma_f32_16x16x32_bf16 v[30:33], v[130:133], v[218:221], v[30:33]
	v_mfma_f32_16x16x32_bf16 v[26:29], v[164:167], v[218:221], v[26:29]
	v_mfma_f32_16x16x32_bf16 v[14:17], v[130:133], v[226:229], v[14:17]
	v_mfma_f32_16x16x32_bf16 v[10:13], v[164:167], v[226:229], v[10:13]
	v_mfma_f32_16x16x32_bf16 v[62:65], v[134:137], v[206:209], v[62:65]
	v_mfma_f32_16x16x32_bf16 v[58:61], v[182:185], v[206:209], v[58:61]
	v_mfma_f32_16x16x32_bf16 v[46:49], v[134:137], v[214:217], v[46:49]
	v_mfma_f32_16x16x32_bf16 v[42:45], v[182:185], v[214:217], v[42:45]
	v_mfma_f32_16x16x32_bf16 v[30:33], v[134:137], v[222:225], v[30:33]
	v_mfma_f32_16x16x32_bf16 v[26:29], v[182:185], v[222:225], v[26:29]
	v_mfma_f32_16x16x32_bf16 v[14:17], v[134:137], v[230:233], v[14:17]
	v_mfma_f32_16x16x32_bf16 v[10:13], v[182:185], v[230:233], v[10:13]
	s_setprio 0
	s_setprio 1
	v_mfma_f32_16x16x32_bf16 v[54:57], v[186:189], v[202:205], v[54:57]
	v_mfma_f32_16x16x32_bf16 v[50:53], v[194:197], v[202:205], v[50:53]
	v_mfma_f32_16x16x32_bf16 v[38:41], v[186:189], v[210:213], v[38:41]
	v_mfma_f32_16x16x32_bf16 v[34:37], v[194:197], v[210:213], v[34:37]
	v_mfma_f32_16x16x32_bf16 v[22:25], v[186:189], v[218:221], v[22:25]
	v_mfma_f32_16x16x32_bf16 v[18:21], v[194:197], v[218:221], v[18:21]
	v_mfma_f32_16x16x32_bf16 v[6:9], v[186:189], v[226:229], v[6:9]
	v_mfma_f32_16x16x32_bf16 v[2:5], v[194:197], v[226:229], v[2:5]
	v_mfma_f32_16x16x32_bf16 v[54:57], v[190:193], v[206:209], v[54:57]
	v_mfma_f32_16x16x32_bf16 v[50:53], v[198:201], v[206:209], v[50:53]
	v_mfma_f32_16x16x32_bf16 v[38:41], v[190:193], v[214:217], v[38:41]
	v_mfma_f32_16x16x32_bf16 v[34:37], v[198:201], v[214:217], v[34:37]
	s_setprio 2
	s_barrier
	v_mfma_f32_16x16x32_bf16 v[22:25], v[190:193], v[222:225], v[22:25]
	v_mfma_f32_16x16x32_bf16 v[18:21], v[198:201], v[222:225], v[18:21]
	v_mfma_f32_16x16x32_bf16 v[6:9], v[190:193], v[230:233], v[6:9]
	v_mfma_f32_16x16x32_bf16 v[2:5], v[198:201], v[230:233], v[2:5]
	s_setprio 0
	s_add_i32 s20, s20, 2
	s_add_u32 s36, s36, 0x100
	s_addc_u32 s37, s37, 0
	s_add_u32 s13, s13, 0x100
	s_addc_u32 s19, s19, 0
	s_cmp_gt_u32 s20, 29
	s_cbranch_scc0 .LBB0_358
	s_and_b64 vcc, exec, s[2:3]
	s_cbranch_vccz .LBB0_361
	s_barrier

.LBB0_1114:
	s_ashr_i32 s19, s18, 31
	s_lshl_b64 s[28:29], s[18:19], 20
	v_readlane_b32 s5, v245, 28
	s_add_u32 s28, s5, s28
	v_readlane_b32 s5, v245, 29
	s_addc_u32 s29, s5, s29
	s_and_b64 s[34:35], s[22:23], exec
	s_cselect_b32 s8, s29, s37
	s_cselect_b32 s19, s28, s36
	s_ashr_i32 s5, s4, 31
	s_lshl_b64 s[34:35], s[4:5], 20
	s_add_u32 s34, s11, s34
	s_addc_u32 s35, s13, s35
	s_and_b64 s[44:45], s[22:23], exec
	s_cselect_b32 s5, s35, s43
	s_cselect_b32 s21, s34, s42
	s_add_u32 s36, s36, 0x80080
	s_addc_u32 s37, s37, 0
	s_add_u32 s41, s42, 0x100
	s_addc_u32 s48, s43, 0
	s_mov_b32 s49, -2
	s_waitcnt vmcnt(0) lgkmcnt(0)
	s_add_u32 s42, s36, 0xfff80080
	s_addc_u32 s43, s37, -1
	s_add_i32 s50, 0, 0x10000
	s_cmp_eq_u32 s49, 28
	s_cselect_b32 s45, s8, s43
	s_cselect_b32 s44, s19, s42
	v_add_u32_e32 v154, s50, v145
	s_cselect_b32 s43, s5, s48
	s_cselect_b32 s42, s21, s41
	s_add_i32 s52, 0, 0x14000
	ds_read_b128 v[130:133], v154
	ds_read_b128 v[134:137], v154 offset:1024
	ds_read_b128 v[150:153], v154 offset:2048
	ds_read_b128 v[158:161], v154 offset:3072
	v_add_u32_e32 v154, s52, v145
	ds_read_b128 v[164:167], v154
	ds_read_b128 v[180:183], v154 offset:1024
	ds_read_b128 v[184:187], v154 offset:2048
	ds_read_b128 v[188:191], v154 offset:3072
	v_lshl_add_u64 v[154:155], s[36:37], 0, v[146:147]
	s_add_i32 m0, s20, 0xc000
	ds_read_b128 v[192:195], v157
	ds_read_b128 v[196:199], v157 offset:1024
	ds_read_b128 v[200:203], v157 offset:2048
	ds_read_b128 v[204:207], v157 offset:3072
	ds_read_b128 v[208:211], v157 offset:4096
	ds_read_b128 v[212:215], v157 offset:5120
	ds_read_b128 v[216:219], v157 offset:6144
	ds_read_b128 v[220:223], v157 offset:7168
	global_load_lds_dwordx4 v[154:155], off
	v_lshl_add_u64 v[154:155], s[36:37], 0, v[148:149]
	s_add_i32 m0, s20, 0xe000
	s_nop 0
	global_load_lds_dwordx4 v[154:155], off
	s_waitcnt vmcnt(8)
	s_waitcnt lgkmcnt(0)
	s_barrier
	s_setprio 1
	s_waitcnt lgkmcnt(0)
	v_mfma_f32_16x16x32_bf16 v[126:129], v[130:133], v[192:195], 0
	v_mfma_f32_16x16x32_bf16 v[122:125], v[150:153], v[192:195], 0
	v_mfma_f32_16x16x32_bf16 v[110:113], v[130:133], v[200:203], 0
	v_mfma_f32_16x16x32_bf16 v[106:109], v[150:153], v[200:203], 0
	v_mfma_f32_16x16x32_bf16 v[94:97], v[130:133], v[208:211], 0
	v_mfma_f32_16x16x32_bf16 v[90:93], v[150:153], v[208:211], 0
	v_mfma_f32_16x16x32_bf16 v[78:81], v[130:133], v[216:219], 0
	v_mfma_f32_16x16x32_bf16 v[74:77], v[150:153], v[216:219], 0
	v_mfma_f32_16x16x32_bf16 v[126:129], v[134:137], v[196:199], v[126:129]
	v_mfma_f32_16x16x32_bf16 v[122:125], v[158:161], v[196:199], v[122:125]
	v_mfma_f32_16x16x32_bf16 v[110:113], v[134:137], v[204:207], v[110:113]
	v_mfma_f32_16x16x32_bf16 v[106:109], v[158:161], v[204:207], v[106:109]
	v_mfma_f32_16x16x32_bf16 v[94:97], v[134:137], v[212:215], v[94:97]
	v_mfma_f32_16x16x32_bf16 v[90:93], v[158:161], v[212:215], v[90:93]
	v_mfma_f32_16x16x32_bf16 v[78:81], v[134:137], v[220:223], v[78:81]
	v_mfma_f32_16x16x32_bf16 v[74:77], v[158:161], v[220:223], v[74:77]
	s_setprio 0
	s_setprio 1
	v_mfma_f32_16x16x32_bf16 v[118:121], v[164:167], v[192:195], 0
	v_mfma_f32_16x16x32_bf16 v[114:117], v[184:187], v[192:195], 0
	v_mfma_f32_16x16x32_bf16 v[102:105], v[164:167], v[200:203], 0
	v_mfma_f32_16x16x32_bf16 v[98:101], v[184:187], v[200:203], 0
	v_mfma_f32_16x16x32_bf16 v[86:89], v[164:167], v[208:211], 0
	v_mfma_f32_16x16x32_bf16 v[82:85], v[184:187], v[208:211], 0
	v_mfma_f32_16x16x32_bf16 v[70:73], v[164:167], v[216:219], 0
	v_mfma_f32_16x16x32_bf16 v[66:69], v[184:187], v[216:219], 0
	v_mfma_f32_16x16x32_bf16 v[118:121], v[180:183], v[196:199], v[118:121]
	v_mfma_f32_16x16x32_bf16 v[114:117], v[188:191], v[196:199], v[114:117]
	v_mfma_f32_16x16x32_bf16 v[102:105], v[180:183], v[204:207], v[102:105]
	v_mfma_f32_16x16x32_bf16 v[98:101], v[188:191], v[204:207], v[98:101]
	s_setprio 2
	s_barrier
	v_mfma_f32_16x16x32_bf16 v[86:89], v[180:183], v[212:215], v[86:89]
	v_mfma_f32_16x16x32_bf16 v[82:85], v[188:191], v[212:215], v[82:85]
	v_mfma_f32_16x16x32_bf16 v[70:73], v[180:183], v[220:223], v[70:73]
	v_mfma_f32_16x16x32_bf16 v[66:69], v[188:191], v[220:223], v[66:69]
	s_setprio 0
	s_add_i32 s50, s50, s9
	v_lshl_add_u64 v[154:155], s[42:43], 0, v[162:163]
	s_mov_b32 m0, s50
	ds_read_b128 v[192:195], v157 offset:16384
	ds_read_b128 v[196:199], v157 offset:17408
	ds_read_b128 v[200:203], v157 offset:18432
	ds_read_b128 v[204:207], v157 offset:19456
	ds_read_b128 v[208:211], v157 offset:20480
	ds_read_b128 v[212:215], v157 offset:21504
	ds_read_b128 v[216:219], v157 offset:22528
	ds_read_b128 v[220:223], v157 offset:23552
	global_load_lds_dwordx4 v[154:155], off
	s_add_i32 m0, s50, 0x2000
	s_add_u32 s50, s42, 0x80000
	v_lshl_add_u64 v[168:169], s[42:43], 0, v[142:143]
	s_addc_u32 s51, s43, 0
	s_add_i32 s52, s52, s9
	global_load_lds_dwordx4 v[168:169], off
	v_lshl_add_u64 v[224:225], s[50:51], 0, v[162:163]
	s_mov_b32 m0, s52
	v_lshl_add_u64 v[226:227], s[44:45], 0, v[140:141]
	global_load_lds_dwordx4 v[224:225], off
	v_lshl_add_u64 v[224:225], s[50:51], 0, v[142:143]
	s_add_i32 m0, s52, 0x2000
	s_nop 0
	global_load_lds_dwordx4 v[224:225], off
	v_lshl_add_u64 v[224:225], s[44:45], 0, v[138:139]
	s_mov_b32 m0, s20
	s_nop 0
	global_load_lds_dwordx4 v[224:225], off
	s_mov_b32 m0, s25
	s_nop 0
	global_load_lds_dwordx4 v[226:227], off
	s_waitcnt vmcnt(8)
	s_waitcnt lgkmcnt(0)
	s_barrier
	s_setprio 1
	s_waitcnt lgkmcnt(0)
	v_mfma_f32_16x16x32_bf16 v[62:65], v[130:133], v[192:195], 0
	v_mfma_f32_16x16x32_bf16 v[58:61], v[150:153], v[192:195], 0
	v_mfma_f32_16x16x32_bf16 v[46:49], v[130:133], v[200:203], 0
	v_mfma_f32_16x16x32_bf16 v[42:45], v[150:153], v[200:203], 0
	v_mfma_f32_16x16x32_bf16 v[30:33], v[130:133], v[208:211], 0
	v_mfma_f32_16x16x32_bf16 v[26:29], v[150:153], v[208:211], 0
	v_mfma_f32_16x16x32_bf16 v[14:17], v[130:133], v[216:219], 0
	v_mfma_f32_16x16x32_bf16 v[10:13], v[150:153], v[216:219], 0
	v_mfma_f32_16x16x32_bf16 v[62:65], v[134:137], v[196:199], v[62:65]
	v_mfma_f32_16x16x32_bf16 v[58:61], v[158:161], v[196:199], v[58:61]
	v_mfma_f32_16x16x32_bf16 v[46:49], v[134:137], v[204:207], v[46:49]
	v_mfma_f32_16x16x32_bf16 v[42:45], v[158:161], v[204:207], v[42:45]
	v_mfma_f32_16x16x32_bf16 v[30:33], v[134:137], v[212:215], v[30:33]
	v_mfma_f32_16x16x32_bf16 v[26:29], v[158:161], v[212:215], v[26:29]
	v_mfma_f32_16x16x32_bf16 v[14:17], v[134:137], v[220:223], v[14:17]
	v_mfma_f32_16x16x32_bf16 v[10:13], v[158:161], v[220:223], v[10:13]
	s_setprio 0
	s_setprio 1
	v_mfma_f32_16x16x32_bf16 v[54:57], v[164:167], v[192:195], 0
	v_mfma_f32_16x16x32_bf16 v[50:53], v[184:187], v[192:195], 0
	v_mfma_f32_16x16x32_bf16 v[38:41], v[164:167], v[200:203], 0
	v_mfma_f32_16x16x32_bf16 v[34:37], v[184:187], v[200:203], 0
	v_mfma_f32_16x16x32_bf16 v[22:25], v[164:167], v[208:211], 0
	v_mfma_f32_16x16x32_bf16 v[18:21], v[184:187], v[208:211], 0
	v_mfma_f32_16x16x32_bf16 v[6:9], v[164:167], v[216:219], 0
	v_mfma_f32_16x16x32_bf16 v[2:5], v[184:187], v[216:219], 0
	v_mfma_f32_16x16x32_bf16 v[54:57], v[180:183], v[196:199], v[54:57]
	v_mfma_f32_16x16x32_bf16 v[50:53], v[188:191], v[196:199], v[50:53]
	v_mfma_f32_16x16x32_bf16 v[38:41], v[180:183], v[204:207], v[38:41]
	v_mfma_f32_16x16x32_bf16 v[34:37], v[188:191], v[204:207], v[34:37]
	s_setprio 2
	s_barrier
	v_mfma_f32_16x16x32_bf16 v[22:25], v[180:183], v[212:215], v[22:25]
	v_mfma_f32_16x16x32_bf16 v[18:21], v[188:191], v[212:215], v[18:21]
	v_mfma_f32_16x16x32_bf16 v[6:9], v[180:183], v[220:223], v[6:9]
	v_mfma_f32_16x16x32_bf16 v[2:5], v[188:191], v[220:223], v[2:5]
	s_setprio 0
	s_add_i32 s50, 0, 0x18000
	s_add_i32 s51, 0, 0x1c000
	v_add_u32_e32 v158, s50, v145
	v_add_u32_e32 v179, s51, v145
	ds_read_b128 v[130:133], v158
	ds_read_b128 v[134:137], v158 offset:1024
	ds_read_b128 v[150:153], v158 offset:2048
	ds_read_b128 v[158:161], v158 offset:3072
	ds_read_b128 v[164:167], v179
	ds_read_b128 v[180:183], v179 offset:1024
	ds_read_b128 v[184:187], v179 offset:2048
	ds_read_b128 v[188:191], v179 offset:3072
	s_add_u32 s44, s44, 0x80000
	s_addc_u32 s45, s45, 0
	s_mov_b32 m0, s26
	v_lshl_add_u64 v[228:229], s[44:45], 0, v[138:139]
	ds_read_b128 v[192:195], v157 offset:32768
	ds_read_b128 v[196:199], v157 offset:33792
	ds_read_b128 v[200:203], v157 offset:34816
	ds_read_b128 v[204:207], v157 offset:35840
	ds_read_b128 v[208:211], v157 offset:36864
	ds_read_b128 v[212:215], v157 offset:37888
	ds_read_b128 v[216:219], v157 offset:38912
	ds_read_b128 v[220:223], v157 offset:39936
	global_load_lds_dwordx4 v[228:229], off
	v_lshl_add_u64 v[228:229], s[44:45], 0, v[140:141]
	s_mov_b32 m0, s27
	s_nop 0
	global_load_lds_dwordx4 v[228:229], off
	s_waitcnt vmcnt(8)
	s_waitcnt lgkmcnt(0)
	s_barrier
	s_setprio 1
	s_waitcnt lgkmcnt(0)
	v_mfma_f32_16x16x32_bf16 v[126:129], v[130:133], v[192:195], v[126:129]
	v_mfma_f32_16x16x32_bf16 v[122:125], v[150:153], v[192:195], v[122:125]
	v_mfma_f32_16x16x32_bf16 v[110:113], v[130:133], v[200:203], v[110:113]
	v_mfma_f32_16x16x32_bf16 v[106:109], v[150:153], v[200:203], v[106:109]
	v_mfma_f32_16x16x32_bf16 v[94:97], v[130:133], v[208:211], v[94:97]
	v_mfma_f32_16x16x32_bf16 v[90:93], v[150:153], v[208:211], v[90:93]
	v_mfma_f32_16x16x32_bf16 v[78:81], v[130:133], v[216:219], v[78:81]
	v_mfma_f32_16x16x32_bf16 v[74:77], v[150:153], v[216:219], v[74:77]
	v_mfma_f32_16x16x32_bf16 v[126:129], v[134:137], v[196:199], v[126:129]
	v_mfma_f32_16x16x32_bf16 v[122:125], v[158:161], v[196:199], v[122:125]
	v_mfma_f32_16x16x32_bf16 v[110:113], v[134:137], v[204:207], v[110:113]
	v_mfma_f32_16x16x32_bf16 v[106:109], v[158:161], v[204:207], v[106:109]
	v_mfma_f32_16x16x32_bf16 v[94:97], v[134:137], v[212:215], v[94:97]
	v_mfma_f32_16x16x32_bf16 v[90:93], v[158:161], v[212:215], v[90:93]
	v_mfma_f32_16x16x32_bf16 v[78:81], v[134:137], v[220:223], v[78:81]
	v_mfma_f32_16x16x32_bf16 v[74:77], v[158:161], v[220:223], v[74:77]
	s_setprio 0
	s_setprio 1
	v_mfma_f32_16x16x32_bf16 v[118:121], v[164:167], v[192:195], v[118:121]
	v_mfma_f32_16x16x32_bf16 v[114:117], v[184:187], v[192:195], v[114:117]
	v_mfma_f32_16x16x32_bf16 v[102:105], v[164:167], v[200:203], v[102:105]
	v_mfma_f32_16x16x32_bf16 v[98:101], v[184:187], v[200:203], v[98:101]
	v_mfma_f32_16x16x32_bf16 v[86:89], v[164:167], v[208:211], v[86:89]
	v_mfma_f32_16x16x32_bf16 v[82:85], v[184:187], v[208:211], v[82:85]
	v_mfma_f32_16x16x32_bf16 v[70:73], v[164:167], v[216:219], v[70:73]
	v_mfma_f32_16x16x32_bf16 v[66:69], v[184:187], v[216:219], v[66:69]
	v_mfma_f32_16x16x32_bf16 v[118:121], v[180:183], v[196:199], v[118:121]
	v_mfma_f32_16x16x32_bf16 v[114:117], v[188:191], v[196:199], v[114:117]
	v_mfma_f32_16x16x32_bf16 v[102:105], v[180:183], v[204:207], v[102:105]
	v_mfma_f32_16x16x32_bf16 v[98:101], v[188:191], v[204:207], v[98:101]
	s_setprio 2
	s_barrier
	v_mfma_f32_16x16x32_bf16 v[86:89], v[180:183], v[212:215], v[86:89]
	v_mfma_f32_16x16x32_bf16 v[82:85], v[188:191], v[212:215], v[82:85]
	v_mfma_f32_16x16x32_bf16 v[70:73], v[180:183], v[220:223], v[70:73]
	v_mfma_f32_16x16x32_bf16 v[66:69], v[188:191], v[220:223], v[66:69]
	s_setprio 0
	s_add_i32 s44, s50, s9
	v_lshl_add_u64 v[154:155], v[154:155], 0, s[6:7]
	s_mov_b32 m0, s44
	ds_read_b128 v[192:195], v157 offset:49152
	ds_read_b128 v[196:199], v157 offset:50176
	ds_read_b128 v[200:203], v157 offset:51200
	ds_read_b128 v[204:207], v157 offset:52224
	ds_read_b128 v[208:211], v157 offset:53248
	ds_read_b128 v[212:215], v157 offset:54272
	ds_read_b128 v[216:219], v157 offset:55296
	ds_read_b128 v[220:223], v157 offset:56320
	global_load_lds_dwordx4 v[154:155], off
	s_add_i32 m0, s44, 0x2000
	s_add_u32 s42, s42, 0x80080
	v_lshl_add_u64 v[154:155], v[168:169], 0, s[6:7]
	s_addc_u32 s43, s43, 0
	s_add_i32 s44, s51, s9
	global_load_lds_dwordx4 v[154:155], off
	v_lshl_add_u64 v[154:155], s[42:43], 0, v[162:163]
	s_mov_b32 m0, s44
	s_nop 0
	global_load_lds_dwordx4 v[154:155], off
	v_lshl_add_u64 v[154:155], s[42:43], 0, v[142:143]
	s_add_i32 m0, s44, 0x2000
	s_nop 0
	global_load_lds_dwordx4 v[154:155], off
	v_lshl_add_u64 v[154:155], v[224:225], 0, s[6:7]
	s_mov_b32 m0, s39
	s_nop 0
	global_load_lds_dwordx4 v[154:155], off
	v_lshl_add_u64 v[154:155], v[226:227], 0, s[6:7]
	s_mov_b32 m0, s46
	s_nop 0
	global_load_lds_dwordx4 v[154:155], off
	s_waitcnt vmcnt(8)
	s_waitcnt lgkmcnt(0)
	s_barrier
	s_setprio 1
	s_waitcnt lgkmcnt(0)
	v_mfma_f32_16x16x32_bf16 v[62:65], v[130:133], v[192:195], v[62:65]
	v_mfma_f32_16x16x32_bf16 v[58:61], v[150:153], v[192:195], v[58:61]
	v_mfma_f32_16x16x32_bf16 v[46:49], v[130:133], v[200:203], v[46:49]
	v_mfma_f32_16x16x32_bf16 v[42:45], v[150:153], v[200:203], v[42:45]
	v_mfma_f32_16x16x32_bf16 v[30:33], v[130:133], v[208:211], v[30:33]
	v_mfma_f32_16x16x32_bf16 v[26:29], v[150:153], v[208:211], v[26:29]
	v_mfma_f32_16x16x32_bf16 v[14:17], v[130:133], v[216:219], v[14:17]
	v_mfma_f32_16x16x32_bf16 v[10:13], v[150:153], v[216:219], v[10:13]
	v_mfma_f32_16x16x32_bf16 v[62:65], v[134:137], v[196:199], v[62:65]
	v_mfma_f32_16x16x32_bf16 v[58:61], v[158:161], v[196:199], v[58:61]
	v_mfma_f32_16x16x32_bf16 v[46:49], v[134:137], v[204:207], v[46:49]
	v_mfma_f32_16x16x32_bf16 v[42:45], v[158:161], v[204:207], v[42:45]
	v_mfma_f32_16x16x32_bf16 v[30:33], v[134:137], v[212:215], v[30:33]
	v_mfma_f32_16x16x32_bf16 v[26:29], v[158:161], v[212:215], v[26:29]
	v_mfma_f32_16x16x32_bf16 v[14:17], v[134:137], v[220:223], v[14:17]
	v_mfma_f32_16x16x32_bf16 v[10:13], v[158:161], v[220:223], v[10:13]
	s_setprio 0
	s_setprio 1
	v_mfma_f32_16x16x32_bf16 v[54:57], v[164:167], v[192:195], v[54:57]
	v_mfma_f32_16x16x32_bf16 v[50:53], v[184:187], v[192:195], v[50:53]
	v_mfma_f32_16x16x32_bf16 v[38:41], v[164:167], v[200:203], v[38:41]
	v_mfma_f32_16x16x32_bf16 v[34:37], v[184:187], v[200:203], v[34:37]
	v_mfma_f32_16x16x32_bf16 v[22:25], v[164:167], v[208:211], v[22:25]
	v_mfma_f32_16x16x32_bf16 v[18:21], v[184:187], v[208:211], v[18:21]
	v_mfma_f32_16x16x32_bf16 v[6:9], v[164:167], v[216:219], v[6:9]
	v_mfma_f32_16x16x32_bf16 v[2:5], v[184:187], v[216:219], v[2:5]
	v_mfma_f32_16x16x32_bf16 v[54:57], v[180:183], v[196:199], v[54:57]
	v_mfma_f32_16x16x32_bf16 v[50:53], v[188:191], v[196:199], v[50:53]
	v_mfma_f32_16x16x32_bf16 v[38:41], v[180:183], v[204:207], v[38:41]
	v_mfma_f32_16x16x32_bf16 v[34:37], v[188:191], v[204:207], v[34:37]
	s_setprio 2
	s_barrier
	v_mfma_f32_16x16x32_bf16 v[22:25], v[180:183], v[212:215], v[22:25]
	v_mfma_f32_16x16x32_bf16 v[18:21], v[188:191], v[212:215], v[18:21]
	v_mfma_f32_16x16x32_bf16 v[6:9], v[180:183], v[220:223], v[6:9]
	v_mfma_f32_16x16x32_bf16 v[2:5], v[188:191], v[220:223], v[2:5]
	s_setprio 0
	s_add_i32 s49, s49, 2
	s_add_u32 s36, s36, 0x100
	s_addc_u32 s37, s37, 0
	s_add_u32 s41, s41, 0x100
	s_addc_u32 s48, s48, 0
	s_cmp_gt_u32 s49, 29
.LBB0_1115:
	s_add_u32 s42, s36, 0xfff80080
	s_addc_u32 s43, s37, -1
	s_add_i32 s50, 0, 0x10000
	s_cmp_eq_u32 s49, 28
	s_cselect_b32 s45, s8, s43
	s_cselect_b32 s44, s19, s42
	v_add_u32_e32 v154, s50, v145
	s_cselect_b32 s43, s5, s48
	s_cselect_b32 s42, s21, s41
	s_add_i32 s52, 0, 0x14000
	ds_read_b128 v[130:133], v154
	ds_read_b128 v[134:137], v154 offset:1024
	ds_read_b128 v[150:153], v154 offset:2048
	ds_read_b128 v[158:161], v154 offset:3072
	v_add_u32_e32 v154, s52, v145
	ds_read_b128 v[164:167], v154
	ds_read_b128 v[180:183], v154 offset:1024
	ds_read_b128 v[184:187], v154 offset:2048
	ds_read_b128 v[188:191], v154 offset:3072
	v_lshl_add_u64 v[154:155], s[36:37], 0, v[146:147]
	s_add_i32 m0, s20, 0xc000
	ds_read_b128 v[192:195], v157
	ds_read_b128 v[196:199], v157 offset:1024
	ds_read_b128 v[200:203], v157 offset:2048
	ds_read_b128 v[204:207], v157 offset:3072
	ds_read_b128 v[208:211], v157 offset:4096
	ds_read_b128 v[212:215], v157 offset:5120
	ds_read_b128 v[216:219], v157 offset:6144
	ds_read_b128 v[220:223], v157 offset:7168
	global_load_lds_dwordx4 v[154:155], off
	v_lshl_add_u64 v[154:155], s[36:37], 0, v[148:149]
	s_add_i32 m0, s20, 0xe000
	s_nop 0
	global_load_lds_dwordx4 v[154:155], off
	s_waitcnt vmcnt(8)
	s_waitcnt lgkmcnt(0)
	s_barrier
	s_setprio 1
	s_waitcnt lgkmcnt(0)
	v_mfma_f32_16x16x32_bf16 v[126:129], v[130:133], v[192:195], v[126:129]
	v_mfma_f32_16x16x32_bf16 v[122:125], v[150:153], v[192:195], v[122:125]
	v_mfma_f32_16x16x32_bf16 v[110:113], v[130:133], v[200:203], v[110:113]
	v_mfma_f32_16x16x32_bf16 v[106:109], v[150:153], v[200:203], v[106:109]
	v_mfma_f32_16x16x32_bf16 v[94:97], v[130:133], v[208:211], v[94:97]
	v_mfma_f32_16x16x32_bf16 v[90:93], v[150:153], v[208:211], v[90:93]
	v_mfma_f32_16x16x32_bf16 v[78:81], v[130:133], v[216:219], v[78:81]
	v_mfma_f32_16x16x32_bf16 v[74:77], v[150:153], v[216:219], v[74:77]
	v_mfma_f32_16x16x32_bf16 v[126:129], v[134:137], v[196:199], v[126:129]
	v_mfma_f32_16x16x32_bf16 v[122:125], v[158:161], v[196:199], v[122:125]
	v_mfma_f32_16x16x32_bf16 v[110:113], v[134:137], v[204:207], v[110:113]
	v_mfma_f32_16x16x32_bf16 v[106:109], v[158:161], v[204:207], v[106:109]
	v_mfma_f32_16x16x32_bf16 v[94:97], v[134:137], v[212:215], v[94:97]
	v_mfma_f32_16x16x32_bf16 v[90:93], v[158:161], v[212:215], v[90:93]
	v_mfma_f32_16x16x32_bf16 v[78:81], v[134:137], v[220:223], v[78:81]
	v_mfma_f32_16x16x32_bf16 v[74:77], v[158:161], v[220:223], v[74:77]
	s_setprio 0
	s_setprio 1
	v_mfma_f32_16x16x32_bf16 v[118:121], v[164:167], v[192:195], v[118:121]
	v_mfma_f32_16x16x32_bf16 v[114:117], v[184:187], v[192:195], v[114:117]
	v_mfma_f32_16x16x32_bf16 v[102:105], v[164:167], v[200:203], v[102:105]
	v_mfma_f32_16x16x32_bf16 v[98:101], v[184:187], v[200:203], v[98:101]
	v_mfma_f32_16x16x32_bf16 v[86:89], v[164:167], v[208:211], v[86:89]
	v_mfma_f32_16x16x32_bf16 v[82:85], v[184:187], v[208:211], v[82:85]
	v_mfma_f32_16x16x32_bf16 v[70:73], v[164:167], v[216:219], v[70:73]
	v_mfma_f32_16x16x32_bf16 v[66:69], v[184:187], v[216:219], v[66:69]
	v_mfma_f32_16x16x32_bf16 v[118:121], v[180:183], v[196:199], v[118:121]
	v_mfma_f32_16x16x32_bf16 v[114:117], v[188:191], v[196:199], v[114:117]
	v_mfma_f32_16x16x32_bf16 v[102:105], v[180:183], v[204:207], v[102:105]
	v_mfma_f32_16x16x32_bf16 v[98:101], v[188:191], v[204:207], v[98:101]
	s_setprio 2
	s_barrier
	v_mfma_f32_16x16x32_bf16 v[86:89], v[180:183], v[212:215], v[86:89]
	v_mfma_f32_16x16x32_bf16 v[82:85], v[188:191], v[212:215], v[82:85]
	v_mfma_f32_16x16x32_bf16 v[70:73], v[180:183], v[220:223], v[70:73]
	v_mfma_f32_16x16x32_bf16 v[66:69], v[188:191], v[220:223], v[66:69]
	s_setprio 0
	s_add_i32 s50, s50, s9
	v_lshl_add_u64 v[154:155], s[42:43], 0, v[162:163]
	s_mov_b32 m0, s50
	ds_read_b128 v[192:195], v157 offset:16384
	ds_read_b128 v[196:199], v157 offset:17408
	ds_read_b128 v[200:203], v157 offset:18432
	ds_read_b128 v[204:207], v157 offset:19456
	ds_read_b128 v[208:211], v157 offset:20480
	ds_read_b128 v[212:215], v157 offset:21504
	ds_read_b128 v[216:219], v157 offset:22528
	ds_read_b128 v[220:223], v157 offset:23552
	global_load_lds_dwordx4 v[154:155], off
	s_add_i32 m0, s50, 0x2000
	s_add_u32 s50, s42, 0x80000
	v_lshl_add_u64 v[168:169], s[42:43], 0, v[142:143]
	s_addc_u32 s51, s43, 0
	s_add_i32 s52, s52, s9
	global_load_lds_dwordx4 v[168:169], off
	v_lshl_add_u64 v[224:225], s[50:51], 0, v[162:163]
	s_mov_b32 m0, s52
	v_lshl_add_u64 v[226:227], s[44:45], 0, v[140:141]
	global_load_lds_dwordx4 v[224:225], off
	v_lshl_add_u64 v[224:225], s[50:51], 0, v[142:143]
	s_add_i32 m0, s52, 0x2000
	s_nop 0
	global_load_lds_dwordx4 v[224:225], off
	v_lshl_add_u64 v[224:225], s[44:45], 0, v[138:139]
	s_mov_b32 m0, s20
	s_nop 0
	global_load_lds_dwordx4 v[224:225], off
	s_mov_b32 m0, s25
	s_nop 0
	global_load_lds_dwordx4 v[226:227], off
	s_waitcnt vmcnt(8)
	s_waitcnt lgkmcnt(0)
	s_barrier
	s_setprio 1
	s_waitcnt lgkmcnt(0)
	v_mfma_f32_16x16x32_bf16 v[62:65], v[130:133], v[192:195], v[62:65]
	v_mfma_f32_16x16x32_bf16 v[58:61], v[150:153], v[192:195], v[58:61]
	v_mfma_f32_16x16x32_bf16 v[46:49], v[130:133], v[200:203], v[46:49]
	v_mfma_f32_16x16x32_bf16 v[42:45], v[150:153], v[200:203], v[42:45]
	v_mfma_f32_16x16x32_bf16 v[30:33], v[130:133], v[208:211], v[30:33]
	v_mfma_f32_16x16x32_bf16 v[26:29], v[150:153], v[208:211], v[26:29]
	v_mfma_f32_16x16x32_bf16 v[14:17], v[130:133], v[216:219], v[14:17]
	v_mfma_f32_16x16x32_bf16 v[10:13], v[150:153], v[216:219], v[10:13]
	v_mfma_f32_16x16x32_bf16 v[62:65], v[134:137], v[196:199], v[62:65]
	v_mfma_f32_16x16x32_bf16 v[58:61], v[158:161], v[196:199], v[58:61]
	v_mfma_f32_16x16x32_bf16 v[46:49], v[134:137], v[204:207], v[46:49]
	v_mfma_f32_16x16x32_bf16 v[42:45], v[158:161], v[204:207], v[42:45]
	v_mfma_f32_16x16x32_bf16 v[30:33], v[134:137], v[212:215], v[30:33]
	v_mfma_f32_16x16x32_bf16 v[26:29], v[158:161], v[212:215], v[26:29]
	v_mfma_f32_16x16x32_bf16 v[14:17], v[134:137], v[220:223], v[14:17]
	v_mfma_f32_16x16x32_bf16 v[10:13], v[158:161], v[220:223], v[10:13]
	s_setprio 0
	s_setprio 1
	v_mfma_f32_16x16x32_bf16 v[54:57], v[164:167], v[192:195], v[54:57]
	v_mfma_f32_16x16x32_bf16 v[50:53], v[184:187], v[192:195], v[50:53]
	v_mfma_f32_16x16x32_bf16 v[38:41], v[164:167], v[200:203], v[38:41]
	v_mfma_f32_16x16x32_bf16 v[34:37], v[184:187], v[200:203], v[34:37]
	v_mfma_f32_16x16x32_bf16 v[22:25], v[164:167], v[208:211], v[22:25]
	v_mfma_f32_16x16x32_bf16 v[18:21], v[184:187], v[208:211], v[18:21]
	v_mfma_f32_16x16x32_bf16 v[6:9], v[164:167], v[216:219], v[6:9]
	v_mfma_f32_16x16x32_bf16 v[2:5], v[184:187], v[216:219], v[2:5]
	v_mfma_f32_16x16x32_bf16 v[54:57], v[180:183], v[196:199], v[54:57]
	v_mfma_f32_16x16x32_bf16 v[50:53], v[188:191], v[196:199], v[50:53]
	v_mfma_f32_16x16x32_bf16 v[38:41], v[180:183], v[204:207], v[38:41]
	v_mfma_f32_16x16x32_bf16 v[34:37], v[188:191], v[204:207], v[34:37]
	s_setprio 2
	s_barrier
	v_mfma_f32_16x16x32_bf16 v[22:25], v[180:183], v[212:215], v[22:25]
	v_mfma_f32_16x16x32_bf16 v[18:21], v[188:191], v[212:215], v[18:21]
	v_mfma_f32_16x16x32_bf16 v[6:9], v[180:183], v[220:223], v[6:9]
	v_mfma_f32_16x16x32_bf16 v[2:5], v[188:191], v[220:223], v[2:5]
	s_setprio 0
	s_add_i32 s50, 0, 0x18000
	s_add_i32 s51, 0, 0x1c000
	v_add_u32_e32 v158, s50, v145
	v_add_u32_e32 v179, s51, v145
	ds_read_b128 v[130:133], v158
	ds_read_b128 v[134:137], v158 offset:1024
	ds_read_b128 v[150:153], v158 offset:2048
	ds_read_b128 v[158:161], v158 offset:3072
	ds_read_b128 v[164:167], v179
	ds_read_b128 v[180:183], v179 offset:1024
	ds_read_b128 v[184:187], v179 offset:2048
	ds_read_b128 v[188:191], v179 offset:3072
	s_add_u32 s44, s44, 0x80000
	s_addc_u32 s45, s45, 0
	s_mov_b32 m0, s26
	v_lshl_add_u64 v[228:229], s[44:45], 0, v[138:139]
	ds_read_b128 v[192:195], v157 offset:32768
	ds_read_b128 v[196:199], v157 offset:33792
	ds_read_b128 v[200:203], v157 offset:34816
	ds_read_b128 v[204:207], v157 offset:35840
	ds_read_b128 v[208:211], v157 offset:36864
	ds_read_b128 v[212:215], v157 offset:37888
	ds_read_b128 v[216:219], v157 offset:38912
	ds_read_b128 v[220:223], v157 offset:39936
	global_load_lds_dwordx4 v[228:229], off
	v_lshl_add_u64 v[228:229], s[44:45], 0, v[140:141]
	s_mov_b32 m0, s27
	s_nop 0
	global_load_lds_dwordx4 v[228:229], off
	s_waitcnt vmcnt(8)
	s_waitcnt lgkmcnt(0)
	s_barrier
	s_setprio 1
	s_waitcnt lgkmcnt(0)
	v_mfma_f32_16x16x32_bf16 v[126:129], v[130:133], v[192:195], v[126:129]
	v_mfma_f32_16x16x32_bf16 v[122:125], v[150:153], v[192:195], v[122:125]
	v_mfma_f32_16x16x32_bf16 v[110:113], v[130:133], v[200:203], v[110:113]
	v_mfma_f32_16x16x32_bf16 v[106:109], v[150:153], v[200:203], v[106:109]
	v_mfma_f32_16x16x32_bf16 v[94:97], v[130:133], v[208:211], v[94:97]
	v_mfma_f32_16x16x32_bf16 v[90:93], v[150:153], v[208:211], v[90:93]
	v_mfma_f32_16x16x32_bf16 v[78:81], v[130:133], v[216:219], v[78:81]
	v_mfma_f32_16x16x32_bf16 v[74:77], v[150:153], v[216:219], v[74:77]
	v_mfma_f32_16x16x32_bf16 v[126:129], v[134:137], v[196:199], v[126:129]
	v_mfma_f32_16x16x32_bf16 v[122:125], v[158:161], v[196:199], v[122:125]
	v_mfma_f32_16x16x32_bf16 v[110:113], v[134:137], v[204:207], v[110:113]
	v_mfma_f32_16x16x32_bf16 v[106:109], v[158:161], v[204:207], v[106:109]
	v_mfma_f32_16x16x32_bf16 v[94:97], v[134:137], v[212:215], v[94:97]
	v_mfma_f32_16x16x32_bf16 v[90:93], v[158:161], v[212:215], v[90:93]
	v_mfma_f32_16x16x32_bf16 v[78:81], v[134:137], v[220:223], v[78:81]
	v_mfma_f32_16x16x32_bf16 v[74:77], v[158:161], v[220:223], v[74:77]
	s_setprio 0
	s_setprio 1
	v_mfma_f32_16x16x32_bf16 v[118:121], v[164:167], v[192:195], v[118:121]
	v_mfma_f32_16x16x32_bf16 v[114:117], v[184:187], v[192:195], v[114:117]
	v_mfma_f32_16x16x32_bf16 v[102:105], v[164:167], v[200:203], v[102:105]
	v_mfma_f32_16x16x32_bf16 v[98:101], v[184:187], v[200:203], v[98:101]
	v_mfma_f32_16x16x32_bf16 v[86:89], v[164:167], v[208:211], v[86:89]
	v_mfma_f32_16x16x32_bf16 v[82:85], v[184:187], v[208:211], v[82:85]
	v_mfma_f32_16x16x32_bf16 v[70:73], v[164:167], v[216:219], v[70:73]
	v_mfma_f32_16x16x32_bf16 v[66:69], v[184:187], v[216:219], v[66:69]
	v_mfma_f32_16x16x32_bf16 v[118:121], v[180:183], v[196:199], v[118:121]
	v_mfma_f32_16x16x32_bf16 v[114:117], v[188:191], v[196:199], v[114:117]
	v_mfma_f32_16x16x32_bf16 v[102:105], v[180:183], v[204:207], v[102:105]
	v_mfma_f32_16x16x32_bf16 v[98:101], v[188:191], v[204:207], v[98:101]
	s_setprio 2
	s_barrier
	v_mfma_f32_16x16x32_bf16 v[86:89], v[180:183], v[212:215], v[86:89]
	v_mfma_f32_16x16x32_bf16 v[82:85], v[188:191], v[212:215], v[82:85]
	v_mfma_f32_16x16x32_bf16 v[70:73], v[180:183], v[220:223], v[70:73]
	v_mfma_f32_16x16x32_bf16 v[66:69], v[188:191], v[220:223], v[66:69]
	s_setprio 0
	s_add_i32 s44, s50, s9
	v_lshl_add_u64 v[154:155], v[154:155], 0, s[6:7]
	s_mov_b32 m0, s44
	ds_read_b128 v[192:195], v157 offset:49152
	ds_read_b128 v[196:199], v157 offset:50176
	ds_read_b128 v[200:203], v157 offset:51200
	ds_read_b128 v[204:207], v157 offset:52224
	ds_read_b128 v[208:211], v157 offset:53248
	ds_read_b128 v[212:215], v157 offset:54272
	ds_read_b128 v[216:219], v157 offset:55296
	ds_read_b128 v[220:223], v157 offset:56320
	global_load_lds_dwordx4 v[154:155], off
	s_add_i32 m0, s44, 0x2000
	s_add_u32 s42, s42, 0x80080
	v_lshl_add_u64 v[154:155], v[168:169], 0, s[6:7]
	s_addc_u32 s43, s43, 0
	s_add_i32 s44, s51, s9
	global_load_lds_dwordx4 v[154:155], off
	v_lshl_add_u64 v[154:155], s[42:43], 0, v[162:163]
	s_mov_b32 m0, s44
	s_nop 0
	global_load_lds_dwordx4 v[154:155], off
	v_lshl_add_u64 v[154:155], s[42:43], 0, v[142:143]
	s_add_i32 m0, s44, 0x2000
	s_nop 0
	global_load_lds_dwordx4 v[154:155], off
	v_lshl_add_u64 v[154:155], v[224:225], 0, s[6:7]
	s_mov_b32 m0, s39
	s_nop 0
	global_load_lds_dwordx4 v[154:155], off
	v_lshl_add_u64 v[154:155], v[226:227], 0, s[6:7]
	s_mov_b32 m0, s46
	s_nop 0
	global_load_lds_dwordx4 v[154:155], off
	s_waitcnt vmcnt(8)
	s_waitcnt lgkmcnt(0)
	s_barrier
	s_setprio 1
	s_waitcnt lgkmcnt(0)
	v_mfma_f32_16x16x32_bf16 v[62:65], v[130:133], v[192:195], v[62:65]
	v_mfma_f32_16x16x32_bf16 v[58:61], v[150:153], v[192:195], v[58:61]
	v_mfma_f32_16x16x32_bf16 v[46:49], v[130:133], v[200:203], v[46:49]
	v_mfma_f32_16x16x32_bf16 v[42:45], v[150:153], v[200:203], v[42:45]
	v_mfma_f32_16x16x32_bf16 v[30:33], v[130:133], v[208:211], v[30:33]
	v_mfma_f32_16x16x32_bf16 v[26:29], v[150:153], v[208:211], v[26:29]
	v_mfma_f32_16x16x32_bf16 v[14:17], v[130:133], v[216:219], v[14:17]
	v_mfma_f32_16x16x32_bf16 v[10:13], v[150:153], v[216:219], v[10:13]
	v_mfma_f32_16x16x32_bf16 v[62:65], v[134:137], v[196:199], v[62:65]
	v_mfma_f32_16x16x32_bf16 v[58:61], v[158:161], v[196:199], v[58:61]
	v_mfma_f32_16x16x32_bf16 v[46:49], v[134:137], v[204:207], v[46:49]
	v_mfma_f32_16x16x32_bf16 v[42:45], v[158:161], v[204:207], v[42:45]
	v_mfma_f32_16x16x32_bf16 v[30:33], v[134:137], v[212:215], v[30:33]
	v_mfma_f32_16x16x32_bf16 v[26:29], v[158:161], v[212:215], v[26:29]
	v_mfma_f32_16x16x32_bf16 v[14:17], v[134:137], v[220:223], v[14:17]
	v_mfma_f32_16x16x32_bf16 v[10:13], v[158:161], v[220:223], v[10:13]
	s_setprio 0
	s_setprio 1
	v_mfma_f32_16x16x32_bf16 v[54:57], v[164:167], v[192:195], v[54:57]
	v_mfma_f32_16x16x32_bf16 v[50:53], v[184:187], v[192:195], v[50:53]
	v_mfma_f32_16x16x32_bf16 v[38:41], v[164:167], v[200:203], v[38:41]
	v_mfma_f32_16x16x32_bf16 v[34:37], v[184:187], v[200:203], v[34:37]
	v_mfma_f32_16x16x32_bf16 v[22:25], v[164:167], v[208:211], v[22:25]
	v_mfma_f32_16x16x32_bf16 v[18:21], v[184:187], v[208:211], v[18:21]
	v_mfma_f32_16x16x32_bf16 v[6:9], v[164:167], v[216:219], v[6:9]
	v_mfma_f32_16x16x32_bf16 v[2:5], v[184:187], v[216:219], v[2:5]
	v_mfma_f32_16x16x32_bf16 v[54:57], v[180:183], v[196:199], v[54:57]
	v_mfma_f32_16x16x32_bf16 v[50:53], v[188:191], v[196:199], v[50:53]
	v_mfma_f32_16x16x32_bf16 v[38:41], v[180:183], v[204:207], v[38:41]
	v_mfma_f32_16x16x32_bf16 v[34:37], v[188:191], v[204:207], v[34:37]
	s_setprio 2
	s_barrier
	v_mfma_f32_16x16x32_bf16 v[22:25], v[180:183], v[212:215], v[22:25]
	v_mfma_f32_16x16x32_bf16 v[18:21], v[188:191], v[212:215], v[18:21]
	v_mfma_f32_16x16x32_bf16 v[6:9], v[180:183], v[220:223], v[6:9]
	v_mfma_f32_16x16x32_bf16 v[2:5], v[188:191], v[220:223], v[2:5]
	s_setprio 0
	s_add_i32 s49, s49, 2
	s_add_u32 s36, s36, 0x100
	s_addc_u32 s37, s37, 0
	s_add_u32 s41, s41, 0x100
	s_addc_u32 s48, s48, 0
	s_cmp_gt_u32 s49, 29
	s_cbranch_scc0 .LBB0_1115
	s_and_b64 vcc, exec, s[2:3]
	s_cbranch_vccz .LBB0_1118
	s_barrier

.LBB0_1293:
	s_ashr_i32 s19, s18, 31
	s_lshl_b64 s[8:9], s[18:19], 20
	v_readlane_b32 s5, v243, 17
	s_add_u32 s28, s5, s8
	v_readlane_b32 s5, v243, 18
	s_addc_u32 s29, s5, s9
	s_and_b64 s[8:9], s[34:35], exec
	s_cselect_b32 s8, s29, s37
	s_cselect_b32 s9, s28, s36
	s_ashr_i32 s5, s4, 31
	s_lshl_b64 s[20:21], s[4:5], 20
	s_add_u32 s38, s25, s20
	s_addc_u32 s39, s27, s21
	s_and_b64 s[20:21], s[34:35], exec
	s_cselect_b32 s5, s39, s43
	s_cselect_b32 s11, s38, s42
	s_add_u32 s36, s36, 0x80080
	s_addc_u32 s37, s37, 0
	s_add_u32 s13, s42, 0x100
	s_addc_u32 s19, s43, 0
	s_mov_b32 s20, -2
	s_waitcnt vmcnt(0) lgkmcnt(0)
	s_add_u32 s21, s36, 0xfff80080
	s_addc_u32 s23, s37, -1
	s_add_i32 s26, 0, 0x10000
	s_cmp_eq_u32 s20, 28
	s_cselect_b32 s45, s8, s23
	s_cselect_b32 s44, s9, s21
	v_add_u32_e32 v153, s26, v147
	s_cselect_b32 s43, s5, s19
	s_cselect_b32 s42, s11, s13
	s_add_i32 s21, 0, 0x14000
	ds_read_b128 v[130:133], v153
	ds_read_b128 v[134:137], v153 offset:1024
	ds_read_b128 v[164:167], v153 offset:2048
	ds_read_b128 v[182:185], v153 offset:3072
	v_add_u32_e32 v153, s21, v147
	ds_read_b128 v[186:189], v153
	ds_read_b128 v[190:193], v153 offset:1024
	ds_read_b128 v[194:197], v153 offset:2048
	ds_read_b128 v[198:201], v153 offset:3072
	v_lshl_add_u64 v[168:169], s[36:37], 0, v[148:149]
	s_add_i32 m0, s47, 0xc000
	ds_read_b128 v[202:205], v180
	ds_read_b128 v[206:209], v180 offset:1024
	ds_read_b128 v[210:213], v180 offset:2048
	ds_read_b128 v[214:217], v180 offset:3072
	ds_read_b128 v[218:221], v180 offset:4096
	ds_read_b128 v[222:225], v180 offset:5120
	ds_read_b128 v[226:229], v180 offset:6144
	ds_read_b128 v[230:233], v180 offset:7168
	global_load_lds_dwordx4 v[168:169], off
	v_lshl_add_u64 v[168:169], s[36:37], 0, v[150:151]
	s_add_i32 m0, s47, 0xe000
	s_nop 0
	global_load_lds_dwordx4 v[168:169], off
	s_waitcnt vmcnt(8)
	s_waitcnt lgkmcnt(0)
	s_barrier
	s_setprio 1
	s_waitcnt lgkmcnt(0)
	v_mfma_f32_16x16x32_bf16 v[126:129], v[130:133], v[202:205], 0
	v_mfma_f32_16x16x32_bf16 v[122:125], v[164:167], v[202:205], 0
	v_mfma_f32_16x16x32_bf16 v[110:113], v[130:133], v[210:213], 0
	v_mfma_f32_16x16x32_bf16 v[106:109], v[164:167], v[210:213], 0
	v_mfma_f32_16x16x32_bf16 v[94:97], v[130:133], v[218:221], 0
	v_mfma_f32_16x16x32_bf16 v[90:93], v[164:167], v[218:221], 0
	v_mfma_f32_16x16x32_bf16 v[78:81], v[130:133], v[226:229], 0
	v_mfma_f32_16x16x32_bf16 v[74:77], v[164:167], v[226:229], 0
	v_mfma_f32_16x16x32_bf16 v[126:129], v[134:137], v[206:209], v[126:129]
	v_mfma_f32_16x16x32_bf16 v[122:125], v[182:185], v[206:209], v[122:125]
	v_mfma_f32_16x16x32_bf16 v[110:113], v[134:137], v[214:217], v[110:113]
	v_mfma_f32_16x16x32_bf16 v[106:109], v[182:185], v[214:217], v[106:109]
	v_mfma_f32_16x16x32_bf16 v[94:97], v[134:137], v[222:225], v[94:97]
	v_mfma_f32_16x16x32_bf16 v[90:93], v[182:185], v[222:225], v[90:93]
	v_mfma_f32_16x16x32_bf16 v[78:81], v[134:137], v[230:233], v[78:81]
	v_mfma_f32_16x16x32_bf16 v[74:77], v[182:185], v[230:233], v[74:77]
	s_setprio 0
	s_setprio 1
	v_mfma_f32_16x16x32_bf16 v[118:121], v[186:189], v[202:205], 0
	v_mfma_f32_16x16x32_bf16 v[114:117], v[194:197], v[202:205], 0
	v_mfma_f32_16x16x32_bf16 v[102:105], v[186:189], v[210:213], 0
	v_mfma_f32_16x16x32_bf16 v[98:101], v[194:197], v[210:213], 0
	v_mfma_f32_16x16x32_bf16 v[86:89], v[186:189], v[218:221], 0
	v_mfma_f32_16x16x32_bf16 v[82:85], v[194:197], v[218:221], 0
	v_mfma_f32_16x16x32_bf16 v[70:73], v[186:189], v[226:229], 0
	v_mfma_f32_16x16x32_bf16 v[66:69], v[194:197], v[226:229], 0
	v_mfma_f32_16x16x32_bf16 v[118:121], v[190:193], v[206:209], v[118:121]
	v_mfma_f32_16x16x32_bf16 v[114:117], v[198:201], v[206:209], v[114:117]
	v_mfma_f32_16x16x32_bf16 v[102:105], v[190:193], v[214:217], v[102:105]
	v_mfma_f32_16x16x32_bf16 v[98:101], v[198:201], v[214:217], v[98:101]
	s_setprio 2
	s_barrier
	v_mfma_f32_16x16x32_bf16 v[86:89], v[190:193], v[222:225], v[86:89]
	v_mfma_f32_16x16x32_bf16 v[82:85], v[198:201], v[222:225], v[82:85]
	v_mfma_f32_16x16x32_bf16 v[70:73], v[190:193], v[230:233], v[70:73]
	v_mfma_f32_16x16x32_bf16 v[66:69], v[198:201], v[230:233], v[66:69]
	s_setprio 0
	s_add_i32 s23, s26, s46
	v_lshl_add_u64 v[168:169], s[42:43], 0, v[162:163]
	s_mov_b32 m0, s23
	ds_read_b128 v[202:205], v180 offset:16384
	ds_read_b128 v[206:209], v180 offset:17408
	ds_read_b128 v[210:213], v180 offset:18432
	ds_read_b128 v[214:217], v180 offset:19456
	ds_read_b128 v[218:221], v180 offset:20480
	ds_read_b128 v[222:225], v180 offset:21504
	ds_read_b128 v[226:229], v180 offset:22528
	ds_read_b128 v[230:233], v180 offset:23552
	global_load_lds_dwordx4 v[168:169], off
	s_add_i32 m0, s23, 0x2000
	s_add_u32 s54, s42, 0x80000
	v_lshl_add_u64 v[234:235], s[42:43], 0, v[142:143]
	s_addc_u32 s55, s43, 0
	s_add_i32 s21, s21, s46
	global_load_lds_dwordx4 v[234:235], off
	v_lshl_add_u64 v[236:237], s[54:55], 0, v[162:163]
	s_mov_b32 m0, s21
	v_lshl_add_u64 v[238:239], s[44:45], 0, v[140:141]
	global_load_lds_dwordx4 v[236:237], off
	v_lshl_add_u64 v[236:237], s[54:55], 0, v[142:143]
	s_add_i32 m0, s21, 0x2000
	s_nop 0
	global_load_lds_dwordx4 v[236:237], off
	v_lshl_add_u64 v[236:237], s[44:45], 0, v[138:139]
	s_mov_b32 m0, s47
	s_nop 0
	global_load_lds_dwordx4 v[236:237], off
	s_mov_b32 m0, s48
	s_nop 0
	global_load_lds_dwordx4 v[238:239], off
	s_waitcnt vmcnt(8)
	s_waitcnt lgkmcnt(0)
	s_barrier
	s_setprio 1
	s_waitcnt lgkmcnt(0)
	v_mfma_f32_16x16x32_bf16 v[62:65], v[130:133], v[202:205], 0
	v_mfma_f32_16x16x32_bf16 v[58:61], v[164:167], v[202:205], 0
	v_mfma_f32_16x16x32_bf16 v[46:49], v[130:133], v[210:213], 0
	v_mfma_f32_16x16x32_bf16 v[42:45], v[164:167], v[210:213], 0
	v_mfma_f32_16x16x32_bf16 v[30:33], v[130:133], v[218:221], 0
	v_mfma_f32_16x16x32_bf16 v[26:29], v[164:167], v[218:221], 0
	v_mfma_f32_16x16x32_bf16 v[14:17], v[130:133], v[226:229], 0
	v_mfma_f32_16x16x32_bf16 v[10:13], v[164:167], v[226:229], 0
	v_mfma_f32_16x16x32_bf16 v[62:65], v[134:137], v[206:209], v[62:65]
	v_mfma_f32_16x16x32_bf16 v[58:61], v[182:185], v[206:209], v[58:61]
	v_mfma_f32_16x16x32_bf16 v[46:49], v[134:137], v[214:217], v[46:49]
	v_mfma_f32_16x16x32_bf16 v[42:45], v[182:185], v[214:217], v[42:45]
	v_mfma_f32_16x16x32_bf16 v[30:33], v[134:137], v[222:225], v[30:33]
	v_mfma_f32_16x16x32_bf16 v[26:29], v[182:185], v[222:225], v[26:29]
	v_mfma_f32_16x16x32_bf16 v[14:17], v[134:137], v[230:233], v[14:17]
	v_mfma_f32_16x16x32_bf16 v[10:13], v[182:185], v[230:233], v[10:13]
	s_setprio 0
	s_setprio 1
	v_mfma_f32_16x16x32_bf16 v[54:57], v[186:189], v[202:205], 0
	v_mfma_f32_16x16x32_bf16 v[50:53], v[194:197], v[202:205], 0
	v_mfma_f32_16x16x32_bf16 v[38:41], v[186:189], v[210:213], 0
	v_mfma_f32_16x16x32_bf16 v[34:37], v[194:197], v[210:213], 0
	v_mfma_f32_16x16x32_bf16 v[22:25], v[186:189], v[218:221], 0
	v_mfma_f32_16x16x32_bf16 v[18:21], v[194:197], v[218:221], 0
	v_mfma_f32_16x16x32_bf16 v[6:9], v[186:189], v[226:229], 0
	v_mfma_f32_16x16x32_bf16 v[2:5], v[194:197], v[226:229], 0
	v_mfma_f32_16x16x32_bf16 v[54:57], v[190:193], v[206:209], v[54:57]
	v_mfma_f32_16x16x32_bf16 v[50:53], v[198:201], v[206:209], v[50:53]
	v_mfma_f32_16x16x32_bf16 v[38:41], v[190:193], v[214:217], v[38:41]
	v_mfma_f32_16x16x32_bf16 v[34:37], v[198:201], v[214:217], v[34:37]
	s_setprio 2
	s_barrier
	v_mfma_f32_16x16x32_bf16 v[22:25], v[190:193], v[222:225], v[22:25]
	v_mfma_f32_16x16x32_bf16 v[18:21], v[198:201], v[222:225], v[18:21]
	v_mfma_f32_16x16x32_bf16 v[6:9], v[190:193], v[230:233], v[6:9]
	v_mfma_f32_16x16x32_bf16 v[2:5], v[198:201], v[230:233], v[2:5]
	s_setprio 0
	s_add_i32 s21, 0, 0x18000
	v_add_u32_e32 v153, s21, v147
	s_add_i32 s23, 0, 0x1c000
	ds_read_b128 v[130:133], v153
	ds_read_b128 v[134:137], v153 offset:1024
	ds_read_b128 v[164:167], v153 offset:2048
	ds_read_b128 v[182:185], v153 offset:3072
	v_add_u32_e32 v153, s23, v147
	ds_read_b128 v[186:189], v153
	ds_read_b128 v[190:193], v153 offset:1024
	ds_read_b128 v[194:197], v153 offset:2048
	ds_read_b128 v[198:201], v153 offset:3072
	s_add_u32 s44, s44, 0x80000
	s_addc_u32 s45, s45, 0
	s_mov_b32 m0, s49
	v_lshl_add_u64 v[240:241], s[44:45], 0, v[138:139]
	ds_read_b128 v[202:205], v180 offset:32768
	ds_read_b128 v[206:209], v180 offset:33792
	ds_read_b128 v[210:213], v180 offset:34816
	ds_read_b128 v[214:217], v180 offset:35840
	ds_read_b128 v[218:221], v180 offset:36864
	ds_read_b128 v[222:225], v180 offset:37888
	ds_read_b128 v[226:229], v180 offset:38912
	ds_read_b128 v[230:233], v180 offset:39936
	global_load_lds_dwordx4 v[240:241], off
	v_lshl_add_u64 v[240:241], s[44:45], 0, v[140:141]
	s_mov_b32 m0, s50
	s_nop 0
	global_load_lds_dwordx4 v[240:241], off
	s_waitcnt vmcnt(8)
	s_waitcnt lgkmcnt(0)
	s_barrier
	s_setprio 1
	s_waitcnt lgkmcnt(0)
	v_mfma_f32_16x16x32_bf16 v[126:129], v[130:133], v[202:205], v[126:129]
	v_mfma_f32_16x16x32_bf16 v[122:125], v[164:167], v[202:205], v[122:125]
	v_mfma_f32_16x16x32_bf16 v[110:113], v[130:133], v[210:213], v[110:113]
	v_mfma_f32_16x16x32_bf16 v[106:109], v[164:167], v[210:213], v[106:109]
	v_mfma_f32_16x16x32_bf16 v[94:97], v[130:133], v[218:221], v[94:97]
	v_mfma_f32_16x16x32_bf16 v[90:93], v[164:167], v[218:221], v[90:93]
	v_mfma_f32_16x16x32_bf16 v[78:81], v[130:133], v[226:229], v[78:81]
	v_mfma_f32_16x16x32_bf16 v[74:77], v[164:167], v[226:229], v[74:77]
	v_mfma_f32_16x16x32_bf16 v[126:129], v[134:137], v[206:209], v[126:129]
	v_mfma_f32_16x16x32_bf16 v[122:125], v[182:185], v[206:209], v[122:125]
	v_mfma_f32_16x16x32_bf16 v[110:113], v[134:137], v[214:217], v[110:113]
	v_mfma_f32_16x16x32_bf16 v[106:109], v[182:185], v[214:217], v[106:109]
	v_mfma_f32_16x16x32_bf16 v[94:97], v[134:137], v[222:225], v[94:97]
	v_mfma_f32_16x16x32_bf16 v[90:93], v[182:185], v[222:225], v[90:93]
	v_mfma_f32_16x16x32_bf16 v[78:81], v[134:137], v[230:233], v[78:81]
	v_mfma_f32_16x16x32_bf16 v[74:77], v[182:185], v[230:233], v[74:77]
	s_setprio 0
	s_setprio 1
	v_mfma_f32_16x16x32_bf16 v[118:121], v[186:189], v[202:205], v[118:121]
	v_mfma_f32_16x16x32_bf16 v[114:117], v[194:197], v[202:205], v[114:117]
	v_mfma_f32_16x16x32_bf16 v[102:105], v[186:189], v[210:213], v[102:105]
	v_mfma_f32_16x16x32_bf16 v[98:101], v[194:197], v[210:213], v[98:101]
	v_mfma_f32_16x16x32_bf16 v[86:89], v[186:189], v[218:221], v[86:89]
	v_mfma_f32_16x16x32_bf16 v[82:85], v[194:197], v[218:221], v[82:85]
	v_mfma_f32_16x16x32_bf16 v[70:73], v[186:189], v[226:229], v[70:73]
	v_mfma_f32_16x16x32_bf16 v[66:69], v[194:197], v[226:229], v[66:69]
	v_mfma_f32_16x16x32_bf16 v[118:121], v[190:193], v[206:209], v[118:121]
	v_mfma_f32_16x16x32_bf16 v[114:117], v[198:201], v[206:209], v[114:117]
	v_mfma_f32_16x16x32_bf16 v[102:105], v[190:193], v[214:217], v[102:105]
	v_mfma_f32_16x16x32_bf16 v[98:101], v[198:201], v[214:217], v[98:101]
	s_setprio 2
	s_barrier
	v_mfma_f32_16x16x32_bf16 v[86:89], v[190:193], v[222:225], v[86:89]
	v_mfma_f32_16x16x32_bf16 v[82:85], v[198:201], v[222:225], v[82:85]
	v_mfma_f32_16x16x32_bf16 v[70:73], v[190:193], v[230:233], v[70:73]
	v_mfma_f32_16x16x32_bf16 v[66:69], v[198:201], v[230:233], v[66:69]
	s_setprio 0
	s_add_i32 s21, s21, s46
	v_lshl_add_u64 v[168:169], v[168:169], 0, s[6:7]
	s_mov_b32 m0, s21
	ds_read_b128 v[202:205], v180 offset:49152
	ds_read_b128 v[206:209], v180 offset:50176
	ds_read_b128 v[210:213], v180 offset:51200
	ds_read_b128 v[214:217], v180 offset:52224
	ds_read_b128 v[218:221], v180 offset:53248
	ds_read_b128 v[222:225], v180 offset:54272
	ds_read_b128 v[226:229], v180 offset:55296
	ds_read_b128 v[230:233], v180 offset:56320
	global_load_lds_dwordx4 v[168:169], off
	s_add_i32 m0, s21, 0x2000
	s_add_u32 s42, s42, 0x80080
	v_lshl_add_u64 v[168:169], v[234:235], 0, s[6:7]
	s_addc_u32 s43, s43, 0
	s_add_i32 s21, s23, s46
	global_load_lds_dwordx4 v[168:169], off
	v_lshl_add_u64 v[168:169], s[42:43], 0, v[162:163]
	s_mov_b32 m0, s21
	s_nop 0
	global_load_lds_dwordx4 v[168:169], off
	v_lshl_add_u64 v[168:169], s[42:43], 0, v[142:143]
	s_add_i32 m0, s21, 0x2000
	s_nop 0
	global_load_lds_dwordx4 v[168:169], off
	v_lshl_add_u64 v[168:169], v[236:237], 0, s[6:7]
	s_mov_b32 m0, s51
	s_nop 0
	global_load_lds_dwordx4 v[168:169], off
	v_lshl_add_u64 v[168:169], v[238:239], 0, s[6:7]
	s_mov_b32 m0, s52
	s_nop 0
	global_load_lds_dwordx4 v[168:169], off
	s_waitcnt vmcnt(8)
	s_waitcnt lgkmcnt(0)
	s_barrier
	s_setprio 1
	s_waitcnt lgkmcnt(0)
	v_mfma_f32_16x16x32_bf16 v[62:65], v[130:133], v[202:205], v[62:65]
	v_mfma_f32_16x16x32_bf16 v[58:61], v[164:167], v[202:205], v[58:61]
	v_mfma_f32_16x16x32_bf16 v[46:49], v[130:133], v[210:213], v[46:49]
	v_mfma_f32_16x16x32_bf16 v[42:45], v[164:167], v[210:213], v[42:45]
	v_mfma_f32_16x16x32_bf16 v[30:33], v[130:133], v[218:221], v[30:33]
	v_mfma_f32_16x16x32_bf16 v[26:29], v[164:167], v[218:221], v[26:29]
	v_mfma_f32_16x16x32_bf16 v[14:17], v[130:133], v[226:229], v[14:17]
	v_mfma_f32_16x16x32_bf16 v[10:13], v[164:167], v[226:229], v[10:13]
	v_mfma_f32_16x16x32_bf16 v[62:65], v[134:137], v[206:209], v[62:65]
	v_mfma_f32_16x16x32_bf16 v[58:61], v[182:185], v[206:209], v[58:61]
	v_mfma_f32_16x16x32_bf16 v[46:49], v[134:137], v[214:217], v[46:49]
	v_mfma_f32_16x16x32_bf16 v[42:45], v[182:185], v[214:217], v[42:45]
	v_mfma_f32_16x16x32_bf16 v[30:33], v[134:137], v[222:225], v[30:33]
	v_mfma_f32_16x16x32_bf16 v[26:29], v[182:185], v[222:225], v[26:29]
	v_mfma_f32_16x16x32_bf16 v[14:17], v[134:137], v[230:233], v[14:17]
	v_mfma_f32_16x16x32_bf16 v[10:13], v[182:185], v[230:233], v[10:13]
	s_setprio 0
	s_setprio 1
	v_mfma_f32_16x16x32_bf16 v[54:57], v[186:189], v[202:205], v[54:57]
	v_mfma_f32_16x16x32_bf16 v[50:53], v[194:197], v[202:205], v[50:53]
	v_mfma_f32_16x16x32_bf16 v[38:41], v[186:189], v[210:213], v[38:41]
	v_mfma_f32_16x16x32_bf16 v[34:37], v[194:197], v[210:213], v[34:37]
	v_mfma_f32_16x16x32_bf16 v[22:25], v[186:189], v[218:221], v[22:25]
	v_mfma_f32_16x16x32_bf16 v[18:21], v[194:197], v[218:221], v[18:21]
	v_mfma_f32_16x16x32_bf16 v[6:9], v[186:189], v[226:229], v[6:9]
	v_mfma_f32_16x16x32_bf16 v[2:5], v[194:197], v[226:229], v[2:5]
	v_mfma_f32_16x16x32_bf16 v[54:57], v[190:193], v[206:209], v[54:57]
	v_mfma_f32_16x16x32_bf16 v[50:53], v[198:201], v[206:209], v[50:53]
	v_mfma_f32_16x16x32_bf16 v[38:41], v[190:193], v[214:217], v[38:41]
	v_mfma_f32_16x16x32_bf16 v[34:37], v[198:201], v[214:217], v[34:37]
	s_setprio 2
	s_barrier
	v_mfma_f32_16x16x32_bf16 v[22:25], v[190:193], v[222:225], v[22:25]
	v_mfma_f32_16x16x32_bf16 v[18:21], v[198:201], v[222:225], v[18:21]
	v_mfma_f32_16x16x32_bf16 v[6:9], v[190:193], v[230:233], v[6:9]
	v_mfma_f32_16x16x32_bf16 v[2:5], v[198:201], v[230:233], v[2:5]
	s_setprio 0
	s_add_i32 s20, s20, 2
	s_add_u32 s36, s36, 0x100
	s_addc_u32 s37, s37, 0
	s_add_u32 s13, s13, 0x100
	s_addc_u32 s19, s19, 0
	s_cmp_gt_u32 s20, 29
.LBB0_1294:
	s_add_u32 s21, s36, 0xfff80080
	s_addc_u32 s23, s37, -1
	s_add_i32 s26, 0, 0x10000
	s_cmp_eq_u32 s20, 28
	s_cselect_b32 s45, s8, s23
	s_cselect_b32 s44, s9, s21
	v_add_u32_e32 v153, s26, v147
	s_cselect_b32 s43, s5, s19
	s_cselect_b32 s42, s11, s13
	s_add_i32 s21, 0, 0x14000
	ds_read_b128 v[130:133], v153
	ds_read_b128 v[134:137], v153 offset:1024
	ds_read_b128 v[164:167], v153 offset:2048
	ds_read_b128 v[182:185], v153 offset:3072
	v_add_u32_e32 v153, s21, v147
	ds_read_b128 v[186:189], v153
	ds_read_b128 v[190:193], v153 offset:1024
	ds_read_b128 v[194:197], v153 offset:2048
	ds_read_b128 v[198:201], v153 offset:3072
	v_lshl_add_u64 v[168:169], s[36:37], 0, v[148:149]
	s_add_i32 m0, s47, 0xc000
	ds_read_b128 v[202:205], v180
	ds_read_b128 v[206:209], v180 offset:1024
	ds_read_b128 v[210:213], v180 offset:2048
	ds_read_b128 v[214:217], v180 offset:3072
	ds_read_b128 v[218:221], v180 offset:4096
	ds_read_b128 v[222:225], v180 offset:5120
	ds_read_b128 v[226:229], v180 offset:6144
	ds_read_b128 v[230:233], v180 offset:7168
	global_load_lds_dwordx4 v[168:169], off
	v_lshl_add_u64 v[168:169], s[36:37], 0, v[150:151]
	s_add_i32 m0, s47, 0xe000
	s_nop 0
	global_load_lds_dwordx4 v[168:169], off
	s_waitcnt vmcnt(8)
	s_waitcnt lgkmcnt(0)
	s_barrier
	s_setprio 1
	s_waitcnt lgkmcnt(0)
	v_mfma_f32_16x16x32_bf16 v[126:129], v[130:133], v[202:205], v[126:129]
	v_mfma_f32_16x16x32_bf16 v[122:125], v[164:167], v[202:205], v[122:125]
	v_mfma_f32_16x16x32_bf16 v[110:113], v[130:133], v[210:213], v[110:113]
	v_mfma_f32_16x16x32_bf16 v[106:109], v[164:167], v[210:213], v[106:109]
	v_mfma_f32_16x16x32_bf16 v[94:97], v[130:133], v[218:221], v[94:97]
	v_mfma_f32_16x16x32_bf16 v[90:93], v[164:167], v[218:221], v[90:93]
	v_mfma_f32_16x16x32_bf16 v[78:81], v[130:133], v[226:229], v[78:81]
	v_mfma_f32_16x16x32_bf16 v[74:77], v[164:167], v[226:229], v[74:77]
	v_mfma_f32_16x16x32_bf16 v[126:129], v[134:137], v[206:209], v[126:129]
	v_mfma_f32_16x16x32_bf16 v[122:125], v[182:185], v[206:209], v[122:125]
	v_mfma_f32_16x16x32_bf16 v[110:113], v[134:137], v[214:217], v[110:113]
	v_mfma_f32_16x16x32_bf16 v[106:109], v[182:185], v[214:217], v[106:109]
	v_mfma_f32_16x16x32_bf16 v[94:97], v[134:137], v[222:225], v[94:97]
	v_mfma_f32_16x16x32_bf16 v[90:93], v[182:185], v[222:225], v[90:93]
	v_mfma_f32_16x16x32_bf16 v[78:81], v[134:137], v[230:233], v[78:81]
	v_mfma_f32_16x16x32_bf16 v[74:77], v[182:185], v[230:233], v[74:77]
	s_setprio 0
	s_setprio 1
	v_mfma_f32_16x16x32_bf16 v[118:121], v[186:189], v[202:205], v[118:121]
	v_mfma_f32_16x16x32_bf16 v[114:117], v[194:197], v[202:205], v[114:117]
	v_mfma_f32_16x16x32_bf16 v[102:105], v[186:189], v[210:213], v[102:105]
	v_mfma_f32_16x16x32_bf16 v[98:101], v[194:197], v[210:213], v[98:101]
	v_mfma_f32_16x16x32_bf16 v[86:89], v[186:189], v[218:221], v[86:89]
	v_mfma_f32_16x16x32_bf16 v[82:85], v[194:197], v[218:221], v[82:85]
	v_mfma_f32_16x16x32_bf16 v[70:73], v[186:189], v[226:229], v[70:73]
	v_mfma_f32_16x16x32_bf16 v[66:69], v[194:197], v[226:229], v[66:69]
	v_mfma_f32_16x16x32_bf16 v[118:121], v[190:193], v[206:209], v[118:121]
	v_mfma_f32_16x16x32_bf16 v[114:117], v[198:201], v[206:209], v[114:117]
	v_mfma_f32_16x16x32_bf16 v[102:105], v[190:193], v[214:217], v[102:105]
	v_mfma_f32_16x16x32_bf16 v[98:101], v[198:201], v[214:217], v[98:101]
	s_setprio 2
	s_barrier
	v_mfma_f32_16x16x32_bf16 v[86:89], v[190:193], v[222:225], v[86:89]
	v_mfma_f32_16x16x32_bf16 v[82:85], v[198:201], v[222:225], v[82:85]
	v_mfma_f32_16x16x32_bf16 v[70:73], v[190:193], v[230:233], v[70:73]
	v_mfma_f32_16x16x32_bf16 v[66:69], v[198:201], v[230:233], v[66:69]
	s_setprio 0
	s_add_i32 s23, s26, s46
	v_lshl_add_u64 v[168:169], s[42:43], 0, v[162:163]
	s_mov_b32 m0, s23
	ds_read_b128 v[202:205], v180 offset:16384
	ds_read_b128 v[206:209], v180 offset:17408
	ds_read_b128 v[210:213], v180 offset:18432
	ds_read_b128 v[214:217], v180 offset:19456
	ds_read_b128 v[218:221], v180 offset:20480
	ds_read_b128 v[222:225], v180 offset:21504
	ds_read_b128 v[226:229], v180 offset:22528
	ds_read_b128 v[230:233], v180 offset:23552
	global_load_lds_dwordx4 v[168:169], off
	s_add_i32 m0, s23, 0x2000
	s_add_u32 s54, s42, 0x80000
	v_lshl_add_u64 v[234:235], s[42:43], 0, v[142:143]
	s_addc_u32 s55, s43, 0
	s_add_i32 s21, s21, s46
	global_load_lds_dwordx4 v[234:235], off
	v_lshl_add_u64 v[236:237], s[54:55], 0, v[162:163]
	s_mov_b32 m0, s21
	v_lshl_add_u64 v[238:239], s[44:45], 0, v[140:141]
	global_load_lds_dwordx4 v[236:237], off
	v_lshl_add_u64 v[236:237], s[54:55], 0, v[142:143]
	s_add_i32 m0, s21, 0x2000
	s_nop 0
	global_load_lds_dwordx4 v[236:237], off
	v_lshl_add_u64 v[236:237], s[44:45], 0, v[138:139]
	s_mov_b32 m0, s47
	s_nop 0
	global_load_lds_dwordx4 v[236:237], off
	s_mov_b32 m0, s48
	s_nop 0
	global_load_lds_dwordx4 v[238:239], off
	s_waitcnt vmcnt(8)
	s_waitcnt lgkmcnt(0)
	s_barrier
	s_setprio 1
	s_waitcnt lgkmcnt(0)
	v_mfma_f32_16x16x32_bf16 v[62:65], v[130:133], v[202:205], v[62:65]
	v_mfma_f32_16x16x32_bf16 v[58:61], v[164:167], v[202:205], v[58:61]
	v_mfma_f32_16x16x32_bf16 v[46:49], v[130:133], v[210:213], v[46:49]
	v_mfma_f32_16x16x32_bf16 v[42:45], v[164:167], v[210:213], v[42:45]
	v_mfma_f32_16x16x32_bf16 v[30:33], v[130:133], v[218:221], v[30:33]
	v_mfma_f32_16x16x32_bf16 v[26:29], v[164:167], v[218:221], v[26:29]
	v_mfma_f32_16x16x32_bf16 v[14:17], v[130:133], v[226:229], v[14:17]
	v_mfma_f32_16x16x32_bf16 v[10:13], v[164:167], v[226:229], v[10:13]
	v_mfma_f32_16x16x32_bf16 v[62:65], v[134:137], v[206:209], v[62:65]
	v_mfma_f32_16x16x32_bf16 v[58:61], v[182:185], v[206:209], v[58:61]
	v_mfma_f32_16x16x32_bf16 v[46:49], v[134:137], v[214:217], v[46:49]
	v_mfma_f32_16x16x32_bf16 v[42:45], v[182:185], v[214:217], v[42:45]
	v_mfma_f32_16x16x32_bf16 v[30:33], v[134:137], v[222:225], v[30:33]
	v_mfma_f32_16x16x32_bf16 v[26:29], v[182:185], v[222:225], v[26:29]
	v_mfma_f32_16x16x32_bf16 v[14:17], v[134:137], v[230:233], v[14:17]
	v_mfma_f32_16x16x32_bf16 v[10:13], v[182:185], v[230:233], v[10:13]
	s_setprio 0
	s_setprio 1
	v_mfma_f32_16x16x32_bf16 v[54:57], v[186:189], v[202:205], v[54:57]
	v_mfma_f32_16x16x32_bf16 v[50:53], v[194:197], v[202:205], v[50:53]
	v_mfma_f32_16x16x32_bf16 v[38:41], v[186:189], v[210:213], v[38:41]
	v_mfma_f32_16x16x32_bf16 v[34:37], v[194:197], v[210:213], v[34:37]
	v_mfma_f32_16x16x32_bf16 v[22:25], v[186:189], v[218:221], v[22:25]
	v_mfma_f32_16x16x32_bf16 v[18:21], v[194:197], v[218:221], v[18:21]
	v_mfma_f32_16x16x32_bf16 v[6:9], v[186:189], v[226:229], v[6:9]
	v_mfma_f32_16x16x32_bf16 v[2:5], v[194:197], v[226:229], v[2:5]
	v_mfma_f32_16x16x32_bf16 v[54:57], v[190:193], v[206:209], v[54:57]
	v_mfma_f32_16x16x32_bf16 v[50:53], v[198:201], v[206:209], v[50:53]
	v_mfma_f32_16x16x32_bf16 v[38:41], v[190:193], v[214:217], v[38:41]
	v_mfma_f32_16x16x32_bf16 v[34:37], v[198:201], v[214:217], v[34:37]
	s_setprio 2
	s_barrier
	v_mfma_f32_16x16x32_bf16 v[22:25], v[190:193], v[222:225], v[22:25]
	v_mfma_f32_16x16x32_bf16 v[18:21], v[198:201], v[222:225], v[18:21]
	v_mfma_f32_16x16x32_bf16 v[6:9], v[190:193], v[230:233], v[6:9]
	v_mfma_f32_16x16x32_bf16 v[2:5], v[198:201], v[230:233], v[2:5]
	s_setprio 0
	s_add_i32 s21, 0, 0x18000
	v_add_u32_e32 v153, s21, v147
	s_add_i32 s23, 0, 0x1c000
	ds_read_b128 v[130:133], v153
	ds_read_b128 v[134:137], v153 offset:1024
	ds_read_b128 v[164:167], v153 offset:2048
	ds_read_b128 v[182:185], v153 offset:3072
	v_add_u32_e32 v153, s23, v147
	ds_read_b128 v[186:189], v153
	ds_read_b128 v[190:193], v153 offset:1024
	ds_read_b128 v[194:197], v153 offset:2048
	ds_read_b128 v[198:201], v153 offset:3072
	s_add_u32 s44, s44, 0x80000
	s_addc_u32 s45, s45, 0
	s_mov_b32 m0, s49
	v_lshl_add_u64 v[240:241], s[44:45], 0, v[138:139]
	ds_read_b128 v[202:205], v180 offset:32768
	ds_read_b128 v[206:209], v180 offset:33792
	ds_read_b128 v[210:213], v180 offset:34816
	ds_read_b128 v[214:217], v180 offset:35840
	ds_read_b128 v[218:221], v180 offset:36864
	ds_read_b128 v[222:225], v180 offset:37888
	ds_read_b128 v[226:229], v180 offset:38912
	ds_read_b128 v[230:233], v180 offset:39936
	global_load_lds_dwordx4 v[240:241], off
	v_lshl_add_u64 v[240:241], s[44:45], 0, v[140:141]
	s_mov_b32 m0, s50
	s_nop 0
	global_load_lds_dwordx4 v[240:241], off
	s_waitcnt vmcnt(8)
	s_waitcnt lgkmcnt(0)
	s_barrier
	s_setprio 1
	s_waitcnt lgkmcnt(0)
	v_mfma_f32_16x16x32_bf16 v[126:129], v[130:133], v[202:205], v[126:129]
	v_mfma_f32_16x16x32_bf16 v[122:125], v[164:167], v[202:205], v[122:125]
	v_mfma_f32_16x16x32_bf16 v[110:113], v[130:133], v[210:213], v[110:113]
	v_mfma_f32_16x16x32_bf16 v[106:109], v[164:167], v[210:213], v[106:109]
	v_mfma_f32_16x16x32_bf16 v[94:97], v[130:133], v[218:221], v[94:97]
	v_mfma_f32_16x16x32_bf16 v[90:93], v[164:167], v[218:221], v[90:93]
	v_mfma_f32_16x16x32_bf16 v[78:81], v[130:133], v[226:229], v[78:81]
	v_mfma_f32_16x16x32_bf16 v[74:77], v[164:167], v[226:229], v[74:77]
	v_mfma_f32_16x16x32_bf16 v[126:129], v[134:137], v[206:209], v[126:129]
	v_mfma_f32_16x16x32_bf16 v[122:125], v[182:185], v[206:209], v[122:125]
	v_mfma_f32_16x16x32_bf16 v[110:113], v[134:137], v[214:217], v[110:113]
	v_mfma_f32_16x16x32_bf16 v[106:109], v[182:185], v[214:217], v[106:109]
	v_mfma_f32_16x16x32_bf16 v[94:97], v[134:137], v[222:225], v[94:97]
	v_mfma_f32_16x16x32_bf16 v[90:93], v[182:185], v[222:225], v[90:93]
	v_mfma_f32_16x16x32_bf16 v[78:81], v[134:137], v[230:233], v[78:81]
	v_mfma_f32_16x16x32_bf16 v[74:77], v[182:185], v[230:233], v[74:77]
	s_setprio 0
	s_setprio 1
	v_mfma_f32_16x16x32_bf16 v[118:121], v[186:189], v[202:205], v[118:121]
	v_mfma_f32_16x16x32_bf16 v[114:117], v[194:197], v[202:205], v[114:117]
	v_mfma_f32_16x16x32_bf16 v[102:105], v[186:189], v[210:213], v[102:105]
	v_mfma_f32_16x16x32_bf16 v[98:101], v[194:197], v[210:213], v[98:101]
	v_mfma_f32_16x16x32_bf16 v[86:89], v[186:189], v[218:221], v[86:89]
	v_mfma_f32_16x16x32_bf16 v[82:85], v[194:197], v[218:221], v[82:85]
	v_mfma_f32_16x16x32_bf16 v[70:73], v[186:189], v[226:229], v[70:73]
	v_mfma_f32_16x16x32_bf16 v[66:69], v[194:197], v[226:229], v[66:69]
	v_mfma_f32_16x16x32_bf16 v[118:121], v[190:193], v[206:209], v[118:121]
	v_mfma_f32_16x16x32_bf16 v[114:117], v[198:201], v[206:209], v[114:117]
	v_mfma_f32_16x16x32_bf16 v[102:105], v[190:193], v[214:217], v[102:105]
	v_mfma_f32_16x16x32_bf16 v[98:101], v[198:201], v[214:217], v[98:101]
	s_setprio 2
	s_barrier
	v_mfma_f32_16x16x32_bf16 v[86:89], v[190:193], v[222:225], v[86:89]
	v_mfma_f32_16x16x32_bf16 v[82:85], v[198:201], v[222:225], v[82:85]
	v_mfma_f32_16x16x32_bf16 v[70:73], v[190:193], v[230:233], v[70:73]
	v_mfma_f32_16x16x32_bf16 v[66:69], v[198:201], v[230:233], v[66:69]
	s_setprio 0
	s_add_i32 s21, s21, s46
	v_lshl_add_u64 v[168:169], v[168:169], 0, s[6:7]
	s_mov_b32 m0, s21
	ds_read_b128 v[202:205], v180 offset:49152
	ds_read_b128 v[206:209], v180 offset:50176
	ds_read_b128 v[210:213], v180 offset:51200
	ds_read_b128 v[214:217], v180 offset:52224
	ds_read_b128 v[218:221], v180 offset:53248
	ds_read_b128 v[222:225], v180 offset:54272
	ds_read_b128 v[226:229], v180 offset:55296
	ds_read_b128 v[230:233], v180 offset:56320
	global_load_lds_dwordx4 v[168:169], off
	s_add_i32 m0, s21, 0x2000
	s_add_u32 s42, s42, 0x80080
	v_lshl_add_u64 v[168:169], v[234:235], 0, s[6:7]
	s_addc_u32 s43, s43, 0
	s_add_i32 s21, s23, s46
	global_load_lds_dwordx4 v[168:169], off
	v_lshl_add_u64 v[168:169], s[42:43], 0, v[162:163]
	s_mov_b32 m0, s21
	s_nop 0
	global_load_lds_dwordx4 v[168:169], off
	v_lshl_add_u64 v[168:169], s[42:43], 0, v[142:143]
	s_add_i32 m0, s21, 0x2000
	s_nop 0
	global_load_lds_dwordx4 v[168:169], off
	v_lshl_add_u64 v[168:169], v[236:237], 0, s[6:7]
	s_mov_b32 m0, s51
	s_nop 0
	global_load_lds_dwordx4 v[168:169], off
	v_lshl_add_u64 v[168:169], v[238:239], 0, s[6:7]
	s_mov_b32 m0, s52
	s_nop 0
	global_load_lds_dwordx4 v[168:169], off
	s_waitcnt vmcnt(8)
	s_waitcnt lgkmcnt(0)
	s_barrier
	s_setprio 1
	s_waitcnt lgkmcnt(0)
	v_mfma_f32_16x16x32_bf16 v[62:65], v[130:133], v[202:205], v[62:65]
	v_mfma_f32_16x16x32_bf16 v[58:61], v[164:167], v[202:205], v[58:61]
	v_mfma_f32_16x16x32_bf16 v[46:49], v[130:133], v[210:213], v[46:49]
	v_mfma_f32_16x16x32_bf16 v[42:45], v[164:167], v[210:213], v[42:45]
	v_mfma_f32_16x16x32_bf16 v[30:33], v[130:133], v[218:221], v[30:33]
	v_mfma_f32_16x16x32_bf16 v[26:29], v[164:167], v[218:221], v[26:29]
	v_mfma_f32_16x16x32_bf16 v[14:17], v[130:133], v[226:229], v[14:17]
	v_mfma_f32_16x16x32_bf16 v[10:13], v[164:167], v[226:229], v[10:13]
	v_mfma_f32_16x16x32_bf16 v[62:65], v[134:137], v[206:209], v[62:65]
	v_mfma_f32_16x16x32_bf16 v[58:61], v[182:185], v[206:209], v[58:61]
	v_mfma_f32_16x16x32_bf16 v[46:49], v[134:137], v[214:217], v[46:49]
	v_mfma_f32_16x16x32_bf16 v[42:45], v[182:185], v[214:217], v[42:45]
	v_mfma_f32_16x16x32_bf16 v[30:33], v[134:137], v[222:225], v[30:33]
	v_mfma_f32_16x16x32_bf16 v[26:29], v[182:185], v[222:225], v[26:29]
	v_mfma_f32_16x16x32_bf16 v[14:17], v[134:137], v[230:233], v[14:17]
	v_mfma_f32_16x16x32_bf16 v[10:13], v[182:185], v[230:233], v[10:13]
	s_setprio 0
	s_setprio 1
	v_mfma_f32_16x16x32_bf16 v[54:57], v[186:189], v[202:205], v[54:57]
	v_mfma_f32_16x16x32_bf16 v[50:53], v[194:197], v[202:205], v[50:53]
	v_mfma_f32_16x16x32_bf16 v[38:41], v[186:189], v[210:213], v[38:41]
	v_mfma_f32_16x16x32_bf16 v[34:37], v[194:197], v[210:213], v[34:37]
	v_mfma_f32_16x16x32_bf16 v[22:25], v[186:189], v[218:221], v[22:25]
	v_mfma_f32_16x16x32_bf16 v[18:21], v[194:197], v[218:221], v[18:21]
	v_mfma_f32_16x16x32_bf16 v[6:9], v[186:189], v[226:229], v[6:9]
	v_mfma_f32_16x16x32_bf16 v[2:5], v[194:197], v[226:229], v[2:5]
	v_mfma_f32_16x16x32_bf16 v[54:57], v[190:193], v[206:209], v[54:57]
	v_mfma_f32_16x16x32_bf16 v[50:53], v[198:201], v[206:209], v[50:53]
	v_mfma_f32_16x16x32_bf16 v[38:41], v[190:193], v[214:217], v[38:41]
	v_mfma_f32_16x16x32_bf16 v[34:37], v[198:201], v[214:217], v[34:37]
	s_setprio 2
	s_barrier
	v_mfma_f32_16x16x32_bf16 v[22:25], v[190:193], v[222:225], v[22:25]
	v_mfma_f32_16x16x32_bf16 v[18:21], v[198:201], v[222:225], v[18:21]
	v_mfma_f32_16x16x32_bf16 v[6:9], v[190:193], v[230:233], v[6:9]
	v_mfma_f32_16x16x32_bf16 v[2:5], v[198:201], v[230:233], v[2:5]
	s_setprio 0
	s_add_i32 s20, s20, 2
	s_add_u32 s36, s36, 0x100
	s_addc_u32 s37, s37, 0
	s_add_u32 s13, s13, 0x100
	s_addc_u32 s19, s19, 0
	s_cmp_gt_u32 s20, 29
	s_cbranch_scc0 .LBB0_1294
	s_and_b64 vcc, exec, s[2:3]
	s_cbranch_vccz .LBB0_1297
	s_barrier

.LBB0_1620:
	s_ashr_i32 s19, s18, 31
	s_lshl_b64 s[28:29], s[18:19], 18
	v_readlane_b32 s5, v245, 24
	s_add_u32 s28, s5, s28
	v_readlane_b32 s5, v245, 26
	s_addc_u32 s29, s5, s29
	s_and_b64 s[34:35], s[22:23], exec
	s_cselect_b32 s8, s29, s43
	s_cselect_b32 s19, s28, s42
	s_ashr_i32 s5, s4, 31
	s_lshl_b64 s[34:35], s[4:5], 18
	s_add_u32 s34, s11, s34
	s_addc_u32 s35, s13, s35
	s_and_b64 s[46:47], s[22:23], exec
	s_cselect_b32 s5, s35, s45
	s_cselect_b32 s21, s34, s44
	s_add_u32 s42, s42, 0x20080
	s_addc_u32 s43, s43, 0
	s_add_u32 s39, s44, 0x100
	s_addc_u32 s50, s45, 0
	s_mov_b32 s51, -2
	s_waitcnt vmcnt(0) lgkmcnt(0)
	s_add_u32 s44, s42, 0xfffe0080
	s_addc_u32 s45, s43, -1
	s_add_i32 s52, 0, 0x10000
	s_cmp_eq_u32 s51, 4
	s_cselect_b32 s47, s8, s45
	s_cselect_b32 s46, s19, s44
	v_add_u32_e32 v154, s52, v145
	s_cselect_b32 s45, s5, s50
	s_cselect_b32 s44, s21, s39
	s_add_i32 s54, 0, 0x14000
	ds_read_b128 v[130:133], v154
	ds_read_b128 v[134:137], v154 offset:1024
	ds_read_b128 v[150:153], v154 offset:2048
	ds_read_b128 v[158:161], v154 offset:3072
	v_add_u32_e32 v154, s54, v145
	ds_read_b128 v[164:167], v154
	ds_read_b128 v[180:183], v154 offset:1024
	ds_read_b128 v[184:187], v154 offset:2048
	ds_read_b128 v[188:191], v154 offset:3072
	v_lshl_add_u64 v[154:155], s[42:43], 0, v[146:147]
	s_add_i32 m0, s20, 0xc000
	ds_read_b128 v[192:195], v157
	ds_read_b128 v[196:199], v157 offset:1024
	ds_read_b128 v[200:203], v157 offset:2048
	ds_read_b128 v[204:207], v157 offset:3072
	ds_read_b128 v[208:211], v157 offset:4096
	ds_read_b128 v[212:215], v157 offset:5120
	ds_read_b128 v[216:219], v157 offset:6144
	ds_read_b128 v[220:223], v157 offset:7168
	global_load_lds_dwordx4 v[154:155], off
	v_lshl_add_u64 v[154:155], s[42:43], 0, v[148:149]
	s_add_i32 m0, s20, 0xe000
	s_nop 0
	global_load_lds_dwordx4 v[154:155], off
	s_waitcnt vmcnt(8)
	s_waitcnt lgkmcnt(0)
	s_barrier
	s_setprio 1
	s_waitcnt lgkmcnt(0)
	v_mfma_f32_16x16x32_bf16 v[126:129], v[130:133], v[192:195], 0
	v_mfma_f32_16x16x32_bf16 v[122:125], v[150:153], v[192:195], 0
	v_mfma_f32_16x16x32_bf16 v[110:113], v[130:133], v[200:203], 0
	v_mfma_f32_16x16x32_bf16 v[106:109], v[150:153], v[200:203], 0
	v_mfma_f32_16x16x32_bf16 v[94:97], v[130:133], v[208:211], 0
	v_mfma_f32_16x16x32_bf16 v[90:93], v[150:153], v[208:211], 0
	v_mfma_f32_16x16x32_bf16 v[78:81], v[130:133], v[216:219], 0
	v_mfma_f32_16x16x32_bf16 v[74:77], v[150:153], v[216:219], 0
	v_mfma_f32_16x16x32_bf16 v[126:129], v[134:137], v[196:199], v[126:129]
	v_mfma_f32_16x16x32_bf16 v[122:125], v[158:161], v[196:199], v[122:125]
	v_mfma_f32_16x16x32_bf16 v[110:113], v[134:137], v[204:207], v[110:113]
	v_mfma_f32_16x16x32_bf16 v[106:109], v[158:161], v[204:207], v[106:109]
	v_mfma_f32_16x16x32_bf16 v[94:97], v[134:137], v[212:215], v[94:97]
	v_mfma_f32_16x16x32_bf16 v[90:93], v[158:161], v[212:215], v[90:93]
	v_mfma_f32_16x16x32_bf16 v[78:81], v[134:137], v[220:223], v[78:81]
	v_mfma_f32_16x16x32_bf16 v[74:77], v[158:161], v[220:223], v[74:77]
	s_setprio 0
	s_setprio 1
	v_mfma_f32_16x16x32_bf16 v[118:121], v[164:167], v[192:195], 0
	v_mfma_f32_16x16x32_bf16 v[114:117], v[184:187], v[192:195], 0
	v_mfma_f32_16x16x32_bf16 v[102:105], v[164:167], v[200:203], 0
	v_mfma_f32_16x16x32_bf16 v[98:101], v[184:187], v[200:203], 0
	v_mfma_f32_16x16x32_bf16 v[86:89], v[164:167], v[208:211], 0
	v_mfma_f32_16x16x32_bf16 v[82:85], v[184:187], v[208:211], 0
	v_mfma_f32_16x16x32_bf16 v[70:73], v[164:167], v[216:219], 0
	v_mfma_f32_16x16x32_bf16 v[66:69], v[184:187], v[216:219], 0
	v_mfma_f32_16x16x32_bf16 v[118:121], v[180:183], v[196:199], v[118:121]
	v_mfma_f32_16x16x32_bf16 v[114:117], v[188:191], v[196:199], v[114:117]
	v_mfma_f32_16x16x32_bf16 v[102:105], v[180:183], v[204:207], v[102:105]
	v_mfma_f32_16x16x32_bf16 v[98:101], v[188:191], v[204:207], v[98:101]
	s_setprio 2
	s_barrier
	v_mfma_f32_16x16x32_bf16 v[86:89], v[180:183], v[212:215], v[86:89]
	v_mfma_f32_16x16x32_bf16 v[82:85], v[188:191], v[212:215], v[82:85]
	v_mfma_f32_16x16x32_bf16 v[70:73], v[180:183], v[220:223], v[70:73]
	v_mfma_f32_16x16x32_bf16 v[66:69], v[188:191], v[220:223], v[66:69]
	s_setprio 0
	s_add_i32 s52, s52, s9
	v_lshl_add_u64 v[154:155], s[44:45], 0, v[162:163]
	s_mov_b32 m0, s52
	ds_read_b128 v[192:195], v157 offset:16384
	ds_read_b128 v[196:199], v157 offset:17408
	ds_read_b128 v[200:203], v157 offset:18432
	ds_read_b128 v[204:207], v157 offset:19456
	ds_read_b128 v[208:211], v157 offset:20480
	ds_read_b128 v[212:215], v157 offset:21504
	ds_read_b128 v[216:219], v157 offset:22528
	ds_read_b128 v[220:223], v157 offset:23552
	global_load_lds_dwordx4 v[154:155], off
	s_add_i32 m0, s52, 0x2000
	s_add_u32 s52, s44, 0x20000
	v_lshl_add_u64 v[168:169], s[44:45], 0, v[142:143]
	s_addc_u32 s53, s45, 0
	s_add_i32 s54, s54, s9
	global_load_lds_dwordx4 v[168:169], off
	v_lshl_add_u64 v[224:225], s[52:53], 0, v[162:163]
	s_mov_b32 m0, s54
	v_lshl_add_u64 v[226:227], s[46:47], 0, v[140:141]
	global_load_lds_dwordx4 v[224:225], off
	v_lshl_add_u64 v[224:225], s[52:53], 0, v[142:143]
	s_add_i32 m0, s54, 0x2000
	s_nop 0
	global_load_lds_dwordx4 v[224:225], off
	v_lshl_add_u64 v[224:225], s[46:47], 0, v[138:139]
	s_mov_b32 m0, s20
	s_nop 0
	global_load_lds_dwordx4 v[224:225], off
	s_mov_b32 m0, s25
	s_nop 0
	global_load_lds_dwordx4 v[226:227], off
	s_waitcnt vmcnt(8)
	s_waitcnt lgkmcnt(0)
	s_barrier
	s_setprio 1
	s_waitcnt lgkmcnt(0)
	v_mfma_f32_16x16x32_bf16 v[62:65], v[130:133], v[192:195], 0
	v_mfma_f32_16x16x32_bf16 v[58:61], v[150:153], v[192:195], 0
	v_mfma_f32_16x16x32_bf16 v[46:49], v[130:133], v[200:203], 0
	v_mfma_f32_16x16x32_bf16 v[42:45], v[150:153], v[200:203], 0
	v_mfma_f32_16x16x32_bf16 v[30:33], v[130:133], v[208:211], 0
	v_mfma_f32_16x16x32_bf16 v[26:29], v[150:153], v[208:211], 0
	v_mfma_f32_16x16x32_bf16 v[14:17], v[130:133], v[216:219], 0
	v_mfma_f32_16x16x32_bf16 v[10:13], v[150:153], v[216:219], 0
	v_mfma_f32_16x16x32_bf16 v[62:65], v[134:137], v[196:199], v[62:65]
	v_mfma_f32_16x16x32_bf16 v[58:61], v[158:161], v[196:199], v[58:61]
	v_mfma_f32_16x16x32_bf16 v[46:49], v[134:137], v[204:207], v[46:49]
	v_mfma_f32_16x16x32_bf16 v[42:45], v[158:161], v[204:207], v[42:45]
	v_mfma_f32_16x16x32_bf16 v[30:33], v[134:137], v[212:215], v[30:33]
	v_mfma_f32_16x16x32_bf16 v[26:29], v[158:161], v[212:215], v[26:29]
	v_mfma_f32_16x16x32_bf16 v[14:17], v[134:137], v[220:223], v[14:17]
	v_mfma_f32_16x16x32_bf16 v[10:13], v[158:161], v[220:223], v[10:13]
	s_setprio 0
	s_setprio 1
	v_mfma_f32_16x16x32_bf16 v[54:57], v[164:167], v[192:195], 0
	v_mfma_f32_16x16x32_bf16 v[50:53], v[184:187], v[192:195], 0
	v_mfma_f32_16x16x32_bf16 v[38:41], v[164:167], v[200:203], 0
	v_mfma_f32_16x16x32_bf16 v[34:37], v[184:187], v[200:203], 0
	v_mfma_f32_16x16x32_bf16 v[22:25], v[164:167], v[208:211], 0
	v_mfma_f32_16x16x32_bf16 v[18:21], v[184:187], v[208:211], 0
	v_mfma_f32_16x16x32_bf16 v[6:9], v[164:167], v[216:219], 0
	v_mfma_f32_16x16x32_bf16 v[2:5], v[184:187], v[216:219], 0
	v_mfma_f32_16x16x32_bf16 v[54:57], v[180:183], v[196:199], v[54:57]
	v_mfma_f32_16x16x32_bf16 v[50:53], v[188:191], v[196:199], v[50:53]
	v_mfma_f32_16x16x32_bf16 v[38:41], v[180:183], v[204:207], v[38:41]
	v_mfma_f32_16x16x32_bf16 v[34:37], v[188:191], v[204:207], v[34:37]
	s_setprio 2
	s_barrier
	v_mfma_f32_16x16x32_bf16 v[22:25], v[180:183], v[212:215], v[22:25]
	v_mfma_f32_16x16x32_bf16 v[18:21], v[188:191], v[212:215], v[18:21]
	v_mfma_f32_16x16x32_bf16 v[6:9], v[180:183], v[220:223], v[6:9]
	v_mfma_f32_16x16x32_bf16 v[2:5], v[188:191], v[220:223], v[2:5]
	s_setprio 0
	s_add_i32 s52, 0, 0x18000
	s_add_i32 s53, 0, 0x1c000
	v_add_u32_e32 v158, s52, v145
	v_add_u32_e32 v179, s53, v145
	ds_read_b128 v[130:133], v158
	ds_read_b128 v[134:137], v158 offset:1024
	ds_read_b128 v[150:153], v158 offset:2048
	ds_read_b128 v[158:161], v158 offset:3072
	ds_read_b128 v[164:167], v179
	ds_read_b128 v[180:183], v179 offset:1024
	ds_read_b128 v[184:187], v179 offset:2048
	ds_read_b128 v[188:191], v179 offset:3072
	s_add_u32 s46, s46, 0x20000
	s_addc_u32 s47, s47, 0
	s_mov_b32 m0, s26
	v_lshl_add_u64 v[228:229], s[46:47], 0, v[138:139]
	ds_read_b128 v[192:195], v157 offset:32768
	ds_read_b128 v[196:199], v157 offset:33792
	ds_read_b128 v[200:203], v157 offset:34816
	ds_read_b128 v[204:207], v157 offset:35840
	ds_read_b128 v[208:211], v157 offset:36864
	ds_read_b128 v[212:215], v157 offset:37888
	ds_read_b128 v[216:219], v157 offset:38912
	ds_read_b128 v[220:223], v157 offset:39936
	global_load_lds_dwordx4 v[228:229], off
	v_lshl_add_u64 v[228:229], s[46:47], 0, v[140:141]
	s_mov_b32 m0, s27
	s_nop 0
	global_load_lds_dwordx4 v[228:229], off
	s_waitcnt vmcnt(8)
	s_waitcnt lgkmcnt(0)
	s_barrier
	s_setprio 1
	s_waitcnt lgkmcnt(0)
	v_mfma_f32_16x16x32_bf16 v[126:129], v[130:133], v[192:195], v[126:129]
	v_mfma_f32_16x16x32_bf16 v[122:125], v[150:153], v[192:195], v[122:125]
	v_mfma_f32_16x16x32_bf16 v[110:113], v[130:133], v[200:203], v[110:113]
	v_mfma_f32_16x16x32_bf16 v[106:109], v[150:153], v[200:203], v[106:109]
	v_mfma_f32_16x16x32_bf16 v[94:97], v[130:133], v[208:211], v[94:97]
	v_mfma_f32_16x16x32_bf16 v[90:93], v[150:153], v[208:211], v[90:93]
	v_mfma_f32_16x16x32_bf16 v[78:81], v[130:133], v[216:219], v[78:81]
	v_mfma_f32_16x16x32_bf16 v[74:77], v[150:153], v[216:219], v[74:77]
	v_mfma_f32_16x16x32_bf16 v[126:129], v[134:137], v[196:199], v[126:129]
	v_mfma_f32_16x16x32_bf16 v[122:125], v[158:161], v[196:199], v[122:125]
	v_mfma_f32_16x16x32_bf16 v[110:113], v[134:137], v[204:207], v[110:113]
	v_mfma_f32_16x16x32_bf16 v[106:109], v[158:161], v[204:207], v[106:109]
	v_mfma_f32_16x16x32_bf16 v[94:97], v[134:137], v[212:215], v[94:97]
	v_mfma_f32_16x16x32_bf16 v[90:93], v[158:161], v[212:215], v[90:93]
	v_mfma_f32_16x16x32_bf16 v[78:81], v[134:137], v[220:223], v[78:81]
	v_mfma_f32_16x16x32_bf16 v[74:77], v[158:161], v[220:223], v[74:77]
	s_setprio 0
	s_setprio 1
	v_mfma_f32_16x16x32_bf16 v[118:121], v[164:167], v[192:195], v[118:121]
	v_mfma_f32_16x16x32_bf16 v[114:117], v[184:187], v[192:195], v[114:117]
	v_mfma_f32_16x16x32_bf16 v[102:105], v[164:167], v[200:203], v[102:105]
	v_mfma_f32_16x16x32_bf16 v[98:101], v[184:187], v[200:203], v[98:101]
	v_mfma_f32_16x16x32_bf16 v[86:89], v[164:167], v[208:211], v[86:89]
	v_mfma_f32_16x16x32_bf16 v[82:85], v[184:187], v[208:211], v[82:85]
	v_mfma_f32_16x16x32_bf16 v[70:73], v[164:167], v[216:219], v[70:73]
	v_mfma_f32_16x16x32_bf16 v[66:69], v[184:187], v[216:219], v[66:69]
	v_mfma_f32_16x16x32_bf16 v[118:121], v[180:183], v[196:199], v[118:121]
	v_mfma_f32_16x16x32_bf16 v[114:117], v[188:191], v[196:199], v[114:117]
	v_mfma_f32_16x16x32_bf16 v[102:105], v[180:183], v[204:207], v[102:105]
	v_mfma_f32_16x16x32_bf16 v[98:101], v[188:191], v[204:207], v[98:101]
	s_setprio 2
	s_barrier
	v_mfma_f32_16x16x32_bf16 v[86:89], v[180:183], v[212:215], v[86:89]
	v_mfma_f32_16x16x32_bf16 v[82:85], v[188:191], v[212:215], v[82:85]
	v_mfma_f32_16x16x32_bf16 v[70:73], v[180:183], v[220:223], v[70:73]
	v_mfma_f32_16x16x32_bf16 v[66:69], v[188:191], v[220:223], v[66:69]
	s_setprio 0
	s_add_i32 s46, s52, s9
	v_lshl_add_u64 v[154:155], v[154:155], 0, s[6:7]
	s_mov_b32 m0, s46
	ds_read_b128 v[192:195], v157 offset:49152
	ds_read_b128 v[196:199], v157 offset:50176
	ds_read_b128 v[200:203], v157 offset:51200
	ds_read_b128 v[204:207], v157 offset:52224
	ds_read_b128 v[208:211], v157 offset:53248
	ds_read_b128 v[212:215], v157 offset:54272
	ds_read_b128 v[216:219], v157 offset:55296
	ds_read_b128 v[220:223], v157 offset:56320
	global_load_lds_dwordx4 v[154:155], off
	s_add_i32 m0, s46, 0x2000
	s_add_u32 s44, s44, 0x20080
	v_lshl_add_u64 v[154:155], v[168:169], 0, s[6:7]
	s_addc_u32 s45, s45, 0
	s_add_i32 s46, s53, s9
	global_load_lds_dwordx4 v[154:155], off
	v_lshl_add_u64 v[154:155], s[44:45], 0, v[162:163]
	s_mov_b32 m0, s46
	s_nop 0
	global_load_lds_dwordx4 v[154:155], off
	v_lshl_add_u64 v[154:155], s[44:45], 0, v[142:143]
	s_add_i32 m0, s46, 0x2000
	s_nop 0
	global_load_lds_dwordx4 v[154:155], off
	v_lshl_add_u64 v[154:155], v[224:225], 0, s[6:7]
	s_mov_b32 m0, s41
	s_nop 0
	global_load_lds_dwordx4 v[154:155], off
	v_lshl_add_u64 v[154:155], v[226:227], 0, s[6:7]
	s_mov_b32 m0, s48
	s_nop 0
	global_load_lds_dwordx4 v[154:155], off
	s_waitcnt vmcnt(8)
	s_waitcnt lgkmcnt(0)
	s_barrier
	s_setprio 1
	s_waitcnt lgkmcnt(0)
	v_mfma_f32_16x16x32_bf16 v[62:65], v[130:133], v[192:195], v[62:65]
	v_mfma_f32_16x16x32_bf16 v[58:61], v[150:153], v[192:195], v[58:61]
	v_mfma_f32_16x16x32_bf16 v[46:49], v[130:133], v[200:203], v[46:49]
	v_mfma_f32_16x16x32_bf16 v[42:45], v[150:153], v[200:203], v[42:45]
	v_mfma_f32_16x16x32_bf16 v[30:33], v[130:133], v[208:211], v[30:33]
	v_mfma_f32_16x16x32_bf16 v[26:29], v[150:153], v[208:211], v[26:29]
	v_mfma_f32_16x16x32_bf16 v[14:17], v[130:133], v[216:219], v[14:17]
	v_mfma_f32_16x16x32_bf16 v[10:13], v[150:153], v[216:219], v[10:13]
	v_mfma_f32_16x16x32_bf16 v[62:65], v[134:137], v[196:199], v[62:65]
	v_mfma_f32_16x16x32_bf16 v[58:61], v[158:161], v[196:199], v[58:61]
	v_mfma_f32_16x16x32_bf16 v[46:49], v[134:137], v[204:207], v[46:49]
	v_mfma_f32_16x16x32_bf16 v[42:45], v[158:161], v[204:207], v[42:45]
	v_mfma_f32_16x16x32_bf16 v[30:33], v[134:137], v[212:215], v[30:33]
	v_mfma_f32_16x16x32_bf16 v[26:29], v[158:161], v[212:215], v[26:29]
	v_mfma_f32_16x16x32_bf16 v[14:17], v[134:137], v[220:223], v[14:17]
	v_mfma_f32_16x16x32_bf16 v[10:13], v[158:161], v[220:223], v[10:13]
	s_setprio 0
	s_setprio 1
	v_mfma_f32_16x16x32_bf16 v[54:57], v[164:167], v[192:195], v[54:57]
	v_mfma_f32_16x16x32_bf16 v[50:53], v[184:187], v[192:195], v[50:53]
	v_mfma_f32_16x16x32_bf16 v[38:41], v[164:167], v[200:203], v[38:41]
	v_mfma_f32_16x16x32_bf16 v[34:37], v[184:187], v[200:203], v[34:37]
	v_mfma_f32_16x16x32_bf16 v[22:25], v[164:167], v[208:211], v[22:25]
	v_mfma_f32_16x16x32_bf16 v[18:21], v[184:187], v[208:211], v[18:21]
	v_mfma_f32_16x16x32_bf16 v[6:9], v[164:167], v[216:219], v[6:9]
	v_mfma_f32_16x16x32_bf16 v[2:5], v[184:187], v[216:219], v[2:5]
	v_mfma_f32_16x16x32_bf16 v[54:57], v[180:183], v[196:199], v[54:57]
	v_mfma_f32_16x16x32_bf16 v[50:53], v[188:191], v[196:199], v[50:53]
	v_mfma_f32_16x16x32_bf16 v[38:41], v[180:183], v[204:207], v[38:41]
	v_mfma_f32_16x16x32_bf16 v[34:37], v[188:191], v[204:207], v[34:37]
	s_setprio 2
	s_barrier
	v_mfma_f32_16x16x32_bf16 v[22:25], v[180:183], v[212:215], v[22:25]
	v_mfma_f32_16x16x32_bf16 v[18:21], v[188:191], v[212:215], v[18:21]
	v_mfma_f32_16x16x32_bf16 v[6:9], v[180:183], v[220:223], v[6:9]
	v_mfma_f32_16x16x32_bf16 v[2:5], v[188:191], v[220:223], v[2:5]
	s_setprio 0
	s_add_i32 s51, s51, 2
	s_add_u32 s42, s42, 0x100
	s_addc_u32 s43, s43, 0
	s_add_u32 s39, s39, 0x100
	s_addc_u32 s50, s50, 0
	s_cmp_gt_u32 s51, 5
.LBB0_1621:
	s_add_u32 s44, s42, 0xfffe0080
	s_addc_u32 s45, s43, -1
	s_add_i32 s52, 0, 0x10000
	s_cmp_eq_u32 s51, 4
	s_cselect_b32 s47, s8, s45
	s_cselect_b32 s46, s19, s44
	v_add_u32_e32 v154, s52, v145
	s_cselect_b32 s45, s5, s50
	s_cselect_b32 s44, s21, s39
	s_add_i32 s54, 0, 0x14000
	ds_read_b128 v[130:133], v154
	ds_read_b128 v[134:137], v154 offset:1024
	ds_read_b128 v[150:153], v154 offset:2048
	ds_read_b128 v[158:161], v154 offset:3072
	v_add_u32_e32 v154, s54, v145
	ds_read_b128 v[164:167], v154
	ds_read_b128 v[180:183], v154 offset:1024
	ds_read_b128 v[184:187], v154 offset:2048
	ds_read_b128 v[188:191], v154 offset:3072
	v_lshl_add_u64 v[154:155], s[42:43], 0, v[146:147]
	s_add_i32 m0, s20, 0xc000
	ds_read_b128 v[192:195], v157
	ds_read_b128 v[196:199], v157 offset:1024
	ds_read_b128 v[200:203], v157 offset:2048
	ds_read_b128 v[204:207], v157 offset:3072
	ds_read_b128 v[208:211], v157 offset:4096
	ds_read_b128 v[212:215], v157 offset:5120
	ds_read_b128 v[216:219], v157 offset:6144
	ds_read_b128 v[220:223], v157 offset:7168
	global_load_lds_dwordx4 v[154:155], off
	v_lshl_add_u64 v[154:155], s[42:43], 0, v[148:149]
	s_add_i32 m0, s20, 0xe000
	s_nop 0
	global_load_lds_dwordx4 v[154:155], off
	s_waitcnt vmcnt(8)
	s_waitcnt lgkmcnt(0)
	s_barrier
	s_setprio 1
	s_waitcnt lgkmcnt(0)
	v_mfma_f32_16x16x32_bf16 v[126:129], v[130:133], v[192:195], v[126:129]
	v_mfma_f32_16x16x32_bf16 v[122:125], v[150:153], v[192:195], v[122:125]
	v_mfma_f32_16x16x32_bf16 v[110:113], v[130:133], v[200:203], v[110:113]
	v_mfma_f32_16x16x32_bf16 v[106:109], v[150:153], v[200:203], v[106:109]
	v_mfma_f32_16x16x32_bf16 v[94:97], v[130:133], v[208:211], v[94:97]
	v_mfma_f32_16x16x32_bf16 v[90:93], v[150:153], v[208:211], v[90:93]
	v_mfma_f32_16x16x32_bf16 v[78:81], v[130:133], v[216:219], v[78:81]
	v_mfma_f32_16x16x32_bf16 v[74:77], v[150:153], v[216:219], v[74:77]
	v_mfma_f32_16x16x32_bf16 v[126:129], v[134:137], v[196:199], v[126:129]
	v_mfma_f32_16x16x32_bf16 v[122:125], v[158:161], v[196:199], v[122:125]
	v_mfma_f32_16x16x32_bf16 v[110:113], v[134:137], v[204:207], v[110:113]
	v_mfma_f32_16x16x32_bf16 v[106:109], v[158:161], v[204:207], v[106:109]
	v_mfma_f32_16x16x32_bf16 v[94:97], v[134:137], v[212:215], v[94:97]
	v_mfma_f32_16x16x32_bf16 v[90:93], v[158:161], v[212:215], v[90:93]
	v_mfma_f32_16x16x32_bf16 v[78:81], v[134:137], v[220:223], v[78:81]
	v_mfma_f32_16x16x32_bf16 v[74:77], v[158:161], v[220:223], v[74:77]
	s_setprio 0
	s_setprio 1
	v_mfma_f32_16x16x32_bf16 v[118:121], v[164:167], v[192:195], v[118:121]
	v_mfma_f32_16x16x32_bf16 v[114:117], v[184:187], v[192:195], v[114:117]
	v_mfma_f32_16x16x32_bf16 v[102:105], v[164:167], v[200:203], v[102:105]
	v_mfma_f32_16x16x32_bf16 v[98:101], v[184:187], v[200:203], v[98:101]
	v_mfma_f32_16x16x32_bf16 v[86:89], v[164:167], v[208:211], v[86:89]
	v_mfma_f32_16x16x32_bf16 v[82:85], v[184:187], v[208:211], v[82:85]
	v_mfma_f32_16x16x32_bf16 v[70:73], v[164:167], v[216:219], v[70:73]
	v_mfma_f32_16x16x32_bf16 v[66:69], v[184:187], v[216:219], v[66:69]
	v_mfma_f32_16x16x32_bf16 v[118:121], v[180:183], v[196:199], v[118:121]
	v_mfma_f32_16x16x32_bf16 v[114:117], v[188:191], v[196:199], v[114:117]
	v_mfma_f32_16x16x32_bf16 v[102:105], v[180:183], v[204:207], v[102:105]
	v_mfma_f32_16x16x32_bf16 v[98:101], v[188:191], v[204:207], v[98:101]
	s_setprio 2
	s_barrier
	v_mfma_f32_16x16x32_bf16 v[86:89], v[180:183], v[212:215], v[86:89]
	v_mfma_f32_16x16x32_bf16 v[82:85], v[188:191], v[212:215], v[82:85]
	v_mfma_f32_16x16x32_bf16 v[70:73], v[180:183], v[220:223], v[70:73]
	v_mfma_f32_16x16x32_bf16 v[66:69], v[188:191], v[220:223], v[66:69]
	s_setprio 0
	s_add_i32 s52, s52, s9
	v_lshl_add_u64 v[154:155], s[44:45], 0, v[162:163]
	s_mov_b32 m0, s52
	ds_read_b128 v[192:195], v157 offset:16384
	ds_read_b128 v[196:199], v157 offset:17408
	ds_read_b128 v[200:203], v157 offset:18432
	ds_read_b128 v[204:207], v157 offset:19456
	ds_read_b128 v[208:211], v157 offset:20480
	ds_read_b128 v[212:215], v157 offset:21504
	ds_read_b128 v[216:219], v157 offset:22528
	ds_read_b128 v[220:223], v157 offset:23552
	global_load_lds_dwordx4 v[154:155], off
	s_add_i32 m0, s52, 0x2000
	s_add_u32 s52, s44, 0x20000
	v_lshl_add_u64 v[168:169], s[44:45], 0, v[142:143]
	s_addc_u32 s53, s45, 0
	s_add_i32 s54, s54, s9
	global_load_lds_dwordx4 v[168:169], off
	v_lshl_add_u64 v[224:225], s[52:53], 0, v[162:163]
	s_mov_b32 m0, s54
	v_lshl_add_u64 v[226:227], s[46:47], 0, v[140:141]
	global_load_lds_dwordx4 v[224:225], off
	v_lshl_add_u64 v[224:225], s[52:53], 0, v[142:143]
	s_add_i32 m0, s54, 0x2000
	s_nop 0
	global_load_lds_dwordx4 v[224:225], off
	v_lshl_add_u64 v[224:225], s[46:47], 0, v[138:139]
	s_mov_b32 m0, s20
	s_nop 0
	global_load_lds_dwordx4 v[224:225], off
	s_mov_b32 m0, s25
	s_nop 0
	global_load_lds_dwordx4 v[226:227], off
	s_waitcnt vmcnt(8)
	s_waitcnt lgkmcnt(0)
	s_barrier
	s_setprio 1
	s_waitcnt lgkmcnt(0)
	v_mfma_f32_16x16x32_bf16 v[62:65], v[130:133], v[192:195], v[62:65]
	v_mfma_f32_16x16x32_bf16 v[58:61], v[150:153], v[192:195], v[58:61]
	v_mfma_f32_16x16x32_bf16 v[46:49], v[130:133], v[200:203], v[46:49]
	v_mfma_f32_16x16x32_bf16 v[42:45], v[150:153], v[200:203], v[42:45]
	v_mfma_f32_16x16x32_bf16 v[30:33], v[130:133], v[208:211], v[30:33]
	v_mfma_f32_16x16x32_bf16 v[26:29], v[150:153], v[208:211], v[26:29]
	v_mfma_f32_16x16x32_bf16 v[14:17], v[130:133], v[216:219], v[14:17]
	v_mfma_f32_16x16x32_bf16 v[10:13], v[150:153], v[216:219], v[10:13]
	v_mfma_f32_16x16x32_bf16 v[62:65], v[134:137], v[196:199], v[62:65]
	v_mfma_f32_16x16x32_bf16 v[58:61], v[158:161], v[196:199], v[58:61]
	v_mfma_f32_16x16x32_bf16 v[46:49], v[134:137], v[204:207], v[46:49]
	v_mfma_f32_16x16x32_bf16 v[42:45], v[158:161], v[204:207], v[42:45]
	v_mfma_f32_16x16x32_bf16 v[30:33], v[134:137], v[212:215], v[30:33]
	v_mfma_f32_16x16x32_bf16 v[26:29], v[158:161], v[212:215], v[26:29]
	v_mfma_f32_16x16x32_bf16 v[14:17], v[134:137], v[220:223], v[14:17]
	v_mfma_f32_16x16x32_bf16 v[10:13], v[158:161], v[220:223], v[10:13]
	s_setprio 0
	s_setprio 1
	v_mfma_f32_16x16x32_bf16 v[54:57], v[164:167], v[192:195], v[54:57]
	v_mfma_f32_16x16x32_bf16 v[50:53], v[184:187], v[192:195], v[50:53]
	v_mfma_f32_16x16x32_bf16 v[38:41], v[164:167], v[200:203], v[38:41]
	v_mfma_f32_16x16x32_bf16 v[34:37], v[184:187], v[200:203], v[34:37]
	v_mfma_f32_16x16x32_bf16 v[22:25], v[164:167], v[208:211], v[22:25]
	v_mfma_f32_16x16x32_bf16 v[18:21], v[184:187], v[208:211], v[18:21]
	v_mfma_f32_16x16x32_bf16 v[6:9], v[164:167], v[216:219], v[6:9]
	v_mfma_f32_16x16x32_bf16 v[2:5], v[184:187], v[216:219], v[2:5]
	v_mfma_f32_16x16x32_bf16 v[54:57], v[180:183], v[196:199], v[54:57]
	v_mfma_f32_16x16x32_bf16 v[50:53], v[188:191], v[196:199], v[50:53]
	v_mfma_f32_16x16x32_bf16 v[38:41], v[180:183], v[204:207], v[38:41]
	v_mfma_f32_16x16x32_bf16 v[34:37], v[188:191], v[204:207], v[34:37]
	s_setprio 2
	s_barrier
	v_mfma_f32_16x16x32_bf16 v[22:25], v[180:183], v[212:215], v[22:25]
	v_mfma_f32_16x16x32_bf16 v[18:21], v[188:191], v[212:215], v[18:21]
	v_mfma_f32_16x16x32_bf16 v[6:9], v[180:183], v[220:223], v[6:9]
	v_mfma_f32_16x16x32_bf16 v[2:5], v[188:191], v[220:223], v[2:5]
	s_setprio 0
	s_add_i32 s52, 0, 0x18000
	s_add_i32 s53, 0, 0x1c000
	v_add_u32_e32 v158, s52, v145
	v_add_u32_e32 v179, s53, v145
	ds_read_b128 v[130:133], v158
	ds_read_b128 v[134:137], v158 offset:1024
	ds_read_b128 v[150:153], v158 offset:2048
	ds_read_b128 v[158:161], v158 offset:3072
	ds_read_b128 v[164:167], v179
	ds_read_b128 v[180:183], v179 offset:1024
	ds_read_b128 v[184:187], v179 offset:2048
	ds_read_b128 v[188:191], v179 offset:3072
	s_add_u32 s46, s46, 0x20000
	s_addc_u32 s47, s47, 0
	s_mov_b32 m0, s26
	v_lshl_add_u64 v[228:229], s[46:47], 0, v[138:139]
	ds_read_b128 v[192:195], v157 offset:32768
	ds_read_b128 v[196:199], v157 offset:33792
	ds_read_b128 v[200:203], v157 offset:34816
	ds_read_b128 v[204:207], v157 offset:35840
	ds_read_b128 v[208:211], v157 offset:36864
	ds_read_b128 v[212:215], v157 offset:37888
	ds_read_b128 v[216:219], v157 offset:38912
	ds_read_b128 v[220:223], v157 offset:39936
	global_load_lds_dwordx4 v[228:229], off
	v_lshl_add_u64 v[228:229], s[46:47], 0, v[140:141]
	s_mov_b32 m0, s27
	s_nop 0
	global_load_lds_dwordx4 v[228:229], off
	s_waitcnt vmcnt(8)
	s_waitcnt lgkmcnt(0)
	s_barrier
	s_setprio 1
	s_waitcnt lgkmcnt(0)
	v_mfma_f32_16x16x32_bf16 v[126:129], v[130:133], v[192:195], v[126:129]
	v_mfma_f32_16x16x32_bf16 v[122:125], v[150:153], v[192:195], v[122:125]
	v_mfma_f32_16x16x32_bf16 v[110:113], v[130:133], v[200:203], v[110:113]
	v_mfma_f32_16x16x32_bf16 v[106:109], v[150:153], v[200:203], v[106:109]
	v_mfma_f32_16x16x32_bf16 v[94:97], v[130:133], v[208:211], v[94:97]
	v_mfma_f32_16x16x32_bf16 v[90:93], v[150:153], v[208:211], v[90:93]
	v_mfma_f32_16x16x32_bf16 v[78:81], v[130:133], v[216:219], v[78:81]
	v_mfma_f32_16x16x32_bf16 v[74:77], v[150:153], v[216:219], v[74:77]
	v_mfma_f32_16x16x32_bf16 v[126:129], v[134:137], v[196:199], v[126:129]
	v_mfma_f32_16x16x32_bf16 v[122:125], v[158:161], v[196:199], v[122:125]
	v_mfma_f32_16x16x32_bf16 v[110:113], v[134:137], v[204:207], v[110:113]
	v_mfma_f32_16x16x32_bf16 v[106:109], v[158:161], v[204:207], v[106:109]
	v_mfma_f32_16x16x32_bf16 v[94:97], v[134:137], v[212:215], v[94:97]
	v_mfma_f32_16x16x32_bf16 v[90:93], v[158:161], v[212:215], v[90:93]
	v_mfma_f32_16x16x32_bf16 v[78:81], v[134:137], v[220:223], v[78:81]
	v_mfma_f32_16x16x32_bf16 v[74:77], v[158:161], v[220:223], v[74:77]
	s_setprio 0
	s_setprio 1
	v_mfma_f32_16x16x32_bf16 v[118:121], v[164:167], v[192:195], v[118:121]
	v_mfma_f32_16x16x32_bf16 v[114:117], v[184:187], v[192:195], v[114:117]
	v_mfma_f32_16x16x32_bf16 v[102:105], v[164:167], v[200:203], v[102:105]
	v_mfma_f32_16x16x32_bf16 v[98:101], v[184:187], v[200:203], v[98:101]
	v_mfma_f32_16x16x32_bf16 v[86:89], v[164:167], v[208:211], v[86:89]
	v_mfma_f32_16x16x32_bf16 v[82:85], v[184:187], v[208:211], v[82:85]
	v_mfma_f32_16x16x32_bf16 v[70:73], v[164:167], v[216:219], v[70:73]
	v_mfma_f32_16x16x32_bf16 v[66:69], v[184:187], v[216:219], v[66:69]
	v_mfma_f32_16x16x32_bf16 v[118:121], v[180:183], v[196:199], v[118:121]
	v_mfma_f32_16x16x32_bf16 v[114:117], v[188:191], v[196:199], v[114:117]
	v_mfma_f32_16x16x32_bf16 v[102:105], v[180:183], v[204:207], v[102:105]
	v_mfma_f32_16x16x32_bf16 v[98:101], v[188:191], v[204:207], v[98:101]
	s_setprio 2
	s_barrier
	v_mfma_f32_16x16x32_bf16 v[86:89], v[180:183], v[212:215], v[86:89]
	v_mfma_f32_16x16x32_bf16 v[82:85], v[188:191], v[212:215], v[82:85]
	v_mfma_f32_16x16x32_bf16 v[70:73], v[180:183], v[220:223], v[70:73]
	v_mfma_f32_16x16x32_bf16 v[66:69], v[188:191], v[220:223], v[66:69]
	s_setprio 0
	s_add_i32 s46, s52, s9
	v_lshl_add_u64 v[154:155], v[154:155], 0, s[6:7]
	s_mov_b32 m0, s46
	ds_read_b128 v[192:195], v157 offset:49152
	ds_read_b128 v[196:199], v157 offset:50176
	ds_read_b128 v[200:203], v157 offset:51200
	ds_read_b128 v[204:207], v157 offset:52224
	ds_read_b128 v[208:211], v157 offset:53248
	ds_read_b128 v[212:215], v157 offset:54272
	ds_read_b128 v[216:219], v157 offset:55296
	ds_read_b128 v[220:223], v157 offset:56320
	global_load_lds_dwordx4 v[154:155], off
	s_add_i32 m0, s46, 0x2000
	s_add_u32 s44, s44, 0x20080
	v_lshl_add_u64 v[154:155], v[168:169], 0, s[6:7]
	s_addc_u32 s45, s45, 0
	s_add_i32 s46, s53, s9
	global_load_lds_dwordx4 v[154:155], off
	v_lshl_add_u64 v[154:155], s[44:45], 0, v[162:163]
	s_mov_b32 m0, s46
	s_nop 0
	global_load_lds_dwordx4 v[154:155], off
	v_lshl_add_u64 v[154:155], s[44:45], 0, v[142:143]
	s_add_i32 m0, s46, 0x2000
	s_nop 0
	global_load_lds_dwordx4 v[154:155], off
	v_lshl_add_u64 v[154:155], v[224:225], 0, s[6:7]
	s_mov_b32 m0, s41
	s_nop 0
	global_load_lds_dwordx4 v[154:155], off
	v_lshl_add_u64 v[154:155], v[226:227], 0, s[6:7]
	s_mov_b32 m0, s48
	s_nop 0
	global_load_lds_dwordx4 v[154:155], off
	s_waitcnt vmcnt(8)
	s_waitcnt lgkmcnt(0)
	s_barrier
	s_setprio 1
	s_waitcnt lgkmcnt(0)
	v_mfma_f32_16x16x32_bf16 v[62:65], v[130:133], v[192:195], v[62:65]
	v_mfma_f32_16x16x32_bf16 v[58:61], v[150:153], v[192:195], v[58:61]
	v_mfma_f32_16x16x32_bf16 v[46:49], v[130:133], v[200:203], v[46:49]
	v_mfma_f32_16x16x32_bf16 v[42:45], v[150:153], v[200:203], v[42:45]
	v_mfma_f32_16x16x32_bf16 v[30:33], v[130:133], v[208:211], v[30:33]
	v_mfma_f32_16x16x32_bf16 v[26:29], v[150:153], v[208:211], v[26:29]
	v_mfma_f32_16x16x32_bf16 v[14:17], v[130:133], v[216:219], v[14:17]
	v_mfma_f32_16x16x32_bf16 v[10:13], v[150:153], v[216:219], v[10:13]
	v_mfma_f32_16x16x32_bf16 v[62:65], v[134:137], v[196:199], v[62:65]
	v_mfma_f32_16x16x32_bf16 v[58:61], v[158:161], v[196:199], v[58:61]
	v_mfma_f32_16x16x32_bf16 v[46:49], v[134:137], v[204:207], v[46:49]
	v_mfma_f32_16x16x32_bf16 v[42:45], v[158:161], v[204:207], v[42:45]
	v_mfma_f32_16x16x32_bf16 v[30:33], v[134:137], v[212:215], v[30:33]
	v_mfma_f32_16x16x32_bf16 v[26:29], v[158:161], v[212:215], v[26:29]
	v_mfma_f32_16x16x32_bf16 v[14:17], v[134:137], v[220:223], v[14:17]
	v_mfma_f32_16x16x32_bf16 v[10:13], v[158:161], v[220:223], v[10:13]
	s_setprio 0
	s_setprio 1
	v_mfma_f32_16x16x32_bf16 v[54:57], v[164:167], v[192:195], v[54:57]
	v_mfma_f32_16x16x32_bf16 v[50:53], v[184:187], v[192:195], v[50:53]
	v_mfma_f32_16x16x32_bf16 v[38:41], v[164:167], v[200:203], v[38:41]
	v_mfma_f32_16x16x32_bf16 v[34:37], v[184:187], v[200:203], v[34:37]
	v_mfma_f32_16x16x32_bf16 v[22:25], v[164:167], v[208:211], v[22:25]
	v_mfma_f32_16x16x32_bf16 v[18:21], v[184:187], v[208:211], v[18:21]
	v_mfma_f32_16x16x32_bf16 v[6:9], v[164:167], v[216:219], v[6:9]
	v_mfma_f32_16x16x32_bf16 v[2:5], v[184:187], v[216:219], v[2:5]
	v_mfma_f32_16x16x32_bf16 v[54:57], v[180:183], v[196:199], v[54:57]
	v_mfma_f32_16x16x32_bf16 v[50:53], v[188:191], v[196:199], v[50:53]
	v_mfma_f32_16x16x32_bf16 v[38:41], v[180:183], v[204:207], v[38:41]
	v_mfma_f32_16x16x32_bf16 v[34:37], v[188:191], v[204:207], v[34:37]
	s_setprio 2
	s_barrier
	v_mfma_f32_16x16x32_bf16 v[22:25], v[180:183], v[212:215], v[22:25]
	v_mfma_f32_16x16x32_bf16 v[18:21], v[188:191], v[212:215], v[18:21]
	v_mfma_f32_16x16x32_bf16 v[6:9], v[180:183], v[220:223], v[6:9]
	v_mfma_f32_16x16x32_bf16 v[2:5], v[188:191], v[220:223], v[2:5]
	s_setprio 0
	s_add_i32 s51, s51, 2
	s_add_u32 s42, s42, 0x100
	s_addc_u32 s43, s43, 0
	s_add_u32 s39, s39, 0x100
	s_addc_u32 s50, s50, 0
	s_cmp_gt_u32 s51, 5
	s_cbranch_scc0 .LBB0_1621
	s_and_b64 vcc, exec, s[2:3]
	s_cbranch_vccz .LBB0_1624
	s_barrier

.LBB0_1797:
	s_ashr_i32 s19, s18, 31
	s_lshl_b64 s[20:21], s[18:19], 20
	v_readlane_b32 s5, v243, 17
	s_add_u32 s28, s5, s20
	v_readlane_b32 s5, v243, 18
	s_addc_u32 s29, s5, s21
	s_and_b64 s[20:21], s[34:35], exec
	s_cselect_b32 s11, s29, s23
	s_cselect_b32 s13, s28, s22
	s_ashr_i32 s5, s4, 31
	s_lshl_b64 s[20:21], s[4:5], 20
	s_add_u32 s38, s25, s20
	s_addc_u32 s39, s27, s21
	s_and_b64 s[20:21], s[34:35], exec
	s_cselect_b32 s5, s39, s41
	s_cselect_b32 s19, s38, s40
	s_add_u32 s22, s22, 0x80080
	s_addc_u32 s23, s23, 0
	s_add_u32 s20, s40, 0x100
	s_addc_u32 s21, s41, 0
	s_mov_b32 s26, -2
	s_add_u32 s40, s22, 0xfff80080
	s_addc_u32 s41, s23, -1
	s_add_i32 s52, 0, 0x10000
	s_cmp_eq_u32 s26, 28
	s_cselect_b32 s43, s11, s41
	s_cselect_b32 s42, s13, s40
	v_add_u32_e32 v147, s52, v141
	s_cselect_b32 s41, s5, s21
	s_cselect_b32 s40, s19, s20
	s_add_i32 s54, 0, 0x14000
	ds_read_b128 v[152:155], v147
	ds_read_b128 v[164:167], v147 offset:1024
	ds_read_b128 v[180:183], v147 offset:2048
	ds_read_b128 v[184:187], v147 offset:3072
	v_add_u32_e32 v147, s54, v141
	ds_read_b128 v[188:191], v147
	ds_read_b128 v[192:195], v147 offset:1024
	ds_read_b128 v[196:199], v147 offset:2048
	ds_read_b128 v[200:203], v147 offset:3072
	v_lshl_add_u64 v[160:161], s[22:23], 0, v[136:137]
	s_add_i32 m0, s45, 0xc000
	ds_read_b128 v[204:207], v145
	ds_read_b128 v[208:211], v145 offset:1024
	ds_read_b128 v[212:215], v145 offset:2048
	ds_read_b128 v[216:219], v145 offset:3072
	ds_read_b128 v[220:223], v145 offset:4096
	ds_read_b128 v[224:227], v145 offset:5120
	ds_read_b128 v[228:231], v145 offset:6144
	ds_read_b128 v[232:235], v145 offset:7168
	global_load_lds_dwordx4 v[160:161], off
	v_lshl_add_u64 v[160:161], s[22:23], 0, v[138:139]
	s_add_i32 m0, s45, 0xe000
	s_nop 0
	global_load_lds_dwordx4 v[160:161], off
	s_nop 0
	s_waitcnt lgkmcnt(0)
	s_barrier
	s_setprio 1
	s_waitcnt lgkmcnt(0)
	v_mfma_f32_16x16x32_bf16 v[126:129], v[152:155], v[204:207], 0
	v_mfma_f32_16x16x32_bf16 v[122:125], v[180:183], v[204:207], 0
	v_mfma_f32_16x16x32_bf16 v[110:113], v[152:155], v[212:215], 0
	v_mfma_f32_16x16x32_bf16 v[106:109], v[180:183], v[212:215], 0
	v_mfma_f32_16x16x32_bf16 v[94:97], v[152:155], v[220:223], 0
	v_mfma_f32_16x16x32_bf16 v[90:93], v[180:183], v[220:223], 0
	v_mfma_f32_16x16x32_bf16 v[78:81], v[152:155], v[228:231], 0
	v_mfma_f32_16x16x32_bf16 v[74:77], v[180:183], v[228:231], 0
	v_mfma_f32_16x16x32_bf16 v[126:129], v[164:167], v[208:211], v[126:129]
	v_mfma_f32_16x16x32_bf16 v[122:125], v[184:187], v[208:211], v[122:125]
	v_mfma_f32_16x16x32_bf16 v[110:113], v[164:167], v[216:219], v[110:113]
	v_mfma_f32_16x16x32_bf16 v[106:109], v[184:187], v[216:219], v[106:109]
	v_mfma_f32_16x16x32_bf16 v[94:97], v[164:167], v[224:227], v[94:97]
	v_mfma_f32_16x16x32_bf16 v[90:93], v[184:187], v[224:227], v[90:93]
	v_mfma_f32_16x16x32_bf16 v[78:81], v[164:167], v[232:235], v[78:81]
	v_mfma_f32_16x16x32_bf16 v[74:77], v[184:187], v[232:235], v[74:77]
	s_setprio 0
	s_setprio 1
	v_mfma_f32_16x16x32_bf16 v[118:121], v[188:191], v[204:207], 0
	v_mfma_f32_16x16x32_bf16 v[114:117], v[196:199], v[204:207], 0
	v_mfma_f32_16x16x32_bf16 v[102:105], v[188:191], v[212:215], 0
	v_mfma_f32_16x16x32_bf16 v[98:101], v[196:199], v[212:215], 0
	v_mfma_f32_16x16x32_bf16 v[86:89], v[188:191], v[220:223], 0
	v_mfma_f32_16x16x32_bf16 v[82:85], v[196:199], v[220:223], 0
	v_mfma_f32_16x16x32_bf16 v[70:73], v[188:191], v[228:231], 0
	v_mfma_f32_16x16x32_bf16 v[66:69], v[196:199], v[228:231], 0
	v_mfma_f32_16x16x32_bf16 v[118:121], v[192:195], v[208:211], v[118:121]
	v_mfma_f32_16x16x32_bf16 v[114:117], v[200:203], v[208:211], v[114:117]
	v_mfma_f32_16x16x32_bf16 v[102:105], v[192:195], v[216:219], v[102:105]
	v_mfma_f32_16x16x32_bf16 v[98:101], v[200:203], v[216:219], v[98:101]
	s_setprio 2
	s_barrier
	v_mfma_f32_16x16x32_bf16 v[86:89], v[192:195], v[224:227], v[86:89]
	v_mfma_f32_16x16x32_bf16 v[82:85], v[200:203], v[224:227], v[82:85]
	v_mfma_f32_16x16x32_bf16 v[70:73], v[192:195], v[232:235], v[70:73]
	v_mfma_f32_16x16x32_bf16 v[66:69], v[200:203], v[232:235], v[66:69]
	s_setprio 0
	s_add_i32 s52, s52, s44
	v_lshl_add_u64 v[160:161], s[40:41], 0, v[162:163]
	s_mov_b32 m0, s52
	ds_read_b128 v[204:207], v145 offset:16384
	ds_read_b128 v[208:211], v145 offset:17408
	ds_read_b128 v[212:215], v145 offset:18432
	ds_read_b128 v[216:219], v145 offset:19456
	ds_read_b128 v[220:223], v145 offset:20480
	ds_read_b128 v[224:227], v145 offset:21504
	ds_read_b128 v[228:231], v145 offset:22528
	ds_read_b128 v[232:235], v145 offset:23552
	global_load_lds_dwordx4 v[160:161], off
	s_add_i32 m0, s52, 0x2000
	s_add_u32 s52, s40, 0x80000
	v_lshl_add_u64 v[168:169], s[40:41], 0, v[130:131]
	s_addc_u32 s53, s41, 0
	s_add_i32 s54, s54, s44
	global_load_lds_dwordx4 v[168:169], off
	v_lshl_add_u64 v[236:237], s[52:53], 0, v[162:163]
	s_mov_b32 m0, s54
	v_lshl_add_u64 v[238:239], s[42:43], 0, v[132:133]
	global_load_lds_dwordx4 v[236:237], off
	v_lshl_add_u64 v[236:237], s[52:53], 0, v[130:131]
	s_add_i32 m0, s54, 0x2000
	s_nop 0
	global_load_lds_dwordx4 v[236:237], off
	v_lshl_add_u64 v[236:237], s[42:43], 0, v[134:135]
	s_mov_b32 m0, s45
	s_nop 0
	global_load_lds_dwordx4 v[236:237], off
	s_mov_b32 m0, s46
	s_nop 0
	global_load_lds_dwordx4 v[238:239], off
	s_cmp_eq_u32 s51, 1
	s_cbranch_scc0 .Lg5_later_tile
	s_waitcnt vmcnt(8)
.Lg5_later_tile:
	s_waitcnt lgkmcnt(0)
	s_barrier
	s_setprio 1
	s_waitcnt lgkmcnt(0)
	v_mfma_f32_16x16x32_bf16 v[62:65], v[152:155], v[204:207], 0
	v_mfma_f32_16x16x32_bf16 v[58:61], v[180:183], v[204:207], 0
	v_mfma_f32_16x16x32_bf16 v[46:49], v[152:155], v[212:215], 0
	v_mfma_f32_16x16x32_bf16 v[42:45], v[180:183], v[212:215], 0
	v_mfma_f32_16x16x32_bf16 v[30:33], v[152:155], v[220:223], 0
	v_mfma_f32_16x16x32_bf16 v[26:29], v[180:183], v[220:223], 0
	v_mfma_f32_16x16x32_bf16 v[14:17], v[152:155], v[228:231], 0
	v_mfma_f32_16x16x32_bf16 v[10:13], v[180:183], v[228:231], 0
	v_mfma_f32_16x16x32_bf16 v[62:65], v[164:167], v[208:211], v[62:65]
	v_mfma_f32_16x16x32_bf16 v[58:61], v[184:187], v[208:211], v[58:61]
	v_mfma_f32_16x16x32_bf16 v[46:49], v[164:167], v[216:219], v[46:49]
	v_mfma_f32_16x16x32_bf16 v[42:45], v[184:187], v[216:219], v[42:45]
	v_mfma_f32_16x16x32_bf16 v[30:33], v[164:167], v[224:227], v[30:33]
	v_mfma_f32_16x16x32_bf16 v[26:29], v[184:187], v[224:227], v[26:29]
	v_mfma_f32_16x16x32_bf16 v[14:17], v[164:167], v[232:235], v[14:17]
	v_mfma_f32_16x16x32_bf16 v[10:13], v[184:187], v[232:235], v[10:13]
	s_setprio 0
	s_setprio 1
	v_mfma_f32_16x16x32_bf16 v[54:57], v[188:191], v[204:207], 0
	v_mfma_f32_16x16x32_bf16 v[50:53], v[196:199], v[204:207], 0
	v_mfma_f32_16x16x32_bf16 v[38:41], v[188:191], v[212:215], 0
	v_mfma_f32_16x16x32_bf16 v[34:37], v[196:199], v[212:215], 0
	v_mfma_f32_16x16x32_bf16 v[22:25], v[188:191], v[220:223], 0
	v_mfma_f32_16x16x32_bf16 v[18:21], v[196:199], v[220:223], 0
	v_mfma_f32_16x16x32_bf16 v[6:9], v[188:191], v[228:231], 0
	v_mfma_f32_16x16x32_bf16 v[2:5], v[196:199], v[228:231], 0
	v_mfma_f32_16x16x32_bf16 v[54:57], v[192:195], v[208:211], v[54:57]
	v_mfma_f32_16x16x32_bf16 v[50:53], v[200:203], v[208:211], v[50:53]
	v_mfma_f32_16x16x32_bf16 v[38:41], v[192:195], v[216:219], v[38:41]
	v_mfma_f32_16x16x32_bf16 v[34:37], v[200:203], v[216:219], v[34:37]
	s_setprio 2
	s_barrier
	v_mfma_f32_16x16x32_bf16 v[22:25], v[192:195], v[224:227], v[22:25]
	v_mfma_f32_16x16x32_bf16 v[18:21], v[200:203], v[224:227], v[18:21]
	v_mfma_f32_16x16x32_bf16 v[6:9], v[192:195], v[232:235], v[6:9]
	v_mfma_f32_16x16x32_bf16 v[2:5], v[200:203], v[232:235], v[2:5]
	s_setprio 0
	s_add_i32 s52, 0, 0x18000
	v_add_u32_e32 v147, s52, v141
	s_add_i32 s53, 0, 0x1c000
	ds_read_b128 v[152:155], v147
	ds_read_b128 v[164:167], v147 offset:1024
	ds_read_b128 v[180:183], v147 offset:2048
	ds_read_b128 v[184:187], v147 offset:3072
	v_add_u32_e32 v147, s53, v141
	ds_read_b128 v[188:191], v147
	ds_read_b128 v[192:195], v147 offset:1024
	ds_read_b128 v[196:199], v147 offset:2048
	ds_read_b128 v[200:203], v147 offset:3072
	s_add_u32 s42, s42, 0x80000
	s_addc_u32 s43, s43, 0
	s_mov_b32 m0, s47
	v_lshl_add_u64 v[240:241], s[42:43], 0, v[134:135]
	ds_read_b128 v[204:207], v145 offset:32768
	ds_read_b128 v[208:211], v145 offset:33792
	ds_read_b128 v[212:215], v145 offset:34816
	ds_read_b128 v[216:219], v145 offset:35840
	ds_read_b128 v[220:223], v145 offset:36864
	ds_read_b128 v[224:227], v145 offset:37888
	ds_read_b128 v[228:231], v145 offset:38912
	ds_read_b128 v[232:235], v145 offset:39936
	global_load_lds_dwordx4 v[240:241], off
	v_lshl_add_u64 v[240:241], s[42:43], 0, v[132:133]
	s_mov_b32 m0, s48
	s_nop 0
	global_load_lds_dwordx4 v[240:241], off
	s_waitcnt vmcnt(8)
	s_waitcnt lgkmcnt(0)
	s_barrier
	s_setprio 1
	s_waitcnt lgkmcnt(0)
	v_mfma_f32_16x16x32_bf16 v[126:129], v[152:155], v[204:207], v[126:129]
	v_mfma_f32_16x16x32_bf16 v[122:125], v[180:183], v[204:207], v[122:125]
	v_mfma_f32_16x16x32_bf16 v[110:113], v[152:155], v[212:215], v[110:113]
	v_mfma_f32_16x16x32_bf16 v[106:109], v[180:183], v[212:215], v[106:109]
	v_mfma_f32_16x16x32_bf16 v[94:97], v[152:155], v[220:223], v[94:97]
	v_mfma_f32_16x16x32_bf16 v[90:93], v[180:183], v[220:223], v[90:93]
	v_mfma_f32_16x16x32_bf16 v[78:81], v[152:155], v[228:231], v[78:81]
	v_mfma_f32_16x16x32_bf16 v[74:77], v[180:183], v[228:231], v[74:77]
	v_mfma_f32_16x16x32_bf16 v[126:129], v[164:167], v[208:211], v[126:129]
	v_mfma_f32_16x16x32_bf16 v[122:125], v[184:187], v[208:211], v[122:125]
	v_mfma_f32_16x16x32_bf16 v[110:113], v[164:167], v[216:219], v[110:113]
	v_mfma_f32_16x16x32_bf16 v[106:109], v[184:187], v[216:219], v[106:109]
	v_mfma_f32_16x16x32_bf16 v[94:97], v[164:167], v[224:227], v[94:97]
	v_mfma_f32_16x16x32_bf16 v[90:93], v[184:187], v[224:227], v[90:93]
	v_mfma_f32_16x16x32_bf16 v[78:81], v[164:167], v[232:235], v[78:81]
	v_mfma_f32_16x16x32_bf16 v[74:77], v[184:187], v[232:235], v[74:77]
	s_setprio 0
	s_setprio 1
	v_mfma_f32_16x16x32_bf16 v[118:121], v[188:191], v[204:207], v[118:121]
	v_mfma_f32_16x16x32_bf16 v[114:117], v[196:199], v[204:207], v[114:117]
	v_mfma_f32_16x16x32_bf16 v[102:105], v[188:191], v[212:215], v[102:105]
	v_mfma_f32_16x16x32_bf16 v[98:101], v[196:199], v[212:215], v[98:101]
	v_mfma_f32_16x16x32_bf16 v[86:89], v[188:191], v[220:223], v[86:89]
	v_mfma_f32_16x16x32_bf16 v[82:85], v[196:199], v[220:223], v[82:85]
	v_mfma_f32_16x16x32_bf16 v[70:73], v[188:191], v[228:231], v[70:73]
	v_mfma_f32_16x16x32_bf16 v[66:69], v[196:199], v[228:231], v[66:69]
	v_mfma_f32_16x16x32_bf16 v[118:121], v[192:195], v[208:211], v[118:121]
	v_mfma_f32_16x16x32_bf16 v[114:117], v[200:203], v[208:211], v[114:117]
	v_mfma_f32_16x16x32_bf16 v[102:105], v[192:195], v[216:219], v[102:105]
	v_mfma_f32_16x16x32_bf16 v[98:101], v[200:203], v[216:219], v[98:101]
	s_setprio 2
	s_barrier
	v_mfma_f32_16x16x32_bf16 v[86:89], v[192:195], v[224:227], v[86:89]
	v_mfma_f32_16x16x32_bf16 v[82:85], v[200:203], v[224:227], v[82:85]
	v_mfma_f32_16x16x32_bf16 v[70:73], v[192:195], v[232:235], v[70:73]
	v_mfma_f32_16x16x32_bf16 v[66:69], v[200:203], v[232:235], v[66:69]
	s_setprio 0
	s_add_i32 s42, s52, s44
	v_lshl_add_u64 v[160:161], v[160:161], 0, s[6:7]
	s_mov_b32 m0, s42
	ds_read_b128 v[204:207], v145 offset:49152
	ds_read_b128 v[208:211], v145 offset:50176
	ds_read_b128 v[212:215], v145 offset:51200
	ds_read_b128 v[216:219], v145 offset:52224
	ds_read_b128 v[220:223], v145 offset:53248
	ds_read_b128 v[224:227], v145 offset:54272
	ds_read_b128 v[228:231], v145 offset:55296
	ds_read_b128 v[232:235], v145 offset:56320
	global_load_lds_dwordx4 v[160:161], off
	s_add_i32 m0, s42, 0x2000
	s_add_u32 s40, s40, 0x80080
	v_lshl_add_u64 v[160:161], v[168:169], 0, s[6:7]
	s_addc_u32 s41, s41, 0
	s_add_i32 s42, s53, s44
	global_load_lds_dwordx4 v[160:161], off
	v_lshl_add_u64 v[160:161], s[40:41], 0, v[162:163]
	s_mov_b32 m0, s42
	s_nop 0
	global_load_lds_dwordx4 v[160:161], off
	v_lshl_add_u64 v[160:161], s[40:41], 0, v[130:131]
	s_add_i32 m0, s42, 0x2000
	s_nop 0
	global_load_lds_dwordx4 v[160:161], off
	v_lshl_add_u64 v[160:161], v[236:237], 0, s[6:7]
	s_mov_b32 m0, s49
	s_nop 0
	global_load_lds_dwordx4 v[160:161], off
	v_lshl_add_u64 v[160:161], v[238:239], 0, s[6:7]
	s_mov_b32 m0, s50
	s_nop 0
	global_load_lds_dwordx4 v[160:161], off
	s_waitcnt vmcnt(8)
	s_waitcnt lgkmcnt(0)
	s_barrier
	s_setprio 1
	s_waitcnt lgkmcnt(0)
	v_mfma_f32_16x16x32_bf16 v[62:65], v[152:155], v[204:207], v[62:65]
	v_mfma_f32_16x16x32_bf16 v[58:61], v[180:183], v[204:207], v[58:61]
	v_mfma_f32_16x16x32_bf16 v[46:49], v[152:155], v[212:215], v[46:49]
	v_mfma_f32_16x16x32_bf16 v[42:45], v[180:183], v[212:215], v[42:45]
	v_mfma_f32_16x16x32_bf16 v[30:33], v[152:155], v[220:223], v[30:33]
	v_mfma_f32_16x16x32_bf16 v[26:29], v[180:183], v[220:223], v[26:29]
	v_mfma_f32_16x16x32_bf16 v[14:17], v[152:155], v[228:231], v[14:17]
	v_mfma_f32_16x16x32_bf16 v[10:13], v[180:183], v[228:231], v[10:13]
	v_mfma_f32_16x16x32_bf16 v[62:65], v[164:167], v[208:211], v[62:65]
	v_mfma_f32_16x16x32_bf16 v[58:61], v[184:187], v[208:211], v[58:61]
	v_mfma_f32_16x16x32_bf16 v[46:49], v[164:167], v[216:219], v[46:49]
	v_mfma_f32_16x16x32_bf16 v[42:45], v[184:187], v[216:219], v[42:45]
	v_mfma_f32_16x16x32_bf16 v[30:33], v[164:167], v[224:227], v[30:33]
	v_mfma_f32_16x16x32_bf16 v[26:29], v[184:187], v[224:227], v[26:29]
	v_mfma_f32_16x16x32_bf16 v[14:17], v[164:167], v[232:235], v[14:17]
	v_mfma_f32_16x16x32_bf16 v[10:13], v[184:187], v[232:235], v[10:13]
	s_setprio 0
	s_setprio 1
	v_mfma_f32_16x16x32_bf16 v[54:57], v[188:191], v[204:207], v[54:57]
	v_mfma_f32_16x16x32_bf16 v[50:53], v[196:199], v[204:207], v[50:53]
	v_mfma_f32_16x16x32_bf16 v[38:41], v[188:191], v[212:215], v[38:41]
	v_mfma_f32_16x16x32_bf16 v[34:37], v[196:199], v[212:215], v[34:37]
	v_mfma_f32_16x16x32_bf16 v[22:25], v[188:191], v[220:223], v[22:25]
	v_mfma_f32_16x16x32_bf16 v[18:21], v[196:199], v[220:223], v[18:21]
	v_mfma_f32_16x16x32_bf16 v[6:9], v[188:191], v[228:231], v[6:9]
	v_mfma_f32_16x16x32_bf16 v[2:5], v[196:199], v[228:231], v[2:5]
	v_mfma_f32_16x16x32_bf16 v[54:57], v[192:195], v[208:211], v[54:57]
	v_mfma_f32_16x16x32_bf16 v[50:53], v[200:203], v[208:211], v[50:53]
	v_mfma_f32_16x16x32_bf16 v[38:41], v[192:195], v[216:219], v[38:41]
	v_mfma_f32_16x16x32_bf16 v[34:37], v[200:203], v[216:219], v[34:37]
	s_setprio 2
	s_barrier
	v_mfma_f32_16x16x32_bf16 v[22:25], v[192:195], v[224:227], v[22:25]
	v_mfma_f32_16x16x32_bf16 v[18:21], v[200:203], v[224:227], v[18:21]
	v_mfma_f32_16x16x32_bf16 v[6:9], v[192:195], v[232:235], v[6:9]
	v_mfma_f32_16x16x32_bf16 v[2:5], v[200:203], v[232:235], v[2:5]
	s_setprio 0
	s_add_i32 s26, s26, 2
	s_add_u32 s22, s22, 0x100
	s_addc_u32 s23, s23, 0
	s_add_u32 s20, s20, 0x100
	s_addc_u32 s21, s21, 0
	s_cmp_gt_u32 s26, 29
.LBB0_1798:
	s_add_u32 s40, s22, 0xfff80080
	s_addc_u32 s41, s23, -1
	s_add_i32 s52, 0, 0x10000
	s_cmp_eq_u32 s26, 28
	s_cselect_b32 s43, s11, s41
	s_cselect_b32 s42, s13, s40
	v_add_u32_e32 v147, s52, v141
	s_cselect_b32 s41, s5, s21
	s_cselect_b32 s40, s19, s20
	s_add_i32 s54, 0, 0x14000
	ds_read_b128 v[152:155], v147
	ds_read_b128 v[164:167], v147 offset:1024
	ds_read_b128 v[180:183], v147 offset:2048
	ds_read_b128 v[184:187], v147 offset:3072
	v_add_u32_e32 v147, s54, v141
	ds_read_b128 v[188:191], v147
	ds_read_b128 v[192:195], v147 offset:1024
	ds_read_b128 v[196:199], v147 offset:2048
	ds_read_b128 v[200:203], v147 offset:3072
	v_lshl_add_u64 v[160:161], s[22:23], 0, v[136:137]
	s_add_i32 m0, s45, 0xc000
	ds_read_b128 v[204:207], v145
	ds_read_b128 v[208:211], v145 offset:1024
	ds_read_b128 v[212:215], v145 offset:2048
	ds_read_b128 v[216:219], v145 offset:3072
	ds_read_b128 v[220:223], v145 offset:4096
	ds_read_b128 v[224:227], v145 offset:5120
	ds_read_b128 v[228:231], v145 offset:6144
	ds_read_b128 v[232:235], v145 offset:7168
	global_load_lds_dwordx4 v[160:161], off
	v_lshl_add_u64 v[160:161], s[22:23], 0, v[138:139]
	s_add_i32 m0, s45, 0xe000
	s_nop 0
	global_load_lds_dwordx4 v[160:161], off
	s_waitcnt vmcnt(8)
	s_waitcnt lgkmcnt(0)
	s_barrier
	s_setprio 1
	s_waitcnt lgkmcnt(0)
	v_mfma_f32_16x16x32_bf16 v[126:129], v[152:155], v[204:207], v[126:129]
	v_mfma_f32_16x16x32_bf16 v[122:125], v[180:183], v[204:207], v[122:125]
	v_mfma_f32_16x16x32_bf16 v[110:113], v[152:155], v[212:215], v[110:113]
	v_mfma_f32_16x16x32_bf16 v[106:109], v[180:183], v[212:215], v[106:109]
	v_mfma_f32_16x16x32_bf16 v[94:97], v[152:155], v[220:223], v[94:97]
	v_mfma_f32_16x16x32_bf16 v[90:93], v[180:183], v[220:223], v[90:93]
	v_mfma_f32_16x16x32_bf16 v[78:81], v[152:155], v[228:231], v[78:81]
	v_mfma_f32_16x16x32_bf16 v[74:77], v[180:183], v[228:231], v[74:77]
	v_mfma_f32_16x16x32_bf16 v[126:129], v[164:167], v[208:211], v[126:129]
	v_mfma_f32_16x16x32_bf16 v[122:125], v[184:187], v[208:211], v[122:125]
	v_mfma_f32_16x16x32_bf16 v[110:113], v[164:167], v[216:219], v[110:113]
	v_mfma_f32_16x16x32_bf16 v[106:109], v[184:187], v[216:219], v[106:109]
	v_mfma_f32_16x16x32_bf16 v[94:97], v[164:167], v[224:227], v[94:97]
	v_mfma_f32_16x16x32_bf16 v[90:93], v[184:187], v[224:227], v[90:93]
	v_mfma_f32_16x16x32_bf16 v[78:81], v[164:167], v[232:235], v[78:81]
	v_mfma_f32_16x16x32_bf16 v[74:77], v[184:187], v[232:235], v[74:77]
	s_setprio 0
	s_setprio 1
	v_mfma_f32_16x16x32_bf16 v[118:121], v[188:191], v[204:207], v[118:121]
	v_mfma_f32_16x16x32_bf16 v[114:117], v[196:199], v[204:207], v[114:117]
	v_mfma_f32_16x16x32_bf16 v[102:105], v[188:191], v[212:215], v[102:105]
	v_mfma_f32_16x16x32_bf16 v[98:101], v[196:199], v[212:215], v[98:101]
	v_mfma_f32_16x16x32_bf16 v[86:89], v[188:191], v[220:223], v[86:89]
	v_mfma_f32_16x16x32_bf16 v[82:85], v[196:199], v[220:223], v[82:85]
	v_mfma_f32_16x16x32_bf16 v[70:73], v[188:191], v[228:231], v[70:73]
	v_mfma_f32_16x16x32_bf16 v[66:69], v[196:199], v[228:231], v[66:69]
	v_mfma_f32_16x16x32_bf16 v[118:121], v[192:195], v[208:211], v[118:121]
	v_mfma_f32_16x16x32_bf16 v[114:117], v[200:203], v[208:211], v[114:117]
	v_mfma_f32_16x16x32_bf16 v[102:105], v[192:195], v[216:219], v[102:105]
	v_mfma_f32_16x16x32_bf16 v[98:101], v[200:203], v[216:219], v[98:101]
	s_setprio 2
	s_barrier
	v_mfma_f32_16x16x32_bf16 v[86:89], v[192:195], v[224:227], v[86:89]
	v_mfma_f32_16x16x32_bf16 v[82:85], v[200:203], v[224:227], v[82:85]
	v_mfma_f32_16x16x32_bf16 v[70:73], v[192:195], v[232:235], v[70:73]
	v_mfma_f32_16x16x32_bf16 v[66:69], v[200:203], v[232:235], v[66:69]
	s_setprio 0
	s_add_i32 s52, s52, s44
	v_lshl_add_u64 v[160:161], s[40:41], 0, v[162:163]
	s_mov_b32 m0, s52
	ds_read_b128 v[204:207], v145 offset:16384
	ds_read_b128 v[208:211], v145 offset:17408
	ds_read_b128 v[212:215], v145 offset:18432
	ds_read_b128 v[216:219], v145 offset:19456
	ds_read_b128 v[220:223], v145 offset:20480
	ds_read_b128 v[224:227], v145 offset:21504
	ds_read_b128 v[228:231], v145 offset:22528
	ds_read_b128 v[232:235], v145 offset:23552
	global_load_lds_dwordx4 v[160:161], off
	s_add_i32 m0, s52, 0x2000
	s_add_u32 s52, s40, 0x80000
	v_lshl_add_u64 v[168:169], s[40:41], 0, v[130:131]
	s_addc_u32 s53, s41, 0
	s_add_i32 s54, s54, s44
	global_load_lds_dwordx4 v[168:169], off
	v_lshl_add_u64 v[236:237], s[52:53], 0, v[162:163]
	s_mov_b32 m0, s54
	v_lshl_add_u64 v[238:239], s[42:43], 0, v[132:133]
	global_load_lds_dwordx4 v[236:237], off
	v_lshl_add_u64 v[236:237], s[52:53], 0, v[130:131]
	s_add_i32 m0, s54, 0x2000
	s_nop 0
	global_load_lds_dwordx4 v[236:237], off
	v_lshl_add_u64 v[236:237], s[42:43], 0, v[134:135]
	s_mov_b32 m0, s45
	s_nop 0
	global_load_lds_dwordx4 v[236:237], off
	s_mov_b32 m0, s46
	s_nop 0
	global_load_lds_dwordx4 v[238:239], off
	s_waitcnt vmcnt(8)
	s_waitcnt lgkmcnt(0)
	s_barrier
	s_setprio 1
	s_waitcnt lgkmcnt(0)
	v_mfma_f32_16x16x32_bf16 v[62:65], v[152:155], v[204:207], v[62:65]
	v_mfma_f32_16x16x32_bf16 v[58:61], v[180:183], v[204:207], v[58:61]
	v_mfma_f32_16x16x32_bf16 v[46:49], v[152:155], v[212:215], v[46:49]
	v_mfma_f32_16x16x32_bf16 v[42:45], v[180:183], v[212:215], v[42:45]
	v_mfma_f32_16x16x32_bf16 v[30:33], v[152:155], v[220:223], v[30:33]
	v_mfma_f32_16x16x32_bf16 v[26:29], v[180:183], v[220:223], v[26:29]
	v_mfma_f32_16x16x32_bf16 v[14:17], v[152:155], v[228:231], v[14:17]
	v_mfma_f32_16x16x32_bf16 v[10:13], v[180:183], v[228:231], v[10:13]
	v_mfma_f32_16x16x32_bf16 v[62:65], v[164:167], v[208:211], v[62:65]
	v_mfma_f32_16x16x32_bf16 v[58:61], v[184:187], v[208:211], v[58:61]
	v_mfma_f32_16x16x32_bf16 v[46:49], v[164:167], v[216:219], v[46:49]
	v_mfma_f32_16x16x32_bf16 v[42:45], v[184:187], v[216:219], v[42:45]
	v_mfma_f32_16x16x32_bf16 v[30:33], v[164:167], v[224:227], v[30:33]
	v_mfma_f32_16x16x32_bf16 v[26:29], v[184:187], v[224:227], v[26:29]
	v_mfma_f32_16x16x32_bf16 v[14:17], v[164:167], v[232:235], v[14:17]
	v_mfma_f32_16x16x32_bf16 v[10:13], v[184:187], v[232:235], v[10:13]
	s_setprio 0
	s_setprio 1
	v_mfma_f32_16x16x32_bf16 v[54:57], v[188:191], v[204:207], v[54:57]
	v_mfma_f32_16x16x32_bf16 v[50:53], v[196:199], v[204:207], v[50:53]
	v_mfma_f32_16x16x32_bf16 v[38:41], v[188:191], v[212:215], v[38:41]
	v_mfma_f32_16x16x32_bf16 v[34:37], v[196:199], v[212:215], v[34:37]
	v_mfma_f32_16x16x32_bf16 v[22:25], v[188:191], v[220:223], v[22:25]
	v_mfma_f32_16x16x32_bf16 v[18:21], v[196:199], v[220:223], v[18:21]
	v_mfma_f32_16x16x32_bf16 v[6:9], v[188:191], v[228:231], v[6:9]
	v_mfma_f32_16x16x32_bf16 v[2:5], v[196:199], v[228:231], v[2:5]
	v_mfma_f32_16x16x32_bf16 v[54:57], v[192:195], v[208:211], v[54:57]
	v_mfma_f32_16x16x32_bf16 v[50:53], v[200:203], v[208:211], v[50:53]
	v_mfma_f32_16x16x32_bf16 v[38:41], v[192:195], v[216:219], v[38:41]
	v_mfma_f32_16x16x32_bf16 v[34:37], v[200:203], v[216:219], v[34:37]
	s_setprio 2
	s_barrier
	v_mfma_f32_16x16x32_bf16 v[22:25], v[192:195], v[224:227], v[22:25]
	v_mfma_f32_16x16x32_bf16 v[18:21], v[200:203], v[224:227], v[18:21]
	v_mfma_f32_16x16x32_bf16 v[6:9], v[192:195], v[232:235], v[6:9]
	v_mfma_f32_16x16x32_bf16 v[2:5], v[200:203], v[232:235], v[2:5]
	s_setprio 0
	s_add_i32 s52, 0, 0x18000
	v_add_u32_e32 v147, s52, v141
	s_add_i32 s53, 0, 0x1c000
	ds_read_b128 v[152:155], v147
	ds_read_b128 v[164:167], v147 offset:1024
	ds_read_b128 v[180:183], v147 offset:2048
	ds_read_b128 v[184:187], v147 offset:3072
	v_add_u32_e32 v147, s53, v141
	ds_read_b128 v[188:191], v147
	ds_read_b128 v[192:195], v147 offset:1024
	ds_read_b128 v[196:199], v147 offset:2048
	ds_read_b128 v[200:203], v147 offset:3072
	s_add_u32 s42, s42, 0x80000
	s_addc_u32 s43, s43, 0
	s_mov_b32 m0, s47
	v_lshl_add_u64 v[240:241], s[42:43], 0, v[134:135]
	ds_read_b128 v[204:207], v145 offset:32768
	ds_read_b128 v[208:211], v145 offset:33792
	ds_read_b128 v[212:215], v145 offset:34816
	ds_read_b128 v[216:219], v145 offset:35840
	ds_read_b128 v[220:223], v145 offset:36864
	ds_read_b128 v[224:227], v145 offset:37888
	ds_read_b128 v[228:231], v145 offset:38912
	ds_read_b128 v[232:235], v145 offset:39936
	global_load_lds_dwordx4 v[240:241], off
	v_lshl_add_u64 v[240:241], s[42:43], 0, v[132:133]
	s_mov_b32 m0, s48
	s_nop 0
	global_load_lds_dwordx4 v[240:241], off
	s_waitcnt vmcnt(8)
	s_waitcnt lgkmcnt(0)
	s_barrier
	s_setprio 1
	s_waitcnt lgkmcnt(0)
	v_mfma_f32_16x16x32_bf16 v[126:129], v[152:155], v[204:207], v[126:129]
	v_mfma_f32_16x16x32_bf16 v[122:125], v[180:183], v[204:207], v[122:125]
	v_mfma_f32_16x16x32_bf16 v[110:113], v[152:155], v[212:215], v[110:113]
	v_mfma_f32_16x16x32_bf16 v[106:109], v[180:183], v[212:215], v[106:109]
	v_mfma_f32_16x16x32_bf16 v[94:97], v[152:155], v[220:223], v[94:97]
	v_mfma_f32_16x16x32_bf16 v[90:93], v[180:183], v[220:223], v[90:93]
	v_mfma_f32_16x16x32_bf16 v[78:81], v[152:155], v[228:231], v[78:81]
	v_mfma_f32_16x16x32_bf16 v[74:77], v[180:183], v[228:231], v[74:77]
	v_mfma_f32_16x16x32_bf16 v[126:129], v[164:167], v[208:211], v[126:129]
	v_mfma_f32_16x16x32_bf16 v[122:125], v[184:187], v[208:211], v[122:125]
	v_mfma_f32_16x16x32_bf16 v[110:113], v[164:167], v[216:219], v[110:113]
	v_mfma_f32_16x16x32_bf16 v[106:109], v[184:187], v[216:219], v[106:109]
	v_mfma_f32_16x16x32_bf16 v[94:97], v[164:167], v[224:227], v[94:97]
	v_mfma_f32_16x16x32_bf16 v[90:93], v[184:187], v[224:227], v[90:93]
	v_mfma_f32_16x16x32_bf16 v[78:81], v[164:167], v[232:235], v[78:81]
	v_mfma_f32_16x16x32_bf16 v[74:77], v[184:187], v[232:235], v[74:77]
	s_setprio 0
	s_setprio 1
	v_mfma_f32_16x16x32_bf16 v[118:121], v[188:191], v[204:207], v[118:121]
	v_mfma_f32_16x16x32_bf16 v[114:117], v[196:199], v[204:207], v[114:117]
	v_mfma_f32_16x16x32_bf16 v[102:105], v[188:191], v[212:215], v[102:105]
	v_mfma_f32_16x16x32_bf16 v[98:101], v[196:199], v[212:215], v[98:101]
	v_mfma_f32_16x16x32_bf16 v[86:89], v[188:191], v[220:223], v[86:89]
	v_mfma_f32_16x16x32_bf16 v[82:85], v[196:199], v[220:223], v[82:85]
	v_mfma_f32_16x16x32_bf16 v[70:73], v[188:191], v[228:231], v[70:73]
	v_mfma_f32_16x16x32_bf16 v[66:69], v[196:199], v[228:231], v[66:69]
	v_mfma_f32_16x16x32_bf16 v[118:121], v[192:195], v[208:211], v[118:121]
	v_mfma_f32_16x16x32_bf16 v[114:117], v[200:203], v[208:211], v[114:117]
	v_mfma_f32_16x16x32_bf16 v[102:105], v[192:195], v[216:219], v[102:105]
	v_mfma_f32_16x16x32_bf16 v[98:101], v[200:203], v[216:219], v[98:101]
	s_setprio 2
	s_barrier
	v_mfma_f32_16x16x32_bf16 v[86:89], v[192:195], v[224:227], v[86:89]
	v_mfma_f32_16x16x32_bf16 v[82:85], v[200:203], v[224:227], v[82:85]
	v_mfma_f32_16x16x32_bf16 v[70:73], v[192:195], v[232:235], v[70:73]
	v_mfma_f32_16x16x32_bf16 v[66:69], v[200:203], v[232:235], v[66:69]
	s_setprio 0
	s_add_i32 s42, s52, s44
	v_lshl_add_u64 v[160:161], v[160:161], 0, s[6:7]
	s_mov_b32 m0, s42
	ds_read_b128 v[204:207], v145 offset:49152
	ds_read_b128 v[208:211], v145 offset:50176
	ds_read_b128 v[212:215], v145 offset:51200
	ds_read_b128 v[216:219], v145 offset:52224
	ds_read_b128 v[220:223], v145 offset:53248
	ds_read_b128 v[224:227], v145 offset:54272
	ds_read_b128 v[228:231], v145 offset:55296
	ds_read_b128 v[232:235], v145 offset:56320
	global_load_lds_dwordx4 v[160:161], off
	s_add_i32 m0, s42, 0x2000
	s_add_u32 s40, s40, 0x80080
	v_lshl_add_u64 v[160:161], v[168:169], 0, s[6:7]
	s_addc_u32 s41, s41, 0
	s_add_i32 s42, s53, s44
	global_load_lds_dwordx4 v[160:161], off
	v_lshl_add_u64 v[160:161], s[40:41], 0, v[162:163]
	s_mov_b32 m0, s42
	s_nop 0
	global_load_lds_dwordx4 v[160:161], off
	v_lshl_add_u64 v[160:161], s[40:41], 0, v[130:131]
	s_add_i32 m0, s42, 0x2000
	s_nop 0
	global_load_lds_dwordx4 v[160:161], off
	v_lshl_add_u64 v[160:161], v[236:237], 0, s[6:7]
	s_mov_b32 m0, s49
	s_nop 0
	global_load_lds_dwordx4 v[160:161], off
	v_lshl_add_u64 v[160:161], v[238:239], 0, s[6:7]
	s_mov_b32 m0, s50
	s_nop 0
	global_load_lds_dwordx4 v[160:161], off
	s_waitcnt vmcnt(8)
	s_waitcnt lgkmcnt(0)
	s_barrier
	s_setprio 1
	s_waitcnt lgkmcnt(0)
	v_mfma_f32_16x16x32_bf16 v[62:65], v[152:155], v[204:207], v[62:65]
	v_mfma_f32_16x16x32_bf16 v[58:61], v[180:183], v[204:207], v[58:61]
	v_mfma_f32_16x16x32_bf16 v[46:49], v[152:155], v[212:215], v[46:49]
	v_mfma_f32_16x16x32_bf16 v[42:45], v[180:183], v[212:215], v[42:45]
	v_mfma_f32_16x16x32_bf16 v[30:33], v[152:155], v[220:223], v[30:33]
	v_mfma_f32_16x16x32_bf16 v[26:29], v[180:183], v[220:223], v[26:29]
	v_mfma_f32_16x16x32_bf16 v[14:17], v[152:155], v[228:231], v[14:17]
	v_mfma_f32_16x16x32_bf16 v[10:13], v[180:183], v[228:231], v[10:13]
	v_mfma_f32_16x16x32_bf16 v[62:65], v[164:167], v[208:211], v[62:65]
	v_mfma_f32_16x16x32_bf16 v[58:61], v[184:187], v[208:211], v[58:61]
	v_mfma_f32_16x16x32_bf16 v[46:49], v[164:167], v[216:219], v[46:49]
	v_mfma_f32_16x16x32_bf16 v[42:45], v[184:187], v[216:219], v[42:45]
	v_mfma_f32_16x16x32_bf16 v[30:33], v[164:167], v[224:227], v[30:33]
	v_mfma_f32_16x16x32_bf16 v[26:29], v[184:187], v[224:227], v[26:29]
	v_mfma_f32_16x16x32_bf16 v[14:17], v[164:167], v[232:235], v[14:17]
	v_mfma_f32_16x16x32_bf16 v[10:13], v[184:187], v[232:235], v[10:13]
	s_setprio 0
	s_setprio 1
	v_mfma_f32_16x16x32_bf16 v[54:57], v[188:191], v[204:207], v[54:57]
	v_mfma_f32_16x16x32_bf16 v[50:53], v[196:199], v[204:207], v[50:53]
	v_mfma_f32_16x16x32_bf16 v[38:41], v[188:191], v[212:215], v[38:41]
	v_mfma_f32_16x16x32_bf16 v[34:37], v[196:199], v[212:215], v[34:37]
	v_mfma_f32_16x16x32_bf16 v[22:25], v[188:191], v[220:223], v[22:25]
	v_mfma_f32_16x16x32_bf16 v[18:21], v[196:199], v[220:223], v[18:21]
	v_mfma_f32_16x16x32_bf16 v[6:9], v[188:191], v[228:231], v[6:9]
	v_mfma_f32_16x16x32_bf16 v[2:5], v[196:199], v[228:231], v[2:5]
	v_mfma_f32_16x16x32_bf16 v[54:57], v[192:195], v[208:211], v[54:57]
	v_mfma_f32_16x16x32_bf16 v[50:53], v[200:203], v[208:211], v[50:53]
	v_mfma_f32_16x16x32_bf16 v[38:41], v[192:195], v[216:219], v[38:41]
	v_mfma_f32_16x16x32_bf16 v[34:37], v[200:203], v[216:219], v[34:37]
	s_setprio 2
	s_barrier
	v_mfma_f32_16x16x32_bf16 v[22:25], v[192:195], v[224:227], v[22:25]
	v_mfma_f32_16x16x32_bf16 v[18:21], v[200:203], v[224:227], v[18:21]
	v_mfma_f32_16x16x32_bf16 v[6:9], v[192:195], v[232:235], v[6:9]
	v_mfma_f32_16x16x32_bf16 v[2:5], v[200:203], v[232:235], v[2:5]
	s_setprio 0
	s_add_i32 s26, s26, 2
	s_add_u32 s22, s22, 0x100
	s_addc_u32 s23, s23, 0
	s_add_u32 s20, s20, 0x100
	s_addc_u32 s21, s21, 0
	s_cmp_gt_u32 s26, 29
	s_cbranch_scc0 .LBB0_1798
	s_and_b64 vcc, exec, s[2:3]
	s_cbranch_vccz .LBB0_1801
	s_barrier

.LBB0_1873:
	s_add_u32 s45, s28, 0x100
	s_addc_u32 s46, s29, 0
	s_mov_b32 s47, -2
	s_waitcnt vmcnt(0) lgkmcnt(0)
	s_add_u32 s28, s22, 0x100
	s_addc_u32 s29, s23, 0
	s_add_i32 s48, 0, 0x10000
	s_cmpk_eq_i32 s47, 0x54
	s_cselect_b32 s39, s5, s29
	s_cselect_b32 s38, s4, s28
	v_add_u32_e32 v154, s48, v145
	s_cselect_b32 s35, s19, s46
	s_cselect_b32 s34, s18, s45
	s_add_i32 s49, 0, 0x14000
	ds_read_b128 v[130:133], v154
	ds_read_b128 v[134:137], v154 offset:1024
	ds_read_b128 v[150:153], v154 offset:2048
	ds_read_b128 v[158:161], v154 offset:3072
	v_add_u32_e32 v154, s49, v145
	ds_read_b128 v[164:167], v154
	ds_read_b128 v[180:183], v154 offset:1024
	ds_read_b128 v[184:187], v154 offset:2048
	ds_read_b128 v[188:191], v154 offset:3072
	v_lshl_add_u64 v[154:155], s[22:23], 0, v[146:147]
	s_add_i32 m0, s20, 0xc000
	ds_read_b128 v[192:195], v157
	ds_read_b128 v[196:199], v157 offset:1024
	ds_read_b128 v[200:203], v157 offset:2048
	ds_read_b128 v[204:207], v157 offset:3072
	ds_read_b128 v[208:211], v157 offset:4096
	ds_read_b128 v[212:215], v157 offset:5120
	ds_read_b128 v[216:219], v157 offset:6144
	ds_read_b128 v[220:223], v157 offset:7168
	global_load_lds_dwordx4 v[154:155], off
	v_lshl_add_u64 v[154:155], s[22:23], 0, v[148:149]
	s_add_i32 m0, s20, 0xe000
	s_nop 0
	global_load_lds_dwordx4 v[154:155], off
	s_waitcnt vmcnt(8)
	s_waitcnt lgkmcnt(0)
	s_barrier
	s_setprio 1
	s_waitcnt lgkmcnt(0)
	v_mfma_f32_16x16x32_bf16 v[126:129], v[130:133], v[192:195], 0
	v_mfma_f32_16x16x32_bf16 v[122:125], v[150:153], v[192:195], 0
	v_mfma_f32_16x16x32_bf16 v[110:113], v[130:133], v[200:203], 0
	v_mfma_f32_16x16x32_bf16 v[106:109], v[150:153], v[200:203], 0
	v_mfma_f32_16x16x32_bf16 v[94:97], v[130:133], v[208:211], 0
	v_mfma_f32_16x16x32_bf16 v[90:93], v[150:153], v[208:211], 0
	v_mfma_f32_16x16x32_bf16 v[78:81], v[130:133], v[216:219], 0
	v_mfma_f32_16x16x32_bf16 v[74:77], v[150:153], v[216:219], 0
	v_mfma_f32_16x16x32_bf16 v[126:129], v[134:137], v[196:199], v[126:129]
	v_mfma_f32_16x16x32_bf16 v[122:125], v[158:161], v[196:199], v[122:125]
	v_mfma_f32_16x16x32_bf16 v[110:113], v[134:137], v[204:207], v[110:113]
	v_mfma_f32_16x16x32_bf16 v[106:109], v[158:161], v[204:207], v[106:109]
	v_mfma_f32_16x16x32_bf16 v[94:97], v[134:137], v[212:215], v[94:97]
	v_mfma_f32_16x16x32_bf16 v[90:93], v[158:161], v[212:215], v[90:93]
	v_mfma_f32_16x16x32_bf16 v[78:81], v[134:137], v[220:223], v[78:81]
	v_mfma_f32_16x16x32_bf16 v[74:77], v[158:161], v[220:223], v[74:77]
	s_setprio 0
	s_setprio 1
	v_mfma_f32_16x16x32_bf16 v[118:121], v[164:167], v[192:195], 0
	v_mfma_f32_16x16x32_bf16 v[114:117], v[184:187], v[192:195], 0
	v_mfma_f32_16x16x32_bf16 v[102:105], v[164:167], v[200:203], 0
	v_mfma_f32_16x16x32_bf16 v[98:101], v[184:187], v[200:203], 0
	v_mfma_f32_16x16x32_bf16 v[86:89], v[164:167], v[208:211], 0
	v_mfma_f32_16x16x32_bf16 v[82:85], v[184:187], v[208:211], 0
	v_mfma_f32_16x16x32_bf16 v[70:73], v[164:167], v[216:219], 0
	v_mfma_f32_16x16x32_bf16 v[66:69], v[184:187], v[216:219], 0
	v_mfma_f32_16x16x32_bf16 v[118:121], v[180:183], v[196:199], v[118:121]
	v_mfma_f32_16x16x32_bf16 v[114:117], v[188:191], v[196:199], v[114:117]
	v_mfma_f32_16x16x32_bf16 v[102:105], v[180:183], v[204:207], v[102:105]
	v_mfma_f32_16x16x32_bf16 v[98:101], v[188:191], v[204:207], v[98:101]
	s_setprio 2
	s_barrier
	v_mfma_f32_16x16x32_bf16 v[86:89], v[180:183], v[212:215], v[86:89]
	v_mfma_f32_16x16x32_bf16 v[82:85], v[188:191], v[212:215], v[82:85]
	v_mfma_f32_16x16x32_bf16 v[70:73], v[180:183], v[220:223], v[70:73]
	v_mfma_f32_16x16x32_bf16 v[66:69], v[188:191], v[220:223], v[66:69]
	s_setprio 0
	s_add_i32 s22, s48, s9
	v_lshl_add_u64 v[154:155], s[34:35], 0, v[162:163]
	s_mov_b32 m0, s22
	ds_read_b128 v[192:195], v157 offset:16384
	ds_read_b128 v[196:199], v157 offset:17408
	ds_read_b128 v[200:203], v157 offset:18432
	ds_read_b128 v[204:207], v157 offset:19456
	ds_read_b128 v[208:211], v157 offset:20480
	ds_read_b128 v[212:215], v157 offset:21504
	ds_read_b128 v[216:219], v157 offset:22528
	ds_read_b128 v[220:223], v157 offset:23552
	global_load_lds_dwordx4 v[154:155], off
	s_add_i32 m0, s22, 0x2000
	s_add_u32 s22, s34, 0x160000
	v_lshl_add_u64 v[168:169], s[34:35], 0, v[142:143]
	s_addc_u32 s23, s35, 0
	s_add_i32 s48, s49, s9
	global_load_lds_dwordx4 v[168:169], off
	v_lshl_add_u64 v[224:225], s[22:23], 0, v[162:163]
	s_mov_b32 m0, s48
	v_lshl_add_u64 v[226:227], s[38:39], 0, v[140:141]
	global_load_lds_dwordx4 v[224:225], off
	v_lshl_add_u64 v[224:225], s[22:23], 0, v[142:143]
	s_add_i32 m0, s48, 0x2000
	s_nop 0
	global_load_lds_dwordx4 v[224:225], off
	v_lshl_add_u64 v[224:225], s[38:39], 0, v[138:139]
	s_mov_b32 m0, s20
	s_nop 0
	global_load_lds_dwordx4 v[224:225], off
	s_mov_b32 m0, s25
	s_nop 0
	global_load_lds_dwordx4 v[226:227], off
	s_waitcnt vmcnt(8)
	s_waitcnt lgkmcnt(0)
	s_barrier
	s_setprio 1
	s_waitcnt lgkmcnt(0)
	v_mfma_f32_16x16x32_bf16 v[62:65], v[130:133], v[192:195], 0
	v_mfma_f32_16x16x32_bf16 v[58:61], v[150:153], v[192:195], 0
	v_mfma_f32_16x16x32_bf16 v[46:49], v[130:133], v[200:203], 0
	v_mfma_f32_16x16x32_bf16 v[42:45], v[150:153], v[200:203], 0
	v_mfma_f32_16x16x32_bf16 v[30:33], v[130:133], v[208:211], 0
	v_mfma_f32_16x16x32_bf16 v[26:29], v[150:153], v[208:211], 0
	v_mfma_f32_16x16x32_bf16 v[14:17], v[130:133], v[216:219], 0
	v_mfma_f32_16x16x32_bf16 v[10:13], v[150:153], v[216:219], 0
	v_mfma_f32_16x16x32_bf16 v[62:65], v[134:137], v[196:199], v[62:65]
	v_mfma_f32_16x16x32_bf16 v[58:61], v[158:161], v[196:199], v[58:61]
	v_mfma_f32_16x16x32_bf16 v[46:49], v[134:137], v[204:207], v[46:49]
	v_mfma_f32_16x16x32_bf16 v[42:45], v[158:161], v[204:207], v[42:45]
	v_mfma_f32_16x16x32_bf16 v[30:33], v[134:137], v[212:215], v[30:33]
	v_mfma_f32_16x16x32_bf16 v[26:29], v[158:161], v[212:215], v[26:29]
	v_mfma_f32_16x16x32_bf16 v[14:17], v[134:137], v[220:223], v[14:17]
	v_mfma_f32_16x16x32_bf16 v[10:13], v[158:161], v[220:223], v[10:13]
	s_setprio 0
	s_setprio 1
	v_mfma_f32_16x16x32_bf16 v[54:57], v[164:167], v[192:195], 0
	v_mfma_f32_16x16x32_bf16 v[50:53], v[184:187], v[192:195], 0
	v_mfma_f32_16x16x32_bf16 v[38:41], v[164:167], v[200:203], 0
	v_mfma_f32_16x16x32_bf16 v[34:37], v[184:187], v[200:203], 0
	v_mfma_f32_16x16x32_bf16 v[22:25], v[164:167], v[208:211], 0
	v_mfma_f32_16x16x32_bf16 v[18:21], v[184:187], v[208:211], 0
	v_mfma_f32_16x16x32_bf16 v[6:9], v[164:167], v[216:219], 0
	v_mfma_f32_16x16x32_bf16 v[2:5], v[184:187], v[216:219], 0
	v_mfma_f32_16x16x32_bf16 v[54:57], v[180:183], v[196:199], v[54:57]
	v_mfma_f32_16x16x32_bf16 v[50:53], v[188:191], v[196:199], v[50:53]
	v_mfma_f32_16x16x32_bf16 v[38:41], v[180:183], v[204:207], v[38:41]
	v_mfma_f32_16x16x32_bf16 v[34:37], v[188:191], v[204:207], v[34:37]
	s_setprio 2
	s_barrier
	v_mfma_f32_16x16x32_bf16 v[22:25], v[180:183], v[212:215], v[22:25]
	v_mfma_f32_16x16x32_bf16 v[18:21], v[188:191], v[212:215], v[18:21]
	v_mfma_f32_16x16x32_bf16 v[6:9], v[180:183], v[220:223], v[6:9]
	v_mfma_f32_16x16x32_bf16 v[2:5], v[188:191], v[220:223], v[2:5]
	s_setprio 0
	s_add_i32 s48, 0, 0x18000
	s_add_i32 s49, 0, 0x1c000
	v_add_u32_e32 v158, s48, v145
	v_add_u32_e32 v179, s49, v145
	ds_read_b128 v[130:133], v158
	ds_read_b128 v[134:137], v158 offset:1024
	ds_read_b128 v[150:153], v158 offset:2048
	ds_read_b128 v[158:161], v158 offset:3072
	ds_read_b128 v[164:167], v179
	ds_read_b128 v[180:183], v179 offset:1024
	ds_read_b128 v[184:187], v179 offset:2048
	ds_read_b128 v[188:191], v179 offset:3072
	s_add_u32 s22, s38, 0x160000
	s_addc_u32 s23, s39, 0
	s_mov_b32 m0, s26
	v_lshl_add_u64 v[228:229], s[22:23], 0, v[138:139]
	ds_read_b128 v[192:195], v157 offset:32768
	ds_read_b128 v[196:199], v157 offset:33792
	ds_read_b128 v[200:203], v157 offset:34816
	ds_read_b128 v[204:207], v157 offset:35840
	ds_read_b128 v[208:211], v157 offset:36864
	ds_read_b128 v[212:215], v157 offset:37888
	ds_read_b128 v[216:219], v157 offset:38912
	ds_read_b128 v[220:223], v157 offset:39936
	global_load_lds_dwordx4 v[228:229], off
	v_lshl_add_u64 v[228:229], s[22:23], 0, v[140:141]
	s_mov_b32 m0, s27
	s_nop 0
	global_load_lds_dwordx4 v[228:229], off
	s_waitcnt vmcnt(8)
	s_waitcnt lgkmcnt(0)
	s_barrier
	s_setprio 1
	s_waitcnt lgkmcnt(0)
	v_mfma_f32_16x16x32_bf16 v[126:129], v[130:133], v[192:195], v[126:129]
	v_mfma_f32_16x16x32_bf16 v[122:125], v[150:153], v[192:195], v[122:125]
	v_mfma_f32_16x16x32_bf16 v[110:113], v[130:133], v[200:203], v[110:113]
	v_mfma_f32_16x16x32_bf16 v[106:109], v[150:153], v[200:203], v[106:109]
	v_mfma_f32_16x16x32_bf16 v[94:97], v[130:133], v[208:211], v[94:97]
	v_mfma_f32_16x16x32_bf16 v[90:93], v[150:153], v[208:211], v[90:93]
	v_mfma_f32_16x16x32_bf16 v[78:81], v[130:133], v[216:219], v[78:81]
	v_mfma_f32_16x16x32_bf16 v[74:77], v[150:153], v[216:219], v[74:77]
	v_mfma_f32_16x16x32_bf16 v[126:129], v[134:137], v[196:199], v[126:129]
	v_mfma_f32_16x16x32_bf16 v[122:125], v[158:161], v[196:199], v[122:125]
	v_mfma_f32_16x16x32_bf16 v[110:113], v[134:137], v[204:207], v[110:113]
	v_mfma_f32_16x16x32_bf16 v[106:109], v[158:161], v[204:207], v[106:109]
	v_mfma_f32_16x16x32_bf16 v[94:97], v[134:137], v[212:215], v[94:97]
	v_mfma_f32_16x16x32_bf16 v[90:93], v[158:161], v[212:215], v[90:93]
	v_mfma_f32_16x16x32_bf16 v[78:81], v[134:137], v[220:223], v[78:81]
	v_mfma_f32_16x16x32_bf16 v[74:77], v[158:161], v[220:223], v[74:77]
	s_setprio 0
	s_setprio 1
	v_mfma_f32_16x16x32_bf16 v[118:121], v[164:167], v[192:195], v[118:121]
	v_mfma_f32_16x16x32_bf16 v[114:117], v[184:187], v[192:195], v[114:117]
	v_mfma_f32_16x16x32_bf16 v[102:105], v[164:167], v[200:203], v[102:105]
	v_mfma_f32_16x16x32_bf16 v[98:101], v[184:187], v[200:203], v[98:101]
	v_mfma_f32_16x16x32_bf16 v[86:89], v[164:167], v[208:211], v[86:89]
	v_mfma_f32_16x16x32_bf16 v[82:85], v[184:187], v[208:211], v[82:85]
	v_mfma_f32_16x16x32_bf16 v[70:73], v[164:167], v[216:219], v[70:73]
	v_mfma_f32_16x16x32_bf16 v[66:69], v[184:187], v[216:219], v[66:69]
	v_mfma_f32_16x16x32_bf16 v[118:121], v[180:183], v[196:199], v[118:121]
	v_mfma_f32_16x16x32_bf16 v[114:117], v[188:191], v[196:199], v[114:117]
	v_mfma_f32_16x16x32_bf16 v[102:105], v[180:183], v[204:207], v[102:105]
	v_mfma_f32_16x16x32_bf16 v[98:101], v[188:191], v[204:207], v[98:101]
	s_setprio 2
	s_barrier
	v_mfma_f32_16x16x32_bf16 v[86:89], v[180:183], v[212:215], v[86:89]
	v_mfma_f32_16x16x32_bf16 v[82:85], v[188:191], v[212:215], v[82:85]
	v_mfma_f32_16x16x32_bf16 v[70:73], v[180:183], v[220:223], v[70:73]
	v_mfma_f32_16x16x32_bf16 v[66:69], v[188:191], v[220:223], v[66:69]
	s_setprio 0
	s_add_i32 s22, s48, s9
	v_lshl_add_u64 v[154:155], v[154:155], 0, s[6:7]
	s_mov_b32 m0, s22
	ds_read_b128 v[192:195], v157 offset:49152
	ds_read_b128 v[196:199], v157 offset:50176
	ds_read_b128 v[200:203], v157 offset:51200
	ds_read_b128 v[204:207], v157 offset:52224
	ds_read_b128 v[208:211], v157 offset:53248
	ds_read_b128 v[212:215], v157 offset:54272
	ds_read_b128 v[216:219], v157 offset:55296
	ds_read_b128 v[220:223], v157 offset:56320
	global_load_lds_dwordx4 v[154:155], off
	s_add_i32 m0, s22, 0x2000
	s_add_u32 s22, s34, 0x160080
	v_lshl_add_u64 v[154:155], v[168:169], 0, s[6:7]
	s_addc_u32 s23, s35, 0
	s_add_i32 s34, s49, s9
	global_load_lds_dwordx4 v[154:155], off
	v_lshl_add_u64 v[154:155], s[22:23], 0, v[162:163]
	s_mov_b32 m0, s34
	s_nop 0
	global_load_lds_dwordx4 v[154:155], off
	v_lshl_add_u64 v[154:155], s[22:23], 0, v[142:143]
	s_add_i32 m0, s34, 0x2000
	s_nop 0
	global_load_lds_dwordx4 v[154:155], off
	v_lshl_add_u64 v[154:155], v[224:225], 0, s[6:7]
	s_mov_b32 m0, s40
	s_nop 0
	global_load_lds_dwordx4 v[154:155], off
	v_lshl_add_u64 v[154:155], v[226:227], 0, s[6:7]
	s_mov_b32 m0, s41
	s_nop 0
	global_load_lds_dwordx4 v[154:155], off
	s_waitcnt vmcnt(8)
	s_waitcnt lgkmcnt(0)
	s_barrier
	s_setprio 1
	s_waitcnt lgkmcnt(0)
	v_mfma_f32_16x16x32_bf16 v[62:65], v[130:133], v[192:195], v[62:65]
	v_mfma_f32_16x16x32_bf16 v[58:61], v[150:153], v[192:195], v[58:61]
	v_mfma_f32_16x16x32_bf16 v[46:49], v[130:133], v[200:203], v[46:49]
	v_mfma_f32_16x16x32_bf16 v[42:45], v[150:153], v[200:203], v[42:45]
	v_mfma_f32_16x16x32_bf16 v[30:33], v[130:133], v[208:211], v[30:33]
	v_mfma_f32_16x16x32_bf16 v[26:29], v[150:153], v[208:211], v[26:29]
	v_mfma_f32_16x16x32_bf16 v[14:17], v[130:133], v[216:219], v[14:17]
	v_mfma_f32_16x16x32_bf16 v[10:13], v[150:153], v[216:219], v[10:13]
	v_mfma_f32_16x16x32_bf16 v[62:65], v[134:137], v[196:199], v[62:65]
	v_mfma_f32_16x16x32_bf16 v[58:61], v[158:161], v[196:199], v[58:61]
	v_mfma_f32_16x16x32_bf16 v[46:49], v[134:137], v[204:207], v[46:49]
	v_mfma_f32_16x16x32_bf16 v[42:45], v[158:161], v[204:207], v[42:45]
	v_mfma_f32_16x16x32_bf16 v[30:33], v[134:137], v[212:215], v[30:33]
	v_mfma_f32_16x16x32_bf16 v[26:29], v[158:161], v[212:215], v[26:29]
	v_mfma_f32_16x16x32_bf16 v[14:17], v[134:137], v[220:223], v[14:17]
	v_mfma_f32_16x16x32_bf16 v[10:13], v[158:161], v[220:223], v[10:13]
	s_setprio 0
	s_setprio 1
	v_mfma_f32_16x16x32_bf16 v[54:57], v[164:167], v[192:195], v[54:57]
	v_mfma_f32_16x16x32_bf16 v[50:53], v[184:187], v[192:195], v[50:53]
	v_mfma_f32_16x16x32_bf16 v[38:41], v[164:167], v[200:203], v[38:41]
	v_mfma_f32_16x16x32_bf16 v[34:37], v[184:187], v[200:203], v[34:37]
	v_mfma_f32_16x16x32_bf16 v[22:25], v[164:167], v[208:211], v[22:25]
	v_mfma_f32_16x16x32_bf16 v[18:21], v[184:187], v[208:211], v[18:21]
	v_mfma_f32_16x16x32_bf16 v[6:9], v[164:167], v[216:219], v[6:9]
	v_mfma_f32_16x16x32_bf16 v[2:5], v[184:187], v[216:219], v[2:5]
	v_mfma_f32_16x16x32_bf16 v[54:57], v[180:183], v[196:199], v[54:57]
	v_mfma_f32_16x16x32_bf16 v[50:53], v[188:191], v[196:199], v[50:53]
	v_mfma_f32_16x16x32_bf16 v[38:41], v[180:183], v[204:207], v[38:41]
	v_mfma_f32_16x16x32_bf16 v[34:37], v[188:191], v[204:207], v[34:37]
	s_setprio 2
	s_barrier
	v_mfma_f32_16x16x32_bf16 v[22:25], v[180:183], v[212:215], v[22:25]
	v_mfma_f32_16x16x32_bf16 v[18:21], v[188:191], v[212:215], v[18:21]
	v_mfma_f32_16x16x32_bf16 v[6:9], v[180:183], v[220:223], v[6:9]
	v_mfma_f32_16x16x32_bf16 v[2:5], v[188:191], v[220:223], v[2:5]
	s_setprio 0
	s_add_i32 s47, s47, 2
	s_add_u32 s45, s45, 0x100
	s_addc_u32 s46, s46, 0
	s_cmpk_gt_u32 s47, 0x55
	s_mov_b64 s[22:23], s[28:29]
.LBB0_1874:
	s_add_u32 s28, s22, 0x100
	s_addc_u32 s29, s23, 0
	s_add_i32 s48, 0, 0x10000
	s_cmpk_eq_i32 s47, 0x54
	s_cselect_b32 s39, s5, s29
	s_cselect_b32 s38, s4, s28
	v_add_u32_e32 v154, s48, v145
	s_cselect_b32 s35, s19, s46
	s_cselect_b32 s34, s18, s45
	s_add_i32 s49, 0, 0x14000
	ds_read_b128 v[130:133], v154
	ds_read_b128 v[134:137], v154 offset:1024
	ds_read_b128 v[150:153], v154 offset:2048
	ds_read_b128 v[158:161], v154 offset:3072
	v_add_u32_e32 v154, s49, v145
	ds_read_b128 v[164:167], v154
	ds_read_b128 v[180:183], v154 offset:1024
	ds_read_b128 v[184:187], v154 offset:2048
	ds_read_b128 v[188:191], v154 offset:3072
	v_lshl_add_u64 v[154:155], s[22:23], 0, v[146:147]
	s_add_i32 m0, s20, 0xc000
	ds_read_b128 v[192:195], v157
	ds_read_b128 v[196:199], v157 offset:1024
	ds_read_b128 v[200:203], v157 offset:2048
	ds_read_b128 v[204:207], v157 offset:3072
	ds_read_b128 v[208:211], v157 offset:4096
	ds_read_b128 v[212:215], v157 offset:5120
	ds_read_b128 v[216:219], v157 offset:6144
	ds_read_b128 v[220:223], v157 offset:7168
	global_load_lds_dwordx4 v[154:155], off
	v_lshl_add_u64 v[154:155], s[22:23], 0, v[148:149]
	s_add_i32 m0, s20, 0xe000
	s_nop 0
	global_load_lds_dwordx4 v[154:155], off
	s_waitcnt vmcnt(8)
	s_waitcnt lgkmcnt(0)
	s_barrier
	s_setprio 1
	s_waitcnt lgkmcnt(0)
	v_mfma_f32_16x16x32_bf16 v[126:129], v[130:133], v[192:195], v[126:129]
	v_mfma_f32_16x16x32_bf16 v[122:125], v[150:153], v[192:195], v[122:125]
	v_mfma_f32_16x16x32_bf16 v[110:113], v[130:133], v[200:203], v[110:113]
	v_mfma_f32_16x16x32_bf16 v[106:109], v[150:153], v[200:203], v[106:109]
	v_mfma_f32_16x16x32_bf16 v[94:97], v[130:133], v[208:211], v[94:97]
	v_mfma_f32_16x16x32_bf16 v[90:93], v[150:153], v[208:211], v[90:93]
	v_mfma_f32_16x16x32_bf16 v[78:81], v[130:133], v[216:219], v[78:81]
	v_mfma_f32_16x16x32_bf16 v[74:77], v[150:153], v[216:219], v[74:77]
	v_mfma_f32_16x16x32_bf16 v[126:129], v[134:137], v[196:199], v[126:129]
	v_mfma_f32_16x16x32_bf16 v[122:125], v[158:161], v[196:199], v[122:125]
	v_mfma_f32_16x16x32_bf16 v[110:113], v[134:137], v[204:207], v[110:113]
	v_mfma_f32_16x16x32_bf16 v[106:109], v[158:161], v[204:207], v[106:109]
	v_mfma_f32_16x16x32_bf16 v[94:97], v[134:137], v[212:215], v[94:97]
	v_mfma_f32_16x16x32_bf16 v[90:93], v[158:161], v[212:215], v[90:93]
	v_mfma_f32_16x16x32_bf16 v[78:81], v[134:137], v[220:223], v[78:81]
	v_mfma_f32_16x16x32_bf16 v[74:77], v[158:161], v[220:223], v[74:77]
	s_setprio 0
	s_setprio 1
	v_mfma_f32_16x16x32_bf16 v[118:121], v[164:167], v[192:195], v[118:121]
	v_mfma_f32_16x16x32_bf16 v[114:117], v[184:187], v[192:195], v[114:117]
	v_mfma_f32_16x16x32_bf16 v[102:105], v[164:167], v[200:203], v[102:105]
	v_mfma_f32_16x16x32_bf16 v[98:101], v[184:187], v[200:203], v[98:101]
	v_mfma_f32_16x16x32_bf16 v[86:89], v[164:167], v[208:211], v[86:89]
	v_mfma_f32_16x16x32_bf16 v[82:85], v[184:187], v[208:211], v[82:85]
	v_mfma_f32_16x16x32_bf16 v[70:73], v[164:167], v[216:219], v[70:73]
	v_mfma_f32_16x16x32_bf16 v[66:69], v[184:187], v[216:219], v[66:69]
	v_mfma_f32_16x16x32_bf16 v[118:121], v[180:183], v[196:199], v[118:121]
	v_mfma_f32_16x16x32_bf16 v[114:117], v[188:191], v[196:199], v[114:117]
	v_mfma_f32_16x16x32_bf16 v[102:105], v[180:183], v[204:207], v[102:105]
	v_mfma_f32_16x16x32_bf16 v[98:101], v[188:191], v[204:207], v[98:101]
	s_setprio 2
	s_barrier
	v_mfma_f32_16x16x32_bf16 v[86:89], v[180:183], v[212:215], v[86:89]
	v_mfma_f32_16x16x32_bf16 v[82:85], v[188:191], v[212:215], v[82:85]
	v_mfma_f32_16x16x32_bf16 v[70:73], v[180:183], v[220:223], v[70:73]
	v_mfma_f32_16x16x32_bf16 v[66:69], v[188:191], v[220:223], v[66:69]
	s_setprio 0
	s_add_i32 s22, s48, s9
	v_lshl_add_u64 v[154:155], s[34:35], 0, v[162:163]
	s_mov_b32 m0, s22
	ds_read_b128 v[192:195], v157 offset:16384
	ds_read_b128 v[196:199], v157 offset:17408
	ds_read_b128 v[200:203], v157 offset:18432
	ds_read_b128 v[204:207], v157 offset:19456
	ds_read_b128 v[208:211], v157 offset:20480
	ds_read_b128 v[212:215], v157 offset:21504
	ds_read_b128 v[216:219], v157 offset:22528
	ds_read_b128 v[220:223], v157 offset:23552
	global_load_lds_dwordx4 v[154:155], off
	s_add_i32 m0, s22, 0x2000
	s_add_u32 s22, s34, 0x160000
	v_lshl_add_u64 v[168:169], s[34:35], 0, v[142:143]
	s_addc_u32 s23, s35, 0
	s_add_i32 s48, s49, s9
	global_load_lds_dwordx4 v[168:169], off
	v_lshl_add_u64 v[224:225], s[22:23], 0, v[162:163]
	s_mov_b32 m0, s48
	v_lshl_add_u64 v[226:227], s[38:39], 0, v[140:141]
	global_load_lds_dwordx4 v[224:225], off
	v_lshl_add_u64 v[224:225], s[22:23], 0, v[142:143]
	s_add_i32 m0, s48, 0x2000
	s_nop 0
	global_load_lds_dwordx4 v[224:225], off
	v_lshl_add_u64 v[224:225], s[38:39], 0, v[138:139]
	s_mov_b32 m0, s20
	s_nop 0
	global_load_lds_dwordx4 v[224:225], off
	s_mov_b32 m0, s25
	s_nop 0
	global_load_lds_dwordx4 v[226:227], off
	s_waitcnt vmcnt(8)
	s_waitcnt lgkmcnt(0)
	s_barrier
	s_setprio 1
	s_waitcnt lgkmcnt(0)
	v_mfma_f32_16x16x32_bf16 v[62:65], v[130:133], v[192:195], v[62:65]
	v_mfma_f32_16x16x32_bf16 v[58:61], v[150:153], v[192:195], v[58:61]
	v_mfma_f32_16x16x32_bf16 v[46:49], v[130:133], v[200:203], v[46:49]
	v_mfma_f32_16x16x32_bf16 v[42:45], v[150:153], v[200:203], v[42:45]
	v_mfma_f32_16x16x32_bf16 v[30:33], v[130:133], v[208:211], v[30:33]
	v_mfma_f32_16x16x32_bf16 v[26:29], v[150:153], v[208:211], v[26:29]
	v_mfma_f32_16x16x32_bf16 v[14:17], v[130:133], v[216:219], v[14:17]
	v_mfma_f32_16x16x32_bf16 v[10:13], v[150:153], v[216:219], v[10:13]
	v_mfma_f32_16x16x32_bf16 v[62:65], v[134:137], v[196:199], v[62:65]
	v_mfma_f32_16x16x32_bf16 v[58:61], v[158:161], v[196:199], v[58:61]
	v_mfma_f32_16x16x32_bf16 v[46:49], v[134:137], v[204:207], v[46:49]
	v_mfma_f32_16x16x32_bf16 v[42:45], v[158:161], v[204:207], v[42:45]
	v_mfma_f32_16x16x32_bf16 v[30:33], v[134:137], v[212:215], v[30:33]
	v_mfma_f32_16x16x32_bf16 v[26:29], v[158:161], v[212:215], v[26:29]
	v_mfma_f32_16x16x32_bf16 v[14:17], v[134:137], v[220:223], v[14:17]
	v_mfma_f32_16x16x32_bf16 v[10:13], v[158:161], v[220:223], v[10:13]
	s_setprio 0
	s_setprio 1
	v_mfma_f32_16x16x32_bf16 v[54:57], v[164:167], v[192:195], v[54:57]
	v_mfma_f32_16x16x32_bf16 v[50:53], v[184:187], v[192:195], v[50:53]
	v_mfma_f32_16x16x32_bf16 v[38:41], v[164:167], v[200:203], v[38:41]
	v_mfma_f32_16x16x32_bf16 v[34:37], v[184:187], v[200:203], v[34:37]
	v_mfma_f32_16x16x32_bf16 v[22:25], v[164:167], v[208:211], v[22:25]
	v_mfma_f32_16x16x32_bf16 v[18:21], v[184:187], v[208:211], v[18:21]
	v_mfma_f32_16x16x32_bf16 v[6:9], v[164:167], v[216:219], v[6:9]
	v_mfma_f32_16x16x32_bf16 v[2:5], v[184:187], v[216:219], v[2:5]
	v_mfma_f32_16x16x32_bf16 v[54:57], v[180:183], v[196:199], v[54:57]
	v_mfma_f32_16x16x32_bf16 v[50:53], v[188:191], v[196:199], v[50:53]
	v_mfma_f32_16x16x32_bf16 v[38:41], v[180:183], v[204:207], v[38:41]
	v_mfma_f32_16x16x32_bf16 v[34:37], v[188:191], v[204:207], v[34:37]
	s_setprio 2
	s_barrier
	v_mfma_f32_16x16x32_bf16 v[22:25], v[180:183], v[212:215], v[22:25]
	v_mfma_f32_16x16x32_bf16 v[18:21], v[188:191], v[212:215], v[18:21]
	v_mfma_f32_16x16x32_bf16 v[6:9], v[180:183], v[220:223], v[6:9]
	v_mfma_f32_16x16x32_bf16 v[2:5], v[188:191], v[220:223], v[2:5]
	s_setprio 0
	s_add_i32 s48, 0, 0x18000
	s_add_i32 s49, 0, 0x1c000
	v_add_u32_e32 v158, s48, v145
	v_add_u32_e32 v179, s49, v145
	ds_read_b128 v[130:133], v158
	ds_read_b128 v[134:137], v158 offset:1024
	ds_read_b128 v[150:153], v158 offset:2048
	ds_read_b128 v[158:161], v158 offset:3072
	ds_read_b128 v[164:167], v179
	ds_read_b128 v[180:183], v179 offset:1024
	ds_read_b128 v[184:187], v179 offset:2048
	ds_read_b128 v[188:191], v179 offset:3072
	s_add_u32 s22, s38, 0x160000
	s_addc_u32 s23, s39, 0
	s_mov_b32 m0, s26
	v_lshl_add_u64 v[228:229], s[22:23], 0, v[138:139]
	ds_read_b128 v[192:195], v157 offset:32768
	ds_read_b128 v[196:199], v157 offset:33792
	ds_read_b128 v[200:203], v157 offset:34816
	ds_read_b128 v[204:207], v157 offset:35840
	ds_read_b128 v[208:211], v157 offset:36864
	ds_read_b128 v[212:215], v157 offset:37888
	ds_read_b128 v[216:219], v157 offset:38912
	ds_read_b128 v[220:223], v157 offset:39936
	global_load_lds_dwordx4 v[228:229], off
	v_lshl_add_u64 v[228:229], s[22:23], 0, v[140:141]
	s_mov_b32 m0, s27
	s_nop 0
	global_load_lds_dwordx4 v[228:229], off
	s_waitcnt vmcnt(8)
	s_waitcnt lgkmcnt(0)
	s_barrier
	s_setprio 1
	s_waitcnt lgkmcnt(0)
	v_mfma_f32_16x16x32_bf16 v[126:129], v[130:133], v[192:195], v[126:129]
	v_mfma_f32_16x16x32_bf16 v[122:125], v[150:153], v[192:195], v[122:125]
	v_mfma_f32_16x16x32_bf16 v[110:113], v[130:133], v[200:203], v[110:113]
	v_mfma_f32_16x16x32_bf16 v[106:109], v[150:153], v[200:203], v[106:109]
	v_mfma_f32_16x16x32_bf16 v[94:97], v[130:133], v[208:211], v[94:97]
	v_mfma_f32_16x16x32_bf16 v[90:93], v[150:153], v[208:211], v[90:93]
	v_mfma_f32_16x16x32_bf16 v[78:81], v[130:133], v[216:219], v[78:81]
	v_mfma_f32_16x16x32_bf16 v[74:77], v[150:153], v[216:219], v[74:77]
	v_mfma_f32_16x16x32_bf16 v[126:129], v[134:137], v[196:199], v[126:129]
	v_mfma_f32_16x16x32_bf16 v[122:125], v[158:161], v[196:199], v[122:125]
	v_mfma_f32_16x16x32_bf16 v[110:113], v[134:137], v[204:207], v[110:113]
	v_mfma_f32_16x16x32_bf16 v[106:109], v[158:161], v[204:207], v[106:109]
	v_mfma_f32_16x16x32_bf16 v[94:97], v[134:137], v[212:215], v[94:97]
	v_mfma_f32_16x16x32_bf16 v[90:93], v[158:161], v[212:215], v[90:93]
	v_mfma_f32_16x16x32_bf16 v[78:81], v[134:137], v[220:223], v[78:81]
	v_mfma_f32_16x16x32_bf16 v[74:77], v[158:161], v[220:223], v[74:77]
	s_setprio 0
	s_setprio 1
	v_mfma_f32_16x16x32_bf16 v[118:121], v[164:167], v[192:195], v[118:121]
	v_mfma_f32_16x16x32_bf16 v[114:117], v[184:187], v[192:195], v[114:117]
	v_mfma_f32_16x16x32_bf16 v[102:105], v[164:167], v[200:203], v[102:105]
	v_mfma_f32_16x16x32_bf16 v[98:101], v[184:187], v[200:203], v[98:101]
	v_mfma_f32_16x16x32_bf16 v[86:89], v[164:167], v[208:211], v[86:89]
	v_mfma_f32_16x16x32_bf16 v[82:85], v[184:187], v[208:211], v[82:85]
	v_mfma_f32_16x16x32_bf16 v[70:73], v[164:167], v[216:219], v[70:73]
	v_mfma_f32_16x16x32_bf16 v[66:69], v[184:187], v[216:219], v[66:69]
	v_mfma_f32_16x16x32_bf16 v[118:121], v[180:183], v[196:199], v[118:121]
	v_mfma_f32_16x16x32_bf16 v[114:117], v[188:191], v[196:199], v[114:117]
	v_mfma_f32_16x16x32_bf16 v[102:105], v[180:183], v[204:207], v[102:105]
	v_mfma_f32_16x16x32_bf16 v[98:101], v[188:191], v[204:207], v[98:101]
	s_setprio 2
	s_barrier
	v_mfma_f32_16x16x32_bf16 v[86:89], v[180:183], v[212:215], v[86:89]
	v_mfma_f32_16x16x32_bf16 v[82:85], v[188:191], v[212:215], v[82:85]
	v_mfma_f32_16x16x32_bf16 v[70:73], v[180:183], v[220:223], v[70:73]
	v_mfma_f32_16x16x32_bf16 v[66:69], v[188:191], v[220:223], v[66:69]
	s_setprio 0
	s_add_i32 s22, s48, s9
	v_lshl_add_u64 v[154:155], v[154:155], 0, s[6:7]
	s_mov_b32 m0, s22
	ds_read_b128 v[192:195], v157 offset:49152
	ds_read_b128 v[196:199], v157 offset:50176
	ds_read_b128 v[200:203], v157 offset:51200
	ds_read_b128 v[204:207], v157 offset:52224
	ds_read_b128 v[208:211], v157 offset:53248
	ds_read_b128 v[212:215], v157 offset:54272
	ds_read_b128 v[216:219], v157 offset:55296
	ds_read_b128 v[220:223], v157 offset:56320
	global_load_lds_dwordx4 v[154:155], off
	s_add_i32 m0, s22, 0x2000
	s_add_u32 s22, s34, 0x160080
	v_lshl_add_u64 v[154:155], v[168:169], 0, s[6:7]
	s_addc_u32 s23, s35, 0
	s_add_i32 s34, s49, s9
	global_load_lds_dwordx4 v[154:155], off
	v_lshl_add_u64 v[154:155], s[22:23], 0, v[162:163]
	s_mov_b32 m0, s34
	s_nop 0
	global_load_lds_dwordx4 v[154:155], off
	v_lshl_add_u64 v[154:155], s[22:23], 0, v[142:143]
	s_add_i32 m0, s34, 0x2000
	s_nop 0
	global_load_lds_dwordx4 v[154:155], off
	v_lshl_add_u64 v[154:155], v[224:225], 0, s[6:7]
	s_mov_b32 m0, s40
	s_nop 0
	global_load_lds_dwordx4 v[154:155], off
	v_lshl_add_u64 v[154:155], v[226:227], 0, s[6:7]
	s_mov_b32 m0, s41
	s_nop 0
	global_load_lds_dwordx4 v[154:155], off
	s_waitcnt vmcnt(8)
	s_waitcnt lgkmcnt(0)
	s_barrier
	s_setprio 1
	s_waitcnt lgkmcnt(0)
	v_mfma_f32_16x16x32_bf16 v[62:65], v[130:133], v[192:195], v[62:65]
	v_mfma_f32_16x16x32_bf16 v[58:61], v[150:153], v[192:195], v[58:61]
	v_mfma_f32_16x16x32_bf16 v[46:49], v[130:133], v[200:203], v[46:49]
	v_mfma_f32_16x16x32_bf16 v[42:45], v[150:153], v[200:203], v[42:45]
	v_mfma_f32_16x16x32_bf16 v[30:33], v[130:133], v[208:211], v[30:33]
	v_mfma_f32_16x16x32_bf16 v[26:29], v[150:153], v[208:211], v[26:29]
	v_mfma_f32_16x16x32_bf16 v[14:17], v[130:133], v[216:219], v[14:17]
	v_mfma_f32_16x16x32_bf16 v[10:13], v[150:153], v[216:219], v[10:13]
	v_mfma_f32_16x16x32_bf16 v[62:65], v[134:137], v[196:199], v[62:65]
	v_mfma_f32_16x16x32_bf16 v[58:61], v[158:161], v[196:199], v[58:61]
	v_mfma_f32_16x16x32_bf16 v[46:49], v[134:137], v[204:207], v[46:49]
	v_mfma_f32_16x16x32_bf16 v[42:45], v[158:161], v[204:207], v[42:45]
	v_mfma_f32_16x16x32_bf16 v[30:33], v[134:137], v[212:215], v[30:33]
	v_mfma_f32_16x16x32_bf16 v[26:29], v[158:161], v[212:215], v[26:29]
	v_mfma_f32_16x16x32_bf16 v[14:17], v[134:137], v[220:223], v[14:17]
	v_mfma_f32_16x16x32_bf16 v[10:13], v[158:161], v[220:223], v[10:13]
	s_setprio 0
	s_setprio 1
	v_mfma_f32_16x16x32_bf16 v[54:57], v[164:167], v[192:195], v[54:57]
	v_mfma_f32_16x16x32_bf16 v[50:53], v[184:187], v[192:195], v[50:53]
	v_mfma_f32_16x16x32_bf16 v[38:41], v[164:167], v[200:203], v[38:41]
	v_mfma_f32_16x16x32_bf16 v[34:37], v[184:187], v[200:203], v[34:37]
	v_mfma_f32_16x16x32_bf16 v[22:25], v[164:167], v[208:211], v[22:25]
	v_mfma_f32_16x16x32_bf16 v[18:21], v[184:187], v[208:211], v[18:21]
	v_mfma_f32_16x16x32_bf16 v[6:9], v[164:167], v[216:219], v[6:9]
	v_mfma_f32_16x16x32_bf16 v[2:5], v[184:187], v[216:219], v[2:5]
	v_mfma_f32_16x16x32_bf16 v[54:57], v[180:183], v[196:199], v[54:57]
	v_mfma_f32_16x16x32_bf16 v[50:53], v[188:191], v[196:199], v[50:53]
	v_mfma_f32_16x16x32_bf16 v[38:41], v[180:183], v[204:207], v[38:41]
	v_mfma_f32_16x16x32_bf16 v[34:37], v[188:191], v[204:207], v[34:37]
	s_setprio 2
	s_barrier
	v_mfma_f32_16x16x32_bf16 v[22:25], v[180:183], v[212:215], v[22:25]
	v_mfma_f32_16x16x32_bf16 v[18:21], v[188:191], v[212:215], v[18:21]
	v_mfma_f32_16x16x32_bf16 v[6:9], v[180:183], v[220:223], v[6:9]
	v_mfma_f32_16x16x32_bf16 v[2:5], v[188:191], v[220:223], v[2:5]
	s_setprio 0
	s_add_i32 s47, s47, 2
	s_add_u32 s45, s45, 0x100
	s_addc_u32 s46, s46, 0
	s_cmpk_gt_u32 s47, 0x55
	s_mov_b64 s[22:23], s[28:29]
	s_cbranch_scc0 .LBB0_1874
	s_and_b64 vcc, exec, s[2:3]
	s_cbranch_vccz .LBB0_1877
	s_barrier
